# K-loop phases: ds_read fragment order + counted lgkmcnt so the reads needed only by MFMAs 9..16 stay in flight under MFMAs 1..8 (re-test with paired measure)
# baseline (speedup 1.0000x reference)
.LBB0_114:
	ds_read_b128 v[178:181], v145
	ds_read_b128 v[186:189], v145 offset:2048
	ds_read_b128 v[182:185], v145 offset:1024
	ds_read_b128 v[190:193], v145 offset:3072
	v_lshl_add_u64 v[140:141], v[132:133], 0, v[136:137]
	v_readfirstlane_b32 s6, v177
	v_lshl_add_u64 v[142:143], v[140:141], 0, s[76:77]
	s_mov_b32 m0, s6
	v_readfirstlane_b32 s6, v176
	ds_read_b128 v[194:197], v144
	ds_read_b128 v[202:205], v144 offset:2048
	ds_read_b128 v[210:213], v144 offset:4096
	ds_read_b128 v[218:221], v144 offset:6144
	ds_read_b128 v[198:201], v144 offset:1024
	ds_read_b128 v[206:209], v144 offset:3072
	ds_read_b128 v[214:217], v144 offset:5120
	ds_read_b128 v[222:225], v144 offset:7168
	global_load_lds_dwordx4 v[142:143], off
	v_lshl_add_u64 v[142:143], v[140:141], 0, s[16:17]
	s_mov_b32 m0, s6
	s_nop 0
	global_load_lds_dwordx4 v[142:143], off
	s_waitcnt lgkmcnt(8)
	s_barrier
	s_waitcnt lgkmcnt(4)
	s_setprio 1
	s_waitcnt lgkmcnt(4)
	v_mfma_f32_16x16x32_bf16 v[124:127], v[178:181], v[194:197], v[124:127]
	v_mfma_f32_16x16x32_bf16 v[120:123], v[186:189], v[194:197], v[120:123]
	v_mfma_f32_16x16x32_bf16 v[116:119], v[178:181], v[202:205], v[116:119]
	v_mfma_f32_16x16x32_bf16 v[112:115], v[186:189], v[202:205], v[112:115]
	v_mfma_f32_16x16x32_bf16 v[100:103], v[178:181], v[210:213], v[100:103]
	v_mfma_f32_16x16x32_bf16 v[96:99], v[186:189], v[210:213], v[96:99]
	v_mfma_f32_16x16x32_bf16 v[84:87], v[178:181], v[218:221], v[84:87]
	v_mfma_f32_16x16x32_bf16 v[80:83], v[186:189], v[218:221], v[80:83]
	s_waitcnt lgkmcnt(0)
	v_mfma_f32_16x16x32_bf16 v[124:127], v[182:185], v[198:201], v[124:127]
	v_mfma_f32_16x16x32_bf16 v[120:123], v[190:193], v[198:201], v[120:123]
	v_mfma_f32_16x16x32_bf16 v[116:119], v[182:185], v[206:209], v[116:119]
	v_mfma_f32_16x16x32_bf16 v[112:115], v[190:193], v[206:209], v[112:115]
	v_mfma_f32_16x16x32_bf16 v[100:103], v[182:185], v[214:217], v[100:103]
	v_mfma_f32_16x16x32_bf16 v[96:99], v[190:193], v[214:217], v[96:99]
	v_mfma_f32_16x16x32_bf16 v[84:87], v[182:185], v[222:225], v[84:87]
	v_mfma_f32_16x16x32_bf16 v[80:83], v[190:193], v[222:225], v[80:83]
	s_setprio 0
	s_barrier
	v_lshl_add_u64 v[142:143], v[130:131], 0, v[136:137]
	v_readfirstlane_b32 s6, v148
	v_lshl_add_u64 v[162:163], v[142:143], 0, s[86:87]
	s_mov_b32 m0, s6
	s_mov_b64 s[6:7], 0x20100
	ds_read_b128 v[226:229], v145 offset:16384
	ds_read_b128 v[234:237], v145 offset:18432
	ds_read_b128 v[230:233], v145 offset:17408
	ds_read_b128 v[238:241], v145 offset:19456
	global_load_lds_dwordx4 v[162:163], off
	v_lshl_add_u64 v[162:163], v[142:143], 0, s[6:7]
	v_readfirstlane_b32 s6, v149
	s_mov_b32 m0, s6
	s_nop 0
	global_load_lds_dwordx4 v[162:163], off
	s_barrier
	s_waitcnt lgkmcnt(2)
	s_setprio 1
	s_waitcnt lgkmcnt(2)
	v_mfma_f32_16x16x32_bf16 v[108:111], v[226:229], v[194:197], v[108:111]
	v_mfma_f32_16x16x32_bf16 v[104:107], v[234:237], v[194:197], v[104:107]
	v_mfma_f32_16x16x32_bf16 v[92:95], v[226:229], v[202:205], v[92:95]
	v_mfma_f32_16x16x32_bf16 v[88:91], v[234:237], v[202:205], v[88:91]
	v_mfma_f32_16x16x32_bf16 v[76:79], v[226:229], v[210:213], v[76:79]
	v_mfma_f32_16x16x32_bf16 v[72:75], v[234:237], v[210:213], v[72:75]
	v_mfma_f32_16x16x32_bf16 v[68:71], v[226:229], v[218:221], v[68:71]
	v_mfma_f32_16x16x32_bf16 v[64:67], v[234:237], v[218:221], v[64:67]
	s_waitcnt lgkmcnt(0)
	v_mfma_f32_16x16x32_bf16 v[108:111], v[230:233], v[198:201], v[108:111]
	v_mfma_f32_16x16x32_bf16 v[104:107], v[238:241], v[198:201], v[104:107]
	v_mfma_f32_16x16x32_bf16 v[92:95], v[230:233], v[206:209], v[92:95]
	v_mfma_f32_16x16x32_bf16 v[88:91], v[238:241], v[206:209], v[88:91]
	v_mfma_f32_16x16x32_bf16 v[76:79], v[230:233], v[214:217], v[76:79]
	v_mfma_f32_16x16x32_bf16 v[72:75], v[238:241], v[214:217], v[72:75]
	v_mfma_f32_16x16x32_bf16 v[68:71], v[230:233], v[222:225], v[68:71]
	v_mfma_f32_16x16x32_bf16 v[64:67], v[238:241], v[222:225], v[64:67]
	s_setprio 0
	v_readfirstlane_b32 s6, v146
	v_lshl_add_u64 v[162:163], v[140:141], 0, s[88:89]
	s_mov_b32 m0, s6
	v_readfirstlane_b32 s6, v150
	s_barrier
	ds_read_b128 v[194:197], v144 offset:16384
	ds_read_b128 v[202:205], v144 offset:18432
	ds_read_b128 v[210:213], v144 offset:20480
	ds_read_b128 v[218:221], v144 offset:22528
	ds_read_b128 v[198:201], v144 offset:17408
	ds_read_b128 v[206:209], v144 offset:19456
	ds_read_b128 v[214:217], v144 offset:21504
	ds_read_b128 v[222:225], v144 offset:23552
	global_load_lds_dwordx4 v[162:163], off
	v_lshl_add_u64 v[162:163], v[140:141], 0, s[90:91]
	s_mov_b32 m0, s6
	s_nop 0
	global_load_lds_dwordx4 v[162:163], off
	s_barrier
	s_waitcnt lgkmcnt(4)
	s_setprio 1
	s_waitcnt lgkmcnt(4)
	v_mfma_f32_16x16x32_bf16 v[60:63], v[178:181], v[194:197], v[60:63]
	v_mfma_f32_16x16x32_bf16 v[56:59], v[186:189], v[194:197], v[56:59]
	v_mfma_f32_16x16x32_bf16 v[52:55], v[178:181], v[202:205], v[52:55]
	v_mfma_f32_16x16x32_bf16 v[44:47], v[186:189], v[202:205], v[44:47]
	v_mfma_f32_16x16x32_bf16 v[36:39], v[178:181], v[210:213], v[36:39]
	v_mfma_f32_16x16x32_bf16 v[28:31], v[186:189], v[210:213], v[28:31]
	v_mfma_f32_16x16x32_bf16 v[20:23], v[178:181], v[218:221], v[20:23]
	v_mfma_f32_16x16x32_bf16 v[12:15], v[186:189], v[218:221], v[12:15]
	s_waitcnt lgkmcnt(0)
	v_mfma_f32_16x16x32_bf16 v[60:63], v[182:185], v[198:201], v[60:63]
	v_mfma_f32_16x16x32_bf16 v[56:59], v[190:193], v[198:201], v[56:59]
	v_mfma_f32_16x16x32_bf16 v[52:55], v[182:185], v[206:209], v[52:55]
	v_mfma_f32_16x16x32_bf16 v[44:47], v[190:193], v[206:209], v[44:47]
	v_mfma_f32_16x16x32_bf16 v[36:39], v[182:185], v[214:217], v[36:39]
	v_mfma_f32_16x16x32_bf16 v[28:31], v[190:193], v[214:217], v[28:31]
	v_mfma_f32_16x16x32_bf16 v[20:23], v[182:185], v[222:225], v[20:23]
	v_mfma_f32_16x16x32_bf16 v[12:15], v[190:193], v[222:225], v[12:15]
	s_setprio 0
	s_barrier
	s_mov_b64 s[6:7], 0x40100
	v_lshl_add_u64 v[162:163], v[142:143], 0, s[6:7]
	v_readfirstlane_b32 s6, v151
	s_mov_b32 m0, s6
	s_mov_b64 s[6:7], 0x60100
	global_load_lds_dwordx4 v[162:163], off
	v_lshl_add_u64 v[162:163], v[142:143], 0, s[6:7]
	v_readfirstlane_b32 s6, v152
	s_mov_b32 m0, s6
	s_nop 0
	global_load_lds_dwordx4 v[162:163], off
	s_waitcnt vmcnt(6)
	s_barrier
	s_setprio 1
	v_mfma_f32_16x16x32_bf16 v[48:51], v[226:229], v[194:197], v[48:51]
	v_mfma_f32_16x16x32_bf16 v[40:43], v[234:237], v[194:197], v[40:43]
	v_mfma_f32_16x16x32_bf16 v[32:35], v[226:229], v[202:205], v[32:35]
	v_mfma_f32_16x16x32_bf16 v[24:27], v[234:237], v[202:205], v[24:27]
	v_mfma_f32_16x16x32_bf16 v[16:19], v[226:229], v[210:213], v[16:19]
	v_mfma_f32_16x16x32_bf16 v[8:11], v[234:237], v[210:213], v[8:11]
	v_mfma_f32_16x16x32_bf16 v[4:7], v[226:229], v[218:221], v[4:7]
	v_mfma_f32_16x16x32_bf16 v[0:3], v[234:237], v[218:221], v[0:3]
	v_mfma_f32_16x16x32_bf16 v[48:51], v[230:233], v[198:201], v[48:51]
	v_mfma_f32_16x16x32_bf16 v[40:43], v[238:241], v[198:201], v[40:43]
	v_mfma_f32_16x16x32_bf16 v[32:35], v[230:233], v[206:209], v[32:35]
	v_mfma_f32_16x16x32_bf16 v[24:27], v[238:241], v[206:209], v[24:27]
	v_mfma_f32_16x16x32_bf16 v[16:19], v[230:233], v[214:217], v[16:19]
	v_mfma_f32_16x16x32_bf16 v[8:11], v[238:241], v[214:217], v[8:11]
	v_mfma_f32_16x16x32_bf16 v[4:7], v[230:233], v[222:225], v[4:7]
	v_mfma_f32_16x16x32_bf16 v[0:3], v[238:241], v[222:225], v[0:3]
	s_setprio 0
	s_barrier
	ds_read_b128 v[178:181], v139
	ds_read_b128 v[186:189], v139 offset:2048
	ds_read_b128 v[182:185], v139 offset:1024
	ds_read_b128 v[190:193], v139 offset:3072
	v_readfirstlane_b32 s6, v153
	v_lshl_add_u64 v[162:163], v[140:141], 0, s[94:95]
	s_mov_b32 m0, s6
	v_readfirstlane_b32 s6, v170
	ds_read_b128 v[194:197], v135
	ds_read_b128 v[202:205], v135 offset:2048
	ds_read_b128 v[210:213], v135 offset:4096
	ds_read_b128 v[218:221], v135 offset:6144
	ds_read_b128 v[198:201], v135 offset:1024
	ds_read_b128 v[206:209], v135 offset:3072
	ds_read_b128 v[214:217], v135 offset:5120
	ds_read_b128 v[222:225], v135 offset:7168
	global_load_lds_dwordx4 v[162:163], off
	v_lshl_add_u64 v[162:163], v[140:141], 0, s[78:79]
	s_mov_b32 m0, s6
	s_nop 0
	global_load_lds_dwordx4 v[162:163], off
	s_waitcnt lgkmcnt(8)
	s_barrier
	s_waitcnt lgkmcnt(4)
	s_setprio 1
	s_waitcnt lgkmcnt(4)
	v_mfma_f32_16x16x32_bf16 v[124:127], v[178:181], v[194:197], v[124:127]
	v_mfma_f32_16x16x32_bf16 v[120:123], v[186:189], v[194:197], v[120:123]
	v_mfma_f32_16x16x32_bf16 v[116:119], v[178:181], v[202:205], v[116:119]
	v_mfma_f32_16x16x32_bf16 v[112:115], v[186:189], v[202:205], v[112:115]
	v_mfma_f32_16x16x32_bf16 v[100:103], v[178:181], v[210:213], v[100:103]
	v_mfma_f32_16x16x32_bf16 v[96:99], v[186:189], v[210:213], v[96:99]
	v_mfma_f32_16x16x32_bf16 v[84:87], v[178:181], v[218:221], v[84:87]
	v_mfma_f32_16x16x32_bf16 v[80:83], v[186:189], v[218:221], v[80:83]
	s_waitcnt lgkmcnt(0)
	v_mfma_f32_16x16x32_bf16 v[124:127], v[182:185], v[198:201], v[124:127]
	v_mfma_f32_16x16x32_bf16 v[120:123], v[190:193], v[198:201], v[120:123]
	v_mfma_f32_16x16x32_bf16 v[116:119], v[182:185], v[206:209], v[116:119]
	v_mfma_f32_16x16x32_bf16 v[112:115], v[190:193], v[206:209], v[112:115]
	v_mfma_f32_16x16x32_bf16 v[100:103], v[182:185], v[214:217], v[100:103]
	v_mfma_f32_16x16x32_bf16 v[96:99], v[190:193], v[214:217], v[96:99]
	v_mfma_f32_16x16x32_bf16 v[84:87], v[182:185], v[222:225], v[84:87]
	v_mfma_f32_16x16x32_bf16 v[80:83], v[190:193], v[222:225], v[80:83]
	s_setprio 0
	s_barrier
	v_readfirstlane_b32 s6, v171
	v_lshl_add_u64 v[162:163], v[142:143], 0, s[8:9]
	s_mov_b32 m0, s6
	s_mov_b64 s[6:7], 0x20180
	ds_read_b128 v[226:229], v139 offset:16384
	ds_read_b128 v[234:237], v139 offset:18432
	ds_read_b128 v[230:233], v139 offset:17408
	ds_read_b128 v[238:241], v139 offset:19456
	global_load_lds_dwordx4 v[162:163], off
	v_lshl_add_u64 v[162:163], v[142:143], 0, s[6:7]
	v_readfirstlane_b32 s6, v172
	s_mov_b32 m0, s6
	s_nop 0
	global_load_lds_dwordx4 v[162:163], off
	s_barrier
	s_waitcnt lgkmcnt(2)
	s_setprio 1
	s_waitcnt lgkmcnt(2)
	v_mfma_f32_16x16x32_bf16 v[108:111], v[226:229], v[194:197], v[108:111]
	v_mfma_f32_16x16x32_bf16 v[104:107], v[234:237], v[194:197], v[104:107]
	v_mfma_f32_16x16x32_bf16 v[92:95], v[226:229], v[202:205], v[92:95]
	v_mfma_f32_16x16x32_bf16 v[88:91], v[234:237], v[202:205], v[88:91]
	v_mfma_f32_16x16x32_bf16 v[76:79], v[226:229], v[210:213], v[76:79]
	v_mfma_f32_16x16x32_bf16 v[72:75], v[234:237], v[210:213], v[72:75]
	v_mfma_f32_16x16x32_bf16 v[68:71], v[226:229], v[218:221], v[68:71]
	v_mfma_f32_16x16x32_bf16 v[64:67], v[234:237], v[218:221], v[64:67]
	s_waitcnt lgkmcnt(0)
	v_mfma_f32_16x16x32_bf16 v[108:111], v[230:233], v[198:201], v[108:111]
	v_mfma_f32_16x16x32_bf16 v[104:107], v[238:241], v[198:201], v[104:107]
	v_mfma_f32_16x16x32_bf16 v[92:95], v[230:233], v[206:209], v[92:95]
	v_mfma_f32_16x16x32_bf16 v[88:91], v[238:241], v[206:209], v[88:91]
	v_mfma_f32_16x16x32_bf16 v[76:79], v[230:233], v[214:217], v[76:79]
	v_mfma_f32_16x16x32_bf16 v[72:75], v[238:241], v[214:217], v[72:75]
	v_mfma_f32_16x16x32_bf16 v[68:71], v[230:233], v[222:225], v[68:71]
	v_mfma_f32_16x16x32_bf16 v[64:67], v[238:241], v[222:225], v[64:67]
	s_setprio 0
	v_readfirstlane_b32 s6, v147
	v_lshl_add_u64 v[162:163], v[140:141], 0, s[24:25]
	s_mov_b32 m0, s6
	v_readfirstlane_b32 s6, v173
	s_barrier
	ds_read_b128 v[194:197], v135 offset:16384
	ds_read_b128 v[202:205], v135 offset:18432
	ds_read_b128 v[210:213], v135 offset:20480
	ds_read_b128 v[218:221], v135 offset:22528
	ds_read_b128 v[198:201], v135 offset:17408
	ds_read_b128 v[206:209], v135 offset:19456
	ds_read_b128 v[214:217], v135 offset:21504
	ds_read_b128 v[222:225], v135 offset:23552
	global_load_lds_dwordx4 v[162:163], off
	v_lshl_add_u64 v[140:141], v[140:141], 0, s[28:29]
	s_mov_b32 m0, s6
	s_nop 0
	global_load_lds_dwordx4 v[140:141], off
	s_barrier
	s_waitcnt lgkmcnt(4)
	s_setprio 1
	s_waitcnt lgkmcnt(4)
	v_mfma_f32_16x16x32_bf16 v[60:63], v[178:181], v[194:197], v[60:63]
	v_mfma_f32_16x16x32_bf16 v[56:59], v[186:189], v[194:197], v[56:59]
	v_mfma_f32_16x16x32_bf16 v[52:55], v[178:181], v[202:205], v[52:55]
	v_mfma_f32_16x16x32_bf16 v[44:47], v[186:189], v[202:205], v[44:47]
	v_mfma_f32_16x16x32_bf16 v[36:39], v[178:181], v[210:213], v[36:39]
	v_mfma_f32_16x16x32_bf16 v[28:31], v[186:189], v[210:213], v[28:31]
	v_mfma_f32_16x16x32_bf16 v[20:23], v[178:181], v[218:221], v[20:23]
	v_mfma_f32_16x16x32_bf16 v[12:15], v[186:189], v[218:221], v[12:15]
	s_waitcnt lgkmcnt(0)
	v_mfma_f32_16x16x32_bf16 v[60:63], v[182:185], v[198:201], v[60:63]
	v_mfma_f32_16x16x32_bf16 v[56:59], v[190:193], v[198:201], v[56:59]
	v_mfma_f32_16x16x32_bf16 v[52:55], v[182:185], v[206:209], v[52:55]
	v_mfma_f32_16x16x32_bf16 v[44:47], v[190:193], v[206:209], v[44:47]
	v_mfma_f32_16x16x32_bf16 v[36:39], v[182:185], v[214:217], v[36:39]
	v_mfma_f32_16x16x32_bf16 v[28:31], v[190:193], v[214:217], v[28:31]
	v_mfma_f32_16x16x32_bf16 v[20:23], v[182:185], v[222:225], v[20:23]
	v_mfma_f32_16x16x32_bf16 v[12:15], v[190:193], v[222:225], v[12:15]
	s_setprio 0
	s_barrier
	s_mov_b64 s[6:7], 0x40180
	v_lshl_add_u64 v[140:141], v[142:143], 0, s[6:7]
	v_readfirstlane_b32 s6, v174
	s_mov_b32 m0, s6
	s_mov_b64 s[6:7], 0x60180
	global_load_lds_dwordx4 v[140:141], off
	v_lshl_add_u64 v[140:141], v[142:143], 0, s[6:7]
	v_readfirstlane_b32 s6, v175
	s_mov_b32 m0, s6
	s_nop 0
	global_load_lds_dwordx4 v[140:141], off
	s_waitcnt vmcnt(6)
	s_barrier
	s_setprio 1
	v_mfma_f32_16x16x32_bf16 v[48:51], v[226:229], v[194:197], v[48:51]
	v_mfma_f32_16x16x32_bf16 v[40:43], v[234:237], v[194:197], v[40:43]
	v_mfma_f32_16x16x32_bf16 v[32:35], v[226:229], v[202:205], v[32:35]
	v_mfma_f32_16x16x32_bf16 v[24:27], v[234:237], v[202:205], v[24:27]
	v_mfma_f32_16x16x32_bf16 v[16:19], v[226:229], v[210:213], v[16:19]
	v_mfma_f32_16x16x32_bf16 v[8:11], v[234:237], v[210:213], v[8:11]
	v_mfma_f32_16x16x32_bf16 v[4:7], v[226:229], v[218:221], v[4:7]
	v_mfma_f32_16x16x32_bf16 v[0:3], v[234:237], v[218:221], v[0:3]
	v_mfma_f32_16x16x32_bf16 v[48:51], v[230:233], v[198:201], v[48:51]
	v_mfma_f32_16x16x32_bf16 v[40:43], v[238:241], v[198:201], v[40:43]
	v_mfma_f32_16x16x32_bf16 v[32:35], v[230:233], v[206:209], v[32:35]
	v_mfma_f32_16x16x32_bf16 v[24:27], v[238:241], v[206:209], v[24:27]
	v_mfma_f32_16x16x32_bf16 v[16:19], v[230:233], v[214:217], v[16:19]
	v_mfma_f32_16x16x32_bf16 v[8:11], v[238:241], v[214:217], v[8:11]
	v_mfma_f32_16x16x32_bf16 v[4:7], v[230:233], v[222:225], v[4:7]
	v_mfma_f32_16x16x32_bf16 v[0:3], v[238:241], v[222:225], v[0:3]
	s_setprio 0
	s_add_i32 s5, s5, 2
	v_lshl_add_u64 v[130:131], v[130:131], 0, s[86:87]
	s_cmp_gt_u32 s5, 11
	v_lshl_add_u64 v[132:133], v[132:133], 0, s[86:87]
	s_barrier
	s_cbranch_scc0 .LBB0_114
	s_mov_b64 s[6:7], 0x40780
	v_readfirstlane_b32 s5, v177
	v_lshl_add_u64 v[140:141], v[128:129], 0, s[6:7]
	s_mov_b32 m0, s5
	s_mov_b64 s[6:7], 0x60780
	v_readfirstlane_b32 s5, v176
	ds_read_b128 v[130:133], v145
	ds_read_b128 v[146:149], v145 offset:1024
	ds_read_b128 v[150:153], v145 offset:2048
	ds_read_b128 v[170:173], v145 offset:3072
	ds_read_b128 v[178:181], v144
	ds_read_b128 v[182:185], v144 offset:1024
	ds_read_b128 v[186:189], v144 offset:2048
	ds_read_b128 v[190:193], v144 offset:3072
	ds_read_b128 v[194:197], v144 offset:4096
	ds_read_b128 v[198:201], v144 offset:5120
	ds_read_b128 v[202:205], v144 offset:6144
	ds_read_b128 v[206:209], v144 offset:7168
	global_load_lds_dwordx4 v[140:141], off
	v_lshl_add_u64 v[128:129], v[128:129], 0, s[6:7]
	s_mov_b32 m0, s5
	s_nop 0
	global_load_lds_dwordx4 v[128:129], off
	s_barrier
	s_waitcnt lgkmcnt(0)
	s_setprio 1
	s_waitcnt lgkmcnt(0)
	v_mfma_f32_16x16x32_bf16 v[124:127], v[130:133], v[178:181], v[124:127]
	v_mfma_f32_16x16x32_bf16 v[116:119], v[130:133], v[186:189], v[116:119]
	v_mfma_f32_16x16x32_bf16 v[100:103], v[130:133], v[194:197], v[100:103]
	v_mfma_f32_16x16x32_bf16 v[84:87], v[130:133], v[202:205], v[84:87]
	v_mfma_f32_16x16x32_bf16 v[124:127], v[146:149], v[182:185], v[124:127]
	v_mfma_f32_16x16x32_bf16 v[120:123], v[150:153], v[178:181], v[120:123]
	v_mfma_f32_16x16x32_bf16 v[116:119], v[146:149], v[190:193], v[116:119]
	v_mfma_f32_16x16x32_bf16 v[112:115], v[150:153], v[186:189], v[112:115]
	v_mfma_f32_16x16x32_bf16 v[100:103], v[146:149], v[198:201], v[100:103]
	v_mfma_f32_16x16x32_bf16 v[96:99], v[150:153], v[194:197], v[96:99]
	v_mfma_f32_16x16x32_bf16 v[84:87], v[146:149], v[206:209], v[84:87]
	v_mfma_f32_16x16x32_bf16 v[80:83], v[150:153], v[202:205], v[80:83]
	v_mfma_f32_16x16x32_bf16 v[174:177], v[170:173], v[182:185], v[120:123]
	v_mfma_f32_16x16x32_bf16 v[210:213], v[170:173], v[190:193], v[112:115]
	v_mfma_f32_16x16x32_bf16 v[214:217], v[170:173], v[198:201], v[96:99]
	v_mfma_f32_16x16x32_bf16 v[218:221], v[170:173], v[206:209], v[80:83]
	s_setprio 0
	s_barrier
	s_nop 1
	ds_read_b128 v[80:83], v145 offset:16384
	ds_read_b128 v[96:99], v145 offset:17408
	ds_read_b128 v[112:115], v145 offset:18432
	ds_read_b128 v[120:123], v145 offset:19456
	s_barrier
	s_waitcnt lgkmcnt(0)
	s_setprio 1
	s_waitcnt lgkmcnt(0)
	v_mfma_f32_16x16x32_bf16 v[108:111], v[80:83], v[178:181], v[108:111]
	v_mfma_f32_16x16x32_bf16 v[92:95], v[80:83], v[186:189], v[92:95]
	v_mfma_f32_16x16x32_bf16 v[76:79], v[80:83], v[194:197], v[76:79]
	v_mfma_f32_16x16x32_bf16 v[68:71], v[80:83], v[202:205], v[68:71]
	v_mfma_f32_16x16x32_bf16 v[108:111], v[96:99], v[182:185], v[108:111]
	v_mfma_f32_16x16x32_bf16 v[104:107], v[112:115], v[178:181], v[104:107]
	v_mfma_f32_16x16x32_bf16 v[92:95], v[96:99], v[190:193], v[92:95]
	v_mfma_f32_16x16x32_bf16 v[88:91], v[112:115], v[186:189], v[88:91]
	v_mfma_f32_16x16x32_bf16 v[76:79], v[96:99], v[198:201], v[76:79]
	v_mfma_f32_16x16x32_bf16 v[72:75], v[112:115], v[194:197], v[72:75]
	v_mfma_f32_16x16x32_bf16 v[68:71], v[96:99], v[206:209], v[68:71]
	v_mfma_f32_16x16x32_bf16 v[64:67], v[112:115], v[202:205], v[64:67]
	v_mfma_f32_16x16x32_bf16 v[178:181], v[120:123], v[182:185], v[104:107]
	v_mfma_f32_16x16x32_bf16 v[182:185], v[120:123], v[190:193], v[88:91]
	v_mfma_f32_16x16x32_bf16 v[186:189], v[120:123], v[198:201], v[72:75]
	v_mfma_f32_16x16x32_bf16 v[190:193], v[120:123], v[206:209], v[64:67]
	s_setprio 0
	s_barrier
	s_nop 1
	ds_read_b128 v[64:67], v144 offset:16384
	ds_read_b128 v[72:75], v144 offset:17408
	ds_read_b128 v[88:91], v144 offset:18432
	ds_read_b128 v[104:107], v144 offset:19456
	ds_read_b128 v[194:197], v144 offset:20480
	ds_read_b128 v[198:201], v144 offset:21504
	ds_read_b128 v[202:205], v144 offset:22528
	ds_read_b128 v[206:209], v144 offset:23552
	s_waitcnt vmcnt(4)
	s_barrier
	s_waitcnt lgkmcnt(0)
	s_setprio 1
	s_waitcnt lgkmcnt(0)
	v_mfma_f32_16x16x32_bf16 v[60:63], v[130:133], v[64:67], v[60:63]
	v_mfma_f32_16x16x32_bf16 v[56:59], v[150:153], v[64:67], v[56:59]
	v_mfma_f32_16x16x32_bf16 v[52:55], v[130:133], v[88:91], v[52:55]
	v_mfma_f32_16x16x32_bf16 v[36:39], v[130:133], v[194:197], v[36:39]
	v_mfma_f32_16x16x32_bf16 v[20:23], v[130:133], v[202:205], v[20:23]
	v_mfma_f32_16x16x32_bf16 v[60:63], v[146:149], v[72:75], v[60:63]
	v_mfma_f32_16x16x32_bf16 v[56:59], v[170:173], v[72:75], v[56:59]
	v_mfma_f32_16x16x32_bf16 v[52:55], v[146:149], v[104:107], v[52:55]
	v_mfma_f32_16x16x32_bf16 v[44:47], v[150:153], v[88:91], v[44:47]
	v_mfma_f32_16x16x32_bf16 v[36:39], v[146:149], v[198:201], v[36:39]
	v_mfma_f32_16x16x32_bf16 v[28:31], v[150:153], v[194:197], v[28:31]
	v_mfma_f32_16x16x32_bf16 v[20:23], v[146:149], v[206:209], v[20:23]
	v_mfma_f32_16x16x32_bf16 v[12:15], v[150:153], v[202:205], v[12:15]
	v_mfma_f32_16x16x32_bf16 v[222:225], v[170:173], v[104:107], v[44:47]
	v_mfma_f32_16x16x32_bf16 v[226:229], v[170:173], v[198:201], v[28:31]
	v_mfma_f32_16x16x32_bf16 v[128:131], v[170:173], v[206:209], v[12:15]
	s_setprio 0
	s_setprio 1
	v_mfma_f32_16x16x32_bf16 v[12:15], v[80:83], v[64:67], v[48:51]
	v_mfma_f32_16x16x32_bf16 v[144:147], v[96:99], v[72:75], v[12:15]
	v_mfma_f32_16x16x32_bf16 v[12:15], v[112:115], v[64:67], v[40:43]
	v_mfma_f32_16x16x32_bf16 v[40:43], v[120:123], v[72:75], v[12:15]
	v_mfma_f32_16x16x32_bf16 v[12:15], v[80:83], v[88:91], v[32:35]
	v_mfma_f32_16x16x32_bf16 v[148:151], v[96:99], v[104:107], v[12:15]
	v_mfma_f32_16x16x32_bf16 v[12:15], v[112:115], v[88:91], v[24:27]
	v_mfma_f32_16x16x32_bf16 v[8:11], v[112:115], v[194:197], v[8:11]
	v_mfma_f32_16x16x32_bf16 v[4:7], v[80:83], v[202:205], v[4:7]
	v_mfma_f32_16x16x32_bf16 v[24:27], v[120:123], v[104:107], v[12:15]
	v_mfma_f32_16x16x32_bf16 v[12:15], v[80:83], v[194:197], v[16:19]
	v_mfma_f32_16x16x32_bf16 v[8:11], v[120:123], v[198:201], v[8:11]
	v_mfma_f32_16x16x32_bf16 v[4:7], v[96:99], v[206:209], v[4:7]
	v_mfma_f32_16x16x32_bf16 v[0:3], v[112:115], v[202:205], v[0:3]
	v_mfma_f32_16x16x32_bf16 v[170:173], v[96:99], v[198:201], v[12:15]
	v_mfma_f32_16x16x32_bf16 v[194:197], v[120:123], v[206:209], v[0:3]
	s_setprio 0
	s_barrier
	s_nop 3
	ds_read_b128 v[0:3], v139
	ds_read_b128 v[12:15], v139 offset:1024
	ds_read_b128 v[198:201], v139 offset:2048
	ds_read_b128 v[202:205], v139 offset:3072
	ds_read_b128 v[16:19], v135
	ds_read_b128 v[28:31], v135 offset:1024
	ds_read_b128 v[32:35], v135 offset:2048
	ds_read_b128 v[44:47], v135 offset:3072
	ds_read_b128 v[48:51], v135 offset:4096
	ds_read_b128 v[206:209], v135 offset:5120
	ds_read_b128 v[230:233], v135 offset:6144
	ds_read_b128 v[234:237], v135 offset:7168
	s_waitcnt vmcnt(2)
	s_barrier
	s_waitcnt lgkmcnt(0)
	s_setprio 1
	s_waitcnt lgkmcnt(0)
	v_mfma_f32_16x16x32_bf16 v[64:67], v[0:3], v[16:19], v[124:127]
	v_mfma_f32_16x16x32_bf16 v[120:123], v[12:15], v[28:31], v[64:67]
	v_mfma_f32_16x16x32_bf16 v[64:67], v[198:201], v[16:19], v[174:177]
	v_mfma_f32_16x16x32_bf16 v[112:115], v[202:205], v[28:31], v[64:67]
	v_mfma_f32_16x16x32_bf16 v[64:67], v[0:3], v[32:35], v[116:119]
	v_mfma_f32_16x16x32_bf16 v[104:107], v[12:15], v[44:47], v[64:67]
	v_mfma_f32_16x16x32_bf16 v[64:67], v[198:201], v[32:35], v[210:213]
	v_mfma_f32_16x16x32_bf16 v[96:99], v[202:205], v[44:47], v[64:67]
	v_mfma_f32_16x16x32_bf16 v[64:67], v[0:3], v[48:51], v[100:103]
	v_mfma_f32_16x16x32_bf16 v[88:91], v[12:15], v[206:209], v[64:67]
	v_mfma_f32_16x16x32_bf16 v[64:67], v[198:201], v[48:51], v[214:217]
	v_mfma_f32_16x16x32_bf16 v[80:83], v[202:205], v[206:209], v[64:67]
	v_mfma_f32_16x16x32_bf16 v[64:67], v[0:3], v[230:233], v[84:87]
	v_mfma_f32_16x16x32_bf16 v[72:75], v[12:15], v[234:237], v[64:67]
	v_mfma_f32_16x16x32_bf16 v[64:67], v[198:201], v[230:233], v[218:221]
	v_mfma_f32_16x16x32_bf16 v[64:67], v[202:205], v[234:237], v[64:67]
	s_setprio 0
	s_barrier
	ds_read_b128 v[174:177], v139 offset:16384
	ds_read_b128 v[210:213], v139 offset:17408
	ds_read_b128 v[214:217], v139 offset:18432
	ds_read_b128 v[218:221], v139 offset:19456
	s_waitcnt vmcnt(0)
	s_barrier
	s_waitcnt lgkmcnt(0)
	s_setprio 1
	s_waitcnt lgkmcnt(0)
	v_mfma_f32_16x16x32_bf16 v[84:87], v[174:177], v[16:19], v[108:111]
	v_mfma_f32_16x16x32_bf16 v[16:19], v[214:217], v[16:19], v[178:181]
	v_mfma_f32_16x16x32_bf16 v[116:119], v[218:221], v[28:31], v[16:19]
	v_mfma_f32_16x16x32_bf16 v[16:19], v[174:177], v[32:35], v[92:95]
	v_mfma_f32_16x16x32_bf16 v[108:111], v[210:213], v[44:47], v[16:19]
	v_mfma_f32_16x16x32_bf16 v[16:19], v[214:217], v[32:35], v[182:185]
	v_mfma_f32_16x16x32_bf16 v[100:103], v[218:221], v[44:47], v[16:19]
	v_mfma_f32_16x16x32_bf16 v[16:19], v[174:177], v[48:51], v[76:79]
	v_mfma_f32_16x16x32_bf16 v[92:95], v[210:213], v[206:209], v[16:19]
	v_mfma_f32_16x16x32_bf16 v[16:19], v[214:217], v[48:51], v[186:189]
	v_mfma_f32_16x16x32_bf16 v[124:127], v[210:213], v[28:31], v[84:87]
	v_mfma_f32_16x16x32_bf16 v[84:87], v[218:221], v[206:209], v[16:19]
	v_mfma_f32_16x16x32_bf16 v[16:19], v[174:177], v[230:233], v[68:71]
	v_mfma_f32_16x16x32_bf16 v[76:79], v[210:213], v[234:237], v[16:19]
	v_mfma_f32_16x16x32_bf16 v[16:19], v[214:217], v[230:233], v[190:193]
	v_mfma_f32_16x16x32_bf16 v[68:71], v[218:221], v[234:237], v[16:19]
	s_setprio 0
	s_barrier
	ds_read_b128 v[178:181], v135 offset:16384
	ds_read_b128 v[182:185], v135 offset:17408
	ds_read_b128 v[186:189], v135 offset:18432
	ds_read_b128 v[190:193], v135 offset:19456
	ds_read_b128 v[206:209], v135 offset:20480
	ds_read_b128 v[230:233], v135 offset:21504
	ds_read_b128 v[234:237], v135 offset:22528
	ds_read_b128 v[238:241], v135 offset:23552
	s_barrier
	s_waitcnt lgkmcnt(0)
	s_setprio 1
	s_waitcnt lgkmcnt(0)
	v_mfma_f32_16x16x32_bf16 v[16:19], v[0:3], v[178:181], v[60:63]
	v_mfma_f32_16x16x32_bf16 v[60:63], v[12:15], v[182:185], v[16:19]
	v_mfma_f32_16x16x32_bf16 v[16:19], v[198:201], v[178:181], v[56:59]
	v_mfma_f32_16x16x32_bf16 v[48:51], v[202:205], v[182:185], v[16:19]
	v_mfma_f32_16x16x32_bf16 v[16:19], v[0:3], v[186:189], v[52:55]
	v_mfma_f32_16x16x32_bf16 v[44:47], v[12:15], v[190:193], v[16:19]
	v_mfma_f32_16x16x32_bf16 v[16:19], v[198:201], v[186:189], v[222:225]
	v_mfma_f32_16x16x32_bf16 v[32:35], v[202:205], v[190:193], v[16:19]
	v_mfma_f32_16x16x32_bf16 v[16:19], v[0:3], v[206:209], v[36:39]
	v_mfma_f32_16x16x32_bf16 v[0:3], v[0:3], v[234:237], v[20:23]
	v_mfma_f32_16x16x32_bf16 v[28:31], v[12:15], v[230:233], v[16:19]
	v_mfma_f32_16x16x32_bf16 v[16:19], v[198:201], v[206:209], v[226:229]
	v_mfma_f32_16x16x32_bf16 v[12:15], v[12:15], v[238:241], v[0:3]
	v_mfma_f32_16x16x32_bf16 v[0:3], v[198:201], v[234:237], v[128:131]
	v_mfma_f32_16x16x32_bf16 v[16:19], v[202:205], v[230:233], v[16:19]
	v_mfma_f32_16x16x32_bf16 v[0:3], v[202:205], v[238:241], v[0:3]
	s_setprio 0
	s_setprio 1
	v_mfma_f32_16x16x32_bf16 v[20:23], v[174:177], v[178:181], v[144:147]
	v_mfma_f32_16x16x32_bf16 v[56:59], v[210:213], v[182:185], v[20:23]
	v_mfma_f32_16x16x32_bf16 v[20:23], v[214:217], v[178:181], v[40:43]
	v_mfma_f32_16x16x32_bf16 v[52:55], v[218:221], v[182:185], v[20:23]
	v_mfma_f32_16x16x32_bf16 v[20:23], v[174:177], v[186:189], v[148:151]
	v_mfma_f32_16x16x32_bf16 v[40:43], v[210:213], v[190:193], v[20:23]
	v_mfma_f32_16x16x32_bf16 v[20:23], v[214:217], v[186:189], v[24:27]
	v_mfma_f32_16x16x32_bf16 v[36:39], v[218:221], v[190:193], v[20:23]
	v_mfma_f32_16x16x32_bf16 v[20:23], v[174:177], v[206:209], v[170:173]
	v_mfma_f32_16x16x32_bf16 v[8:11], v[214:217], v[206:209], v[8:11]
	v_mfma_f32_16x16x32_bf16 v[4:7], v[174:177], v[234:237], v[4:7]
	v_mfma_f32_16x16x32_bf16 v[24:27], v[210:213], v[230:233], v[20:23]
	v_mfma_f32_16x16x32_bf16 v[20:23], v[218:221], v[230:233], v[8:11]
	v_mfma_f32_16x16x32_bf16 v[8:11], v[210:213], v[238:241], v[4:7]
	v_mfma_f32_16x16x32_bf16 v[4:7], v[214:217], v[234:237], v[194:197]
	v_mfma_f32_16x16x32_bf16 v[4:7], v[218:221], v[238:241], v[4:7]
	s_setprio 0
	s_movk_i32 s5, 0x100
	v_cmp_gt_u32_e32 vcc, s5, v134
	s_barrier
	s_and_saveexec_b64 s[6:7], vcc
	s_cbranch_execz .LBB0_110
	s_barrier
	s_branch .LBB0_110

.LBB0_153:
	ds_read_b128 v[178:181], v135
	ds_read_b128 v[186:189], v135 offset:2048
	ds_read_b128 v[182:185], v135 offset:1024
	ds_read_b128 v[190:193], v135 offset:3072
	v_add_u32_e32 v176, 0x4000, v147
	v_lshl_add_u64 v[140:141], v[132:133], 0, v[136:137]
	v_readfirstlane_b32 s5, v176
	v_add_u32_e32 v177, 0x6000, v147
	v_lshl_add_u64 v[142:143], v[140:141], 0, s[36:37]
	s_mov_b32 m0, s5
	v_readfirstlane_b32 s5, v177
	ds_read_b128 v[194:197], v134
	ds_read_b128 v[202:205], v134 offset:2048
	ds_read_b128 v[210:213], v134 offset:4096
	ds_read_b128 v[218:221], v134 offset:6144
	ds_read_b128 v[198:201], v134 offset:1024
	ds_read_b128 v[206:209], v134 offset:3072
	ds_read_b128 v[214:217], v134 offset:5120
	ds_read_b128 v[222:225], v134 offset:7168
	global_load_lds_dwordx4 v[142:143], off
	v_lshl_add_u64 v[142:143], v[140:141], 0, s[96:97]
	s_mov_b32 m0, s5
	s_nop 0
	global_load_lds_dwordx4 v[142:143], off
	s_waitcnt lgkmcnt(8)
	s_barrier
	s_waitcnt lgkmcnt(4)
	s_setprio 1
	s_waitcnt lgkmcnt(4)
	v_mfma_f32_16x16x32_bf16 v[124:127], v[178:181], v[194:197], v[124:127]
	v_mfma_f32_16x16x32_bf16 v[120:123], v[186:189], v[194:197], v[120:123]
	v_mfma_f32_16x16x32_bf16 v[116:119], v[178:181], v[202:205], v[116:119]
	v_mfma_f32_16x16x32_bf16 v[112:115], v[186:189], v[202:205], v[112:115]
	v_mfma_f32_16x16x32_bf16 v[100:103], v[178:181], v[210:213], v[100:103]
	v_mfma_f32_16x16x32_bf16 v[96:99], v[186:189], v[210:213], v[96:99]
	v_mfma_f32_16x16x32_bf16 v[84:87], v[178:181], v[218:221], v[84:87]
	v_mfma_f32_16x16x32_bf16 v[80:83], v[186:189], v[218:221], v[80:83]
	s_waitcnt lgkmcnt(0)
	v_mfma_f32_16x16x32_bf16 v[124:127], v[182:185], v[198:201], v[124:127]
	v_mfma_f32_16x16x32_bf16 v[120:123], v[190:193], v[198:201], v[120:123]
	v_mfma_f32_16x16x32_bf16 v[116:119], v[182:185], v[206:209], v[116:119]
	v_mfma_f32_16x16x32_bf16 v[112:115], v[190:193], v[206:209], v[112:115]
	v_mfma_f32_16x16x32_bf16 v[100:103], v[182:185], v[214:217], v[100:103]
	v_mfma_f32_16x16x32_bf16 v[96:99], v[190:193], v[214:217], v[96:99]
	v_mfma_f32_16x16x32_bf16 v[84:87], v[182:185], v[222:225], v[84:87]
	v_mfma_f32_16x16x32_bf16 v[80:83], v[190:193], v[222:225], v[80:83]
	s_setprio 0
	s_barrier
	v_lshl_add_u64 v[142:143], v[130:131], 0, v[136:137]
	s_mov_b64 s[26:27], 0xb00100
	v_readfirstlane_b32 s5, v148
	v_lshl_add_u64 v[162:163], v[142:143], 0, s[26:27]
	s_mov_b32 m0, s5
	s_mov_b64 s[26:27], 0xb58100
	v_readfirstlane_b32 s5, v149
	ds_read_b128 v[226:229], v135 offset:16384
	ds_read_b128 v[234:237], v135 offset:18432
	ds_read_b128 v[230:233], v135 offset:17408
	ds_read_b128 v[238:241], v135 offset:19456
	global_load_lds_dwordx4 v[162:163], off
	v_lshl_add_u64 v[162:163], v[142:143], 0, s[26:27]
	s_mov_b32 m0, s5
	s_nop 0
	global_load_lds_dwordx4 v[162:163], off
	s_barrier
	s_waitcnt lgkmcnt(2)
	s_setprio 1
	s_waitcnt lgkmcnt(2)
	v_mfma_f32_16x16x32_bf16 v[108:111], v[226:229], v[194:197], v[108:111]
	v_mfma_f32_16x16x32_bf16 v[104:107], v[234:237], v[194:197], v[104:107]
	v_mfma_f32_16x16x32_bf16 v[92:95], v[226:229], v[202:205], v[92:95]
	v_mfma_f32_16x16x32_bf16 v[88:91], v[234:237], v[202:205], v[88:91]
	v_mfma_f32_16x16x32_bf16 v[76:79], v[226:229], v[210:213], v[76:79]
	v_mfma_f32_16x16x32_bf16 v[72:75], v[234:237], v[210:213], v[72:75]
	v_mfma_f32_16x16x32_bf16 v[68:71], v[226:229], v[218:221], v[68:71]
	v_mfma_f32_16x16x32_bf16 v[64:67], v[234:237], v[218:221], v[64:67]
	s_waitcnt lgkmcnt(0)
	v_mfma_f32_16x16x32_bf16 v[108:111], v[230:233], v[198:201], v[108:111]
	v_mfma_f32_16x16x32_bf16 v[104:107], v[238:241], v[198:201], v[104:107]
	v_mfma_f32_16x16x32_bf16 v[92:95], v[230:233], v[206:209], v[92:95]
	v_mfma_f32_16x16x32_bf16 v[88:91], v[238:241], v[206:209], v[88:91]
	v_mfma_f32_16x16x32_bf16 v[76:79], v[230:233], v[214:217], v[76:79]
	v_mfma_f32_16x16x32_bf16 v[72:75], v[238:241], v[214:217], v[72:75]
	v_mfma_f32_16x16x32_bf16 v[68:71], v[230:233], v[222:225], v[68:71]
	v_mfma_f32_16x16x32_bf16 v[64:67], v[238:241], v[222:225], v[64:67]
	s_setprio 0
	v_readfirstlane_b32 s5, v146
	v_lshl_add_u64 v[162:163], v[140:141], 0, s[34:35]
	s_mov_b32 m0, s5
	v_readfirstlane_b32 s5, v150
	s_barrier
	ds_read_b128 v[194:197], v134 offset:16384
	ds_read_b128 v[202:205], v134 offset:18432
	ds_read_b128 v[210:213], v134 offset:20480
	ds_read_b128 v[218:221], v134 offset:22528
	ds_read_b128 v[198:201], v134 offset:17408
	ds_read_b128 v[206:209], v134 offset:19456
	ds_read_b128 v[214:217], v134 offset:21504
	ds_read_b128 v[222:225], v134 offset:23552
	global_load_lds_dwordx4 v[162:163], off
	v_lshl_add_u64 v[162:163], v[140:141], 0, s[80:81]
	s_mov_b32 m0, s5
	s_nop 0
	global_load_lds_dwordx4 v[162:163], off
	s_barrier
	s_waitcnt lgkmcnt(4)
	s_setprio 1
	s_waitcnt lgkmcnt(4)
	v_mfma_f32_16x16x32_bf16 v[60:63], v[178:181], v[194:197], v[60:63]
	v_mfma_f32_16x16x32_bf16 v[56:59], v[186:189], v[194:197], v[56:59]
	v_mfma_f32_16x16x32_bf16 v[52:55], v[178:181], v[202:205], v[52:55]
	v_mfma_f32_16x16x32_bf16 v[44:47], v[186:189], v[202:205], v[44:47]
	v_mfma_f32_16x16x32_bf16 v[36:39], v[178:181], v[210:213], v[36:39]
	v_mfma_f32_16x16x32_bf16 v[28:31], v[186:189], v[210:213], v[28:31]
	v_mfma_f32_16x16x32_bf16 v[20:23], v[178:181], v[218:221], v[20:23]
	v_mfma_f32_16x16x32_bf16 v[12:15], v[186:189], v[218:221], v[12:15]
	s_waitcnt lgkmcnt(0)
	v_mfma_f32_16x16x32_bf16 v[60:63], v[182:185], v[198:201], v[60:63]
	v_mfma_f32_16x16x32_bf16 v[56:59], v[190:193], v[198:201], v[56:59]
	v_mfma_f32_16x16x32_bf16 v[52:55], v[182:185], v[206:209], v[52:55]
	v_mfma_f32_16x16x32_bf16 v[44:47], v[190:193], v[206:209], v[44:47]
	v_mfma_f32_16x16x32_bf16 v[36:39], v[182:185], v[214:217], v[36:39]
	v_mfma_f32_16x16x32_bf16 v[28:31], v[190:193], v[214:217], v[28:31]
	v_mfma_f32_16x16x32_bf16 v[20:23], v[182:185], v[222:225], v[20:23]
	v_mfma_f32_16x16x32_bf16 v[12:15], v[190:193], v[222:225], v[12:15]
	s_setprio 0
	s_barrier
	s_mov_b64 s[26:27], 0xbb0100
	v_readfirstlane_b32 s5, v151
	v_lshl_add_u64 v[162:163], v[142:143], 0, s[26:27]
	s_mov_b32 m0, s5
	s_mov_b64 s[26:27], 0xc08100
	v_readfirstlane_b32 s5, v152
	global_load_lds_dwordx4 v[162:163], off
	v_lshl_add_u64 v[162:163], v[142:143], 0, s[26:27]
	s_mov_b32 m0, s5
	s_nop 0
	global_load_lds_dwordx4 v[162:163], off
	s_waitcnt vmcnt(6)
	s_barrier
	s_setprio 1
	v_mfma_f32_16x16x32_bf16 v[48:51], v[226:229], v[194:197], v[48:51]
	v_mfma_f32_16x16x32_bf16 v[40:43], v[234:237], v[194:197], v[40:43]
	v_mfma_f32_16x16x32_bf16 v[32:35], v[226:229], v[202:205], v[32:35]
	v_mfma_f32_16x16x32_bf16 v[24:27], v[234:237], v[202:205], v[24:27]
	v_mfma_f32_16x16x32_bf16 v[16:19], v[226:229], v[210:213], v[16:19]
	v_mfma_f32_16x16x32_bf16 v[8:11], v[234:237], v[210:213], v[8:11]
	v_mfma_f32_16x16x32_bf16 v[4:7], v[226:229], v[218:221], v[4:7]
	v_mfma_f32_16x16x32_bf16 v[0:3], v[234:237], v[218:221], v[0:3]
	v_mfma_f32_16x16x32_bf16 v[48:51], v[230:233], v[198:201], v[48:51]
	v_mfma_f32_16x16x32_bf16 v[40:43], v[238:241], v[198:201], v[40:43]
	v_mfma_f32_16x16x32_bf16 v[32:35], v[230:233], v[206:209], v[32:35]
	v_mfma_f32_16x16x32_bf16 v[24:27], v[238:241], v[206:209], v[24:27]
	v_mfma_f32_16x16x32_bf16 v[16:19], v[230:233], v[214:217], v[16:19]
	v_mfma_f32_16x16x32_bf16 v[8:11], v[238:241], v[214:217], v[8:11]
	v_mfma_f32_16x16x32_bf16 v[4:7], v[230:233], v[222:225], v[4:7]
	v_mfma_f32_16x16x32_bf16 v[0:3], v[238:241], v[222:225], v[0:3]
	s_setprio 0
	s_barrier
	ds_read_b128 v[178:181], v145
	ds_read_b128 v[186:189], v145 offset:2048
	ds_read_b128 v[182:185], v145 offset:1024
	ds_read_b128 v[190:193], v145 offset:3072
	v_readfirstlane_b32 s5, v153
	v_lshl_add_u64 v[162:163], v[140:141], 0, s[18:19]
	s_mov_b32 m0, s5
	v_readfirstlane_b32 s5, v170
	ds_read_b128 v[194:197], v144
	ds_read_b128 v[202:205], v144 offset:2048
	ds_read_b128 v[210:213], v144 offset:4096
	ds_read_b128 v[218:221], v144 offset:6144
	ds_read_b128 v[198:201], v144 offset:1024
	ds_read_b128 v[206:209], v144 offset:3072
	ds_read_b128 v[214:217], v144 offset:5120
	ds_read_b128 v[222:225], v144 offset:7168
	global_load_lds_dwordx4 v[162:163], off
	v_lshl_add_u64 v[162:163], v[140:141], 0, s[84:85]
	s_mov_b32 m0, s5
	s_nop 0
	global_load_lds_dwordx4 v[162:163], off
	s_waitcnt lgkmcnt(8)
	s_barrier
	s_waitcnt lgkmcnt(4)
	s_setprio 1
	s_waitcnt lgkmcnt(4)
	v_mfma_f32_16x16x32_bf16 v[124:127], v[178:181], v[194:197], v[124:127]
	v_mfma_f32_16x16x32_bf16 v[120:123], v[186:189], v[194:197], v[120:123]
	v_mfma_f32_16x16x32_bf16 v[116:119], v[178:181], v[202:205], v[116:119]
	v_mfma_f32_16x16x32_bf16 v[112:115], v[186:189], v[202:205], v[112:115]
	v_mfma_f32_16x16x32_bf16 v[100:103], v[178:181], v[210:213], v[100:103]
	v_mfma_f32_16x16x32_bf16 v[96:99], v[186:189], v[210:213], v[96:99]
	v_mfma_f32_16x16x32_bf16 v[84:87], v[178:181], v[218:221], v[84:87]
	v_mfma_f32_16x16x32_bf16 v[80:83], v[186:189], v[218:221], v[80:83]
	s_waitcnt lgkmcnt(0)
	v_mfma_f32_16x16x32_bf16 v[124:127], v[182:185], v[198:201], v[124:127]
	v_mfma_f32_16x16x32_bf16 v[120:123], v[190:193], v[198:201], v[120:123]
	v_mfma_f32_16x16x32_bf16 v[116:119], v[182:185], v[206:209], v[116:119]
	v_mfma_f32_16x16x32_bf16 v[112:115], v[190:193], v[206:209], v[112:115]
	v_mfma_f32_16x16x32_bf16 v[100:103], v[182:185], v[214:217], v[100:103]
	v_mfma_f32_16x16x32_bf16 v[96:99], v[190:193], v[214:217], v[96:99]
	v_mfma_f32_16x16x32_bf16 v[84:87], v[182:185], v[222:225], v[84:87]
	v_mfma_f32_16x16x32_bf16 v[80:83], v[190:193], v[222:225], v[80:83]
	s_setprio 0
	s_barrier
	s_mov_b64 s[26:27], 0xb00180
	v_readfirstlane_b32 s5, v171
	v_lshl_add_u64 v[162:163], v[142:143], 0, s[26:27]
	s_mov_b32 m0, s5
	s_mov_b64 s[26:27], 0xb58180
	v_readfirstlane_b32 s5, v172
	ds_read_b128 v[226:229], v145 offset:16384
	ds_read_b128 v[234:237], v145 offset:18432
	ds_read_b128 v[230:233], v145 offset:17408
	ds_read_b128 v[238:241], v145 offset:19456
	global_load_lds_dwordx4 v[162:163], off
	v_lshl_add_u64 v[162:163], v[142:143], 0, s[26:27]
	s_mov_b32 m0, s5
	s_nop 0
	global_load_lds_dwordx4 v[162:163], off
	s_barrier
	s_waitcnt lgkmcnt(2)
	s_setprio 1
	s_waitcnt lgkmcnt(2)
	v_mfma_f32_16x16x32_bf16 v[108:111], v[226:229], v[194:197], v[108:111]
	v_mfma_f32_16x16x32_bf16 v[104:107], v[234:237], v[194:197], v[104:107]
	v_mfma_f32_16x16x32_bf16 v[92:95], v[226:229], v[202:205], v[92:95]
	v_mfma_f32_16x16x32_bf16 v[88:91], v[234:237], v[202:205], v[88:91]
	v_mfma_f32_16x16x32_bf16 v[76:79], v[226:229], v[210:213], v[76:79]
	v_mfma_f32_16x16x32_bf16 v[72:75], v[234:237], v[210:213], v[72:75]
	v_mfma_f32_16x16x32_bf16 v[68:71], v[226:229], v[218:221], v[68:71]
	v_mfma_f32_16x16x32_bf16 v[64:67], v[234:237], v[218:221], v[64:67]
	s_waitcnt lgkmcnt(0)
	v_mfma_f32_16x16x32_bf16 v[108:111], v[230:233], v[198:201], v[108:111]
	v_mfma_f32_16x16x32_bf16 v[104:107], v[238:241], v[198:201], v[104:107]
	v_mfma_f32_16x16x32_bf16 v[92:95], v[230:233], v[206:209], v[92:95]
	v_mfma_f32_16x16x32_bf16 v[88:91], v[238:241], v[206:209], v[88:91]
	v_mfma_f32_16x16x32_bf16 v[76:79], v[230:233], v[214:217], v[76:79]
	v_mfma_f32_16x16x32_bf16 v[72:75], v[238:241], v[214:217], v[72:75]
	v_mfma_f32_16x16x32_bf16 v[68:71], v[230:233], v[222:225], v[68:71]
	v_mfma_f32_16x16x32_bf16 v[64:67], v[238:241], v[222:225], v[64:67]
	s_setprio 0
	v_readfirstlane_b32 s5, v147
	v_lshl_add_u64 v[162:163], v[140:141], 0, s[30:31]
	s_mov_b32 m0, s5
	v_readfirstlane_b32 s5, v173
	s_barrier
	ds_read_b128 v[194:197], v144 offset:16384
	ds_read_b128 v[202:205], v144 offset:18432
	ds_read_b128 v[210:213], v144 offset:20480
	ds_read_b128 v[218:221], v144 offset:22528
	ds_read_b128 v[198:201], v144 offset:17408
	ds_read_b128 v[206:209], v144 offset:19456
	ds_read_b128 v[214:217], v144 offset:21504
	ds_read_b128 v[222:225], v144 offset:23552
	global_load_lds_dwordx4 v[162:163], off
	v_lshl_add_u64 v[140:141], v[140:141], 0, s[38:39]
	s_mov_b32 m0, s5
	s_nop 0
	global_load_lds_dwordx4 v[140:141], off
	s_barrier
	s_waitcnt lgkmcnt(4)
	s_setprio 1
	s_waitcnt lgkmcnt(4)
	v_mfma_f32_16x16x32_bf16 v[60:63], v[178:181], v[194:197], v[60:63]
	v_mfma_f32_16x16x32_bf16 v[56:59], v[186:189], v[194:197], v[56:59]
	v_mfma_f32_16x16x32_bf16 v[52:55], v[178:181], v[202:205], v[52:55]
	v_mfma_f32_16x16x32_bf16 v[44:47], v[186:189], v[202:205], v[44:47]
	v_mfma_f32_16x16x32_bf16 v[36:39], v[178:181], v[210:213], v[36:39]
	v_mfma_f32_16x16x32_bf16 v[28:31], v[186:189], v[210:213], v[28:31]
	v_mfma_f32_16x16x32_bf16 v[20:23], v[178:181], v[218:221], v[20:23]
	v_mfma_f32_16x16x32_bf16 v[12:15], v[186:189], v[218:221], v[12:15]
	s_waitcnt lgkmcnt(0)
	v_mfma_f32_16x16x32_bf16 v[60:63], v[182:185], v[198:201], v[60:63]
	v_mfma_f32_16x16x32_bf16 v[56:59], v[190:193], v[198:201], v[56:59]
	v_mfma_f32_16x16x32_bf16 v[52:55], v[182:185], v[206:209], v[52:55]
	v_mfma_f32_16x16x32_bf16 v[44:47], v[190:193], v[206:209], v[44:47]
	v_mfma_f32_16x16x32_bf16 v[36:39], v[182:185], v[214:217], v[36:39]
	v_mfma_f32_16x16x32_bf16 v[28:31], v[190:193], v[214:217], v[28:31]
	v_mfma_f32_16x16x32_bf16 v[20:23], v[182:185], v[222:225], v[20:23]
	v_mfma_f32_16x16x32_bf16 v[12:15], v[190:193], v[222:225], v[12:15]
	s_setprio 0
	s_barrier
	s_mov_b64 s[26:27], 0xbb0180
	v_readfirstlane_b32 s5, v174
	v_lshl_add_u64 v[140:141], v[142:143], 0, s[26:27]
	s_mov_b32 m0, s5
	s_mov_b64 s[26:27], 0xc08180
	v_readfirstlane_b32 s5, v175
	global_load_lds_dwordx4 v[140:141], off
	v_lshl_add_u64 v[140:141], v[142:143], 0, s[26:27]
	s_mov_b32 m0, s5
	s_nop 0
	global_load_lds_dwordx4 v[140:141], off
	s_waitcnt vmcnt(6)
	s_barrier
	s_setprio 1
	v_mfma_f32_16x16x32_bf16 v[48:51], v[226:229], v[194:197], v[48:51]
	v_mfma_f32_16x16x32_bf16 v[40:43], v[234:237], v[194:197], v[40:43]
	v_mfma_f32_16x16x32_bf16 v[32:35], v[226:229], v[202:205], v[32:35]
	v_mfma_f32_16x16x32_bf16 v[24:27], v[234:237], v[202:205], v[24:27]
	v_mfma_f32_16x16x32_bf16 v[16:19], v[226:229], v[210:213], v[16:19]
	v_mfma_f32_16x16x32_bf16 v[8:11], v[234:237], v[210:213], v[8:11]
	v_mfma_f32_16x16x32_bf16 v[4:7], v[226:229], v[218:221], v[4:7]
	v_mfma_f32_16x16x32_bf16 v[0:3], v[234:237], v[218:221], v[0:3]
	v_mfma_f32_16x16x32_bf16 v[48:51], v[230:233], v[198:201], v[48:51]
	v_mfma_f32_16x16x32_bf16 v[40:43], v[238:241], v[198:201], v[40:43]
	v_mfma_f32_16x16x32_bf16 v[32:35], v[230:233], v[206:209], v[32:35]
	v_mfma_f32_16x16x32_bf16 v[24:27], v[238:241], v[206:209], v[24:27]
	v_mfma_f32_16x16x32_bf16 v[16:19], v[230:233], v[214:217], v[16:19]
	v_mfma_f32_16x16x32_bf16 v[8:11], v[238:241], v[214:217], v[8:11]
	v_mfma_f32_16x16x32_bf16 v[4:7], v[230:233], v[222:225], v[4:7]
	v_mfma_f32_16x16x32_bf16 v[0:3], v[238:241], v[222:225], v[0:3]
	s_setprio 0
	s_add_i32 s4, s4, 2
	v_lshl_add_u64 v[130:131], v[130:131], 0, s[86:87]
	s_cmp_gt_u32 s4, 39
	v_lshl_add_u64 v[132:133], v[132:133], 0, s[86:87]
	s_barrier
	s_cbranch_scc0 .LBB0_153
	s_mov_b64 s[4:5], 0xb1580
	v_lshl_add_u64 v[140:141], v[128:129], 0, s[4:5]
	v_readfirstlane_b32 s4, v176
	s_mov_b32 m0, s4
	s_mov_b64 s[4:5], 0x109580
	v_lshl_add_u64 v[128:129], v[128:129], 0, s[4:5]
	v_readfirstlane_b32 s4, v177
	ds_read_b128 v[130:133], v135
	ds_read_b128 v[146:149], v135 offset:1024
	ds_read_b128 v[150:153], v135 offset:2048
	ds_read_b128 v[170:173], v135 offset:3072
	ds_read_b128 v[178:181], v134
	ds_read_b128 v[182:185], v134 offset:1024
	ds_read_b128 v[186:189], v134 offset:2048
	ds_read_b128 v[190:193], v134 offset:3072
	ds_read_b128 v[194:197], v134 offset:4096
	ds_read_b128 v[198:201], v134 offset:5120
	ds_read_b128 v[202:205], v134 offset:6144
	ds_read_b128 v[206:209], v134 offset:7168
	global_load_lds_dwordx4 v[140:141], off
	s_mov_b32 m0, s4
	s_nop 0
	global_load_lds_dwordx4 v[128:129], off
	s_barrier
	s_waitcnt lgkmcnt(0)
	s_setprio 1
	s_waitcnt lgkmcnt(0)
	v_mfma_f32_16x16x32_bf16 v[124:127], v[130:133], v[178:181], v[124:127]
	v_mfma_f32_16x16x32_bf16 v[120:123], v[150:153], v[178:181], v[120:123]
	v_mfma_f32_16x16x32_bf16 v[116:119], v[130:133], v[186:189], v[116:119]
	v_mfma_f32_16x16x32_bf16 v[112:115], v[150:153], v[186:189], v[112:115]
	v_mfma_f32_16x16x32_bf16 v[100:103], v[130:133], v[194:197], v[100:103]
	v_mfma_f32_16x16x32_bf16 v[96:99], v[150:153], v[194:197], v[96:99]
	v_mfma_f32_16x16x32_bf16 v[84:87], v[130:133], v[202:205], v[84:87]
	v_mfma_f32_16x16x32_bf16 v[80:83], v[150:153], v[202:205], v[80:83]
	v_mfma_f32_16x16x32_bf16 v[124:127], v[146:149], v[182:185], v[124:127]
	v_mfma_f32_16x16x32_bf16 v[120:123], v[170:173], v[182:185], v[120:123]
	v_mfma_f32_16x16x32_bf16 v[116:119], v[146:149], v[190:193], v[116:119]
	v_mfma_f32_16x16x32_bf16 v[112:115], v[170:173], v[190:193], v[112:115]
	v_mfma_f32_16x16x32_bf16 v[100:103], v[146:149], v[198:201], v[100:103]
	v_mfma_f32_16x16x32_bf16 v[96:99], v[170:173], v[198:201], v[96:99]
	v_mfma_f32_16x16x32_bf16 v[84:87], v[146:149], v[206:209], v[84:87]
	v_mfma_f32_16x16x32_bf16 v[80:83], v[170:173], v[206:209], v[80:83]
	s_setprio 0
	s_barrier
	ds_read_b128 v[174:177], v135 offset:16384
	ds_read_b128 v[210:213], v135 offset:17408
	ds_read_b128 v[214:217], v135 offset:18432
	ds_read_b128 v[218:221], v135 offset:19456
	s_barrier
	s_waitcnt lgkmcnt(0)
	s_setprio 1
	s_waitcnt lgkmcnt(0)
	v_mfma_f32_16x16x32_bf16 v[92:95], v[174:177], v[186:189], v[92:95]
	v_mfma_f32_16x16x32_bf16 v[88:91], v[214:217], v[186:189], v[88:91]
	v_mfma_f32_16x16x32_bf16 v[68:71], v[174:177], v[202:205], v[68:71]
	v_mfma_f32_16x16x32_bf16 v[64:67], v[214:217], v[202:205], v[64:67]
	v_mfma_f32_16x16x32_bf16 v[108:111], v[174:177], v[178:181], v[108:111]
	v_mfma_f32_16x16x32_bf16 v[104:107], v[214:217], v[178:181], v[104:107]
	v_mfma_f32_16x16x32_bf16 v[92:95], v[210:213], v[190:193], v[92:95]
	v_mfma_f32_16x16x32_bf16 v[88:91], v[218:221], v[190:193], v[88:91]
	v_mfma_f32_16x16x32_bf16 v[76:79], v[174:177], v[194:197], v[76:79]
	v_mfma_f32_16x16x32_bf16 v[72:75], v[214:217], v[194:197], v[72:75]
	v_mfma_f32_16x16x32_bf16 v[68:71], v[210:213], v[206:209], v[68:71]
	v_mfma_f32_16x16x32_bf16 v[64:67], v[218:221], v[206:209], v[64:67]
	v_mfma_f32_16x16x32_bf16 v[222:225], v[210:213], v[182:185], v[108:111]
	v_mfma_f32_16x16x32_bf16 v[178:181], v[218:221], v[182:185], v[104:107]
	v_mfma_f32_16x16x32_bf16 v[76:79], v[210:213], v[198:201], v[76:79]
	v_mfma_f32_16x16x32_bf16 v[72:75], v[218:221], v[198:201], v[72:75]
	s_setprio 0
	s_barrier
	ds_read_b128 v[104:107], v134 offset:16384
	ds_read_b128 v[108:111], v134 offset:17408
	ds_read_b128 v[182:185], v134 offset:18432
	ds_read_b128 v[186:189], v134 offset:19456
	ds_read_b128 v[190:193], v134 offset:20480
	ds_read_b128 v[194:197], v134 offset:21504
	ds_read_b128 v[198:201], v134 offset:22528
	ds_read_b128 v[202:205], v134 offset:23552
	s_waitcnt vmcnt(4)
	s_barrier
	s_waitcnt lgkmcnt(0)
	s_setprio 1
	s_waitcnt lgkmcnt(0)
	v_mfma_f32_16x16x32_bf16 v[36:39], v[130:133], v[190:193], v[36:39]
	v_mfma_f32_16x16x32_bf16 v[28:31], v[150:153], v[190:193], v[28:31]
	v_mfma_f32_16x16x32_bf16 v[20:23], v[130:133], v[198:201], v[20:23]
	v_mfma_f32_16x16x32_bf16 v[12:15], v[150:153], v[198:201], v[12:15]
	v_mfma_f32_16x16x32_bf16 v[60:63], v[130:133], v[104:107], v[60:63]
	v_mfma_f32_16x16x32_bf16 v[56:59], v[150:153], v[104:107], v[56:59]
	v_mfma_f32_16x16x32_bf16 v[52:55], v[130:133], v[182:185], v[52:55]
	v_mfma_f32_16x16x32_bf16 v[44:47], v[150:153], v[182:185], v[44:47]
	v_mfma_f32_16x16x32_bf16 v[36:39], v[146:149], v[194:197], v[36:39]
	v_mfma_f32_16x16x32_bf16 v[28:31], v[170:173], v[194:197], v[28:31]
	v_mfma_f32_16x16x32_bf16 v[20:23], v[146:149], v[202:205], v[20:23]
	v_mfma_f32_16x16x32_bf16 v[12:15], v[170:173], v[202:205], v[12:15]
	v_mfma_f32_16x16x32_bf16 v[206:209], v[146:149], v[108:111], v[60:63]
	v_mfma_f32_16x16x32_bf16 v[226:229], v[170:173], v[108:111], v[56:59]
	v_mfma_f32_16x16x32_bf16 v[230:233], v[146:149], v[186:189], v[52:55]
	v_mfma_f32_16x16x32_bf16 v[234:237], v[170:173], v[186:189], v[44:47]
	s_setprio 0
	s_setprio 1
	v_mfma_f32_16x16x32_bf16 v[8:11], v[214:217], v[190:193], v[8:11]
	v_mfma_f32_16x16x32_bf16 v[4:7], v[174:177], v[198:201], v[4:7]
	v_mfma_f32_16x16x32_bf16 v[0:3], v[214:217], v[198:201], v[0:3]
	v_mfma_f32_16x16x32_bf16 v[44:47], v[174:177], v[104:107], v[48:51]
	v_mfma_f32_16x16x32_bf16 v[40:43], v[214:217], v[104:107], v[40:43]
	v_mfma_f32_16x16x32_bf16 v[32:35], v[174:177], v[182:185], v[32:35]
	v_mfma_f32_16x16x32_bf16 v[24:27], v[214:217], v[182:185], v[24:27]
	v_mfma_f32_16x16x32_bf16 v[16:19], v[174:177], v[190:193], v[16:19]
	v_mfma_f32_16x16x32_bf16 v[8:11], v[218:221], v[194:197], v[8:11]
	v_mfma_f32_16x16x32_bf16 v[4:7], v[210:213], v[202:205], v[4:7]
	v_mfma_f32_16x16x32_bf16 v[0:3], v[218:221], v[202:205], v[0:3]
	v_mfma_f32_16x16x32_bf16 v[146:149], v[210:213], v[108:111], v[44:47]
	v_mfma_f32_16x16x32_bf16 v[150:153], v[218:221], v[108:111], v[40:43]
	v_mfma_f32_16x16x32_bf16 v[170:173], v[210:213], v[186:189], v[32:35]
	v_mfma_f32_16x16x32_bf16 v[182:185], v[218:221], v[186:189], v[24:27]
	v_mfma_f32_16x16x32_bf16 v[186:189], v[210:213], v[194:197], v[16:19]
	s_setprio 0
	s_barrier
	s_nop 0
	ds_read_b128 v[16:19], v145
	ds_read_b128 v[174:177], v145 offset:1024
	ds_read_b128 v[190:193], v145 offset:2048
	ds_read_b128 v[194:197], v145 offset:3072
	ds_read_b128 v[24:27], v144
	ds_read_b128 v[32:35], v144 offset:1024
	ds_read_b128 v[40:43], v144 offset:2048
	ds_read_b128 v[44:47], v144 offset:3072
	ds_read_b128 v[198:201], v144 offset:4096
	ds_read_b128 v[202:205], v144 offset:5120
	ds_read_b128 v[210:213], v144 offset:6144
	ds_read_b128 v[214:217], v144 offset:7168
	s_waitcnt vmcnt(2)
	s_barrier
	s_waitcnt lgkmcnt(0)
	s_setprio 1
	s_waitcnt lgkmcnt(0)
	v_mfma_f32_16x16x32_bf16 v[48:51], v[16:19], v[24:27], v[124:127]
	v_mfma_f32_16x16x32_bf16 v[132:135], v[174:177], v[32:35], v[48:51]
	v_mfma_f32_16x16x32_bf16 v[48:51], v[190:193], v[24:27], v[120:123]
	v_mfma_f32_16x16x32_bf16 v[128:131], v[194:197], v[32:35], v[48:51]
	v_mfma_f32_16x16x32_bf16 v[48:51], v[16:19], v[40:43], v[116:119]
	v_mfma_f32_16x16x32_bf16 v[124:127], v[174:177], v[44:47], v[48:51]
	v_mfma_f32_16x16x32_bf16 v[48:51], v[190:193], v[40:43], v[112:115]
	v_mfma_f32_16x16x32_bf16 v[120:123], v[194:197], v[44:47], v[48:51]
	v_mfma_f32_16x16x32_bf16 v[48:51], v[16:19], v[198:201], v[100:103]
	v_mfma_f32_16x16x32_bf16 v[116:119], v[174:177], v[202:205], v[48:51]
	v_mfma_f32_16x16x32_bf16 v[48:51], v[190:193], v[198:201], v[96:99]
	v_mfma_f32_16x16x32_bf16 v[112:115], v[194:197], v[202:205], v[48:51]
	v_mfma_f32_16x16x32_bf16 v[48:51], v[16:19], v[210:213], v[84:87]
	v_mfma_f32_16x16x32_bf16 v[108:111], v[174:177], v[214:217], v[48:51]
	v_mfma_f32_16x16x32_bf16 v[48:51], v[190:193], v[210:213], v[80:83]
	v_mfma_f32_16x16x32_bf16 v[104:107], v[194:197], v[214:217], v[48:51]
	s_setprio 0
	s_barrier
	ds_read_b128 v[218:221], v145 offset:16384
	ds_read_b128 v[238:241], v145 offset:17408
	ds_read_b128 v[242:245], v145 offset:18432
	ds_read_b128 v[246:249], v145 offset:19456
	s_waitcnt vmcnt(0)
	s_barrier
	s_waitcnt lgkmcnt(0)
	s_setprio 1
	s_waitcnt lgkmcnt(0)
	v_mfma_f32_16x16x32_bf16 v[48:51], v[218:221], v[24:27], v[222:225]
	v_mfma_f32_16x16x32_bf16 v[24:27], v[242:245], v[24:27], v[178:181]
	v_mfma_f32_16x16x32_bf16 v[56:59], v[246:249], v[32:35], v[24:27]
	v_mfma_f32_16x16x32_bf16 v[24:27], v[218:221], v[40:43], v[92:95]
	v_mfma_f32_16x16x32_bf16 v[52:55], v[238:241], v[44:47], v[24:27]
	v_mfma_f32_16x16x32_bf16 v[24:27], v[242:245], v[40:43], v[88:91]
	v_mfma_f32_16x16x32_bf16 v[60:63], v[238:241], v[32:35], v[48:51]
	v_mfma_f32_16x16x32_bf16 v[48:51], v[246:249], v[44:47], v[24:27]
	v_mfma_f32_16x16x32_bf16 v[24:27], v[218:221], v[198:201], v[76:79]
	v_mfma_f32_16x16x32_bf16 v[44:47], v[238:241], v[202:205], v[24:27]
	v_mfma_f32_16x16x32_bf16 v[24:27], v[242:245], v[198:201], v[72:75]
	v_mfma_f32_16x16x32_bf16 v[40:43], v[246:249], v[202:205], v[24:27]
	v_mfma_f32_16x16x32_bf16 v[24:27], v[218:221], v[210:213], v[68:71]
	v_mfma_f32_16x16x32_bf16 v[32:35], v[238:241], v[214:217], v[24:27]
	v_mfma_f32_16x16x32_bf16 v[24:27], v[242:245], v[210:213], v[64:67]
	v_mfma_f32_16x16x32_bf16 v[24:27], v[246:249], v[214:217], v[24:27]
	s_setprio 0
	s_barrier
	ds_read_b128 v[72:75], v144 offset:16384
	ds_read_b128 v[76:79], v144 offset:17408
	ds_read_b128 v[178:181], v144 offset:18432
	ds_read_b128 v[198:201], v144 offset:19456
	ds_read_b128 v[202:205], v144 offset:20480
	ds_read_b128 v[210:213], v144 offset:21504
	ds_read_b128 v[214:217], v144 offset:22528
	ds_read_b128 v[222:225], v144 offset:23552
	s_barrier
	s_waitcnt lgkmcnt(0)
	s_setprio 1
	s_waitcnt lgkmcnt(0)
	v_mfma_f32_16x16x32_bf16 v[64:67], v[16:19], v[72:75], v[206:209]
	v_mfma_f32_16x16x32_bf16 v[100:103], v[174:177], v[76:79], v[64:67]
	v_mfma_f32_16x16x32_bf16 v[64:67], v[190:193], v[72:75], v[226:229]
	v_mfma_f32_16x16x32_bf16 v[96:99], v[194:197], v[76:79], v[64:67]
	v_mfma_f32_16x16x32_bf16 v[64:67], v[16:19], v[178:181], v[230:233]
	v_mfma_f32_16x16x32_bf16 v[92:95], v[174:177], v[198:201], v[64:67]
	v_mfma_f32_16x16x32_bf16 v[64:67], v[190:193], v[178:181], v[234:237]
	v_mfma_f32_16x16x32_bf16 v[36:39], v[16:19], v[202:205], v[36:39]
	v_mfma_f32_16x16x32_bf16 v[28:31], v[190:193], v[202:205], v[28:31]
	v_mfma_f32_16x16x32_bf16 v[16:19], v[16:19], v[214:217], v[20:23]
	v_mfma_f32_16x16x32_bf16 v[12:15], v[190:193], v[214:217], v[12:15]
	v_mfma_f32_16x16x32_bf16 v[88:91], v[194:197], v[198:201], v[64:67]
	v_mfma_f32_16x16x32_bf16 v[84:87], v[174:177], v[210:213], v[36:39]
	v_mfma_f32_16x16x32_bf16 v[80:83], v[194:197], v[210:213], v[28:31]
	v_mfma_f32_16x16x32_bf16 v[68:71], v[174:177], v[222:225], v[16:19]
	v_mfma_f32_16x16x32_bf16 v[64:67], v[194:197], v[222:225], v[12:15]
	s_setprio 0
	s_setprio 1
	v_mfma_f32_16x16x32_bf16 v[12:15], v[218:221], v[72:75], v[146:149]
	v_mfma_f32_16x16x32_bf16 v[36:39], v[238:241], v[76:79], v[12:15]
	v_mfma_f32_16x16x32_bf16 v[12:15], v[242:245], v[72:75], v[150:153]
	v_mfma_f32_16x16x32_bf16 v[28:31], v[246:249], v[76:79], v[12:15]
	v_mfma_f32_16x16x32_bf16 v[12:15], v[218:221], v[178:181], v[170:173]
	v_mfma_f32_16x16x32_bf16 v[20:23], v[238:241], v[198:201], v[12:15]
	v_mfma_f32_16x16x32_bf16 v[12:15], v[242:245], v[178:181], v[182:185]
	v_mfma_f32_16x16x32_bf16 v[16:19], v[246:249], v[198:201], v[12:15]
	v_mfma_f32_16x16x32_bf16 v[12:15], v[218:221], v[202:205], v[186:189]
	v_mfma_f32_16x16x32_bf16 v[8:11], v[242:245], v[202:205], v[8:11]
	v_mfma_f32_16x16x32_bf16 v[4:7], v[218:221], v[214:217], v[4:7]
	v_mfma_f32_16x16x32_bf16 v[0:3], v[242:245], v[214:217], v[0:3]
	v_mfma_f32_16x16x32_bf16 v[12:15], v[238:241], v[210:213], v[12:15]
	v_mfma_f32_16x16x32_bf16 v[8:11], v[246:249], v[210:213], v[8:11]
	v_mfma_f32_16x16x32_bf16 v[4:7], v[238:241], v[222:225], v[4:7]
	v_mfma_f32_16x16x32_bf16 v[0:3], v[246:249], v[222:225], v[0:3]
	s_setprio 0
	s_movk_i32 s4, 0x100
	v_cmp_gt_u32_e32 vcc, s4, v139
	s_barrier
	s_and_saveexec_b64 s[4:5], vcc
	s_cbranch_execz .LBB0_149
	s_barrier
	s_branch .LBB0_149

.LBB0_225:
	ds_read_b128 v[140:143], v145
	ds_read_b128 v[182:185], v145 offset:2048
	ds_read_b128 v[178:181], v145 offset:1024
	ds_read_b128 v[186:189], v145 offset:3072
	v_add_u32_e32 v176, 0x4000, v147
	v_lshl_add_u64 v[162:163], v[132:133], 0, v[136:137]
	v_readfirstlane_b32 s1, v176
	v_add_u32_e32 v177, 0x6000, v147
	v_lshl_add_u64 v[164:165], v[162:163], 0, s[76:77]
	s_mov_b32 m0, s1
	v_readfirstlane_b32 s1, v177
	ds_read_b128 v[190:193], v144
	ds_read_b128 v[198:201], v144 offset:2048
	ds_read_b128 v[206:209], v144 offset:4096
	ds_read_b128 v[214:217], v144 offset:6144
	ds_read_b128 v[194:197], v144 offset:1024
	ds_read_b128 v[202:205], v144 offset:3072
	ds_read_b128 v[210:213], v144 offset:5120
	ds_read_b128 v[218:221], v144 offset:7168
	global_load_lds_dwordx4 v[164:165], off
	v_lshl_add_u64 v[164:165], v[162:163], 0, s[16:17]
	s_mov_b32 m0, s1
	s_nop 0
	global_load_lds_dwordx4 v[164:165], off
	s_waitcnt lgkmcnt(8)
	s_barrier
	s_waitcnt lgkmcnt(4)
	s_setprio 1
	s_waitcnt lgkmcnt(4)
	v_mfma_f32_16x16x32_bf16 v[124:127], v[140:143], v[190:193], v[124:127]
	v_mfma_f32_16x16x32_bf16 v[120:123], v[182:185], v[190:193], v[120:123]
	v_mfma_f32_16x16x32_bf16 v[116:119], v[140:143], v[198:201], v[116:119]
	v_mfma_f32_16x16x32_bf16 v[112:115], v[182:185], v[198:201], v[112:115]
	v_mfma_f32_16x16x32_bf16 v[100:103], v[140:143], v[206:209], v[100:103]
	v_mfma_f32_16x16x32_bf16 v[96:99], v[182:185], v[206:209], v[96:99]
	v_mfma_f32_16x16x32_bf16 v[84:87], v[140:143], v[214:217], v[84:87]
	v_mfma_f32_16x16x32_bf16 v[80:83], v[182:185], v[214:217], v[80:83]
	s_waitcnt lgkmcnt(0)
	v_mfma_f32_16x16x32_bf16 v[124:127], v[178:181], v[194:197], v[124:127]
	v_mfma_f32_16x16x32_bf16 v[120:123], v[186:189], v[194:197], v[120:123]
	v_mfma_f32_16x16x32_bf16 v[116:119], v[178:181], v[202:205], v[116:119]
	v_mfma_f32_16x16x32_bf16 v[112:115], v[186:189], v[202:205], v[112:115]
	v_mfma_f32_16x16x32_bf16 v[100:103], v[178:181], v[210:213], v[100:103]
	v_mfma_f32_16x16x32_bf16 v[96:99], v[186:189], v[210:213], v[96:99]
	v_mfma_f32_16x16x32_bf16 v[84:87], v[178:181], v[218:221], v[84:87]
	v_mfma_f32_16x16x32_bf16 v[80:83], v[186:189], v[218:221], v[80:83]
	s_setprio 0
	s_barrier
	v_lshl_add_u64 v[164:165], v[130:131], 0, v[136:137]
	s_mov_b64 s[6:7], 0x1080100
	v_readfirstlane_b32 s1, v148
	v_lshl_add_u64 v[238:239], v[164:165], 0, s[6:7]
	s_mov_b32 m0, s1
	s_mov_b64 s[6:7], 0x10a0100
	v_readfirstlane_b32 s1, v149
	ds_read_b128 v[222:225], v145 offset:16384
	ds_read_b128 v[230:233], v145 offset:18432
	ds_read_b128 v[226:229], v145 offset:17408
	ds_read_b128 v[234:237], v145 offset:19456
	global_load_lds_dwordx4 v[238:239], off
	v_lshl_add_u64 v[238:239], v[164:165], 0, s[6:7]
	s_mov_b32 m0, s1
	s_nop 0
	global_load_lds_dwordx4 v[238:239], off
	s_barrier
	s_waitcnt lgkmcnt(2)
	s_setprio 1
	s_waitcnt lgkmcnt(2)
	v_mfma_f32_16x16x32_bf16 v[108:111], v[222:225], v[190:193], v[108:111]
	v_mfma_f32_16x16x32_bf16 v[104:107], v[230:233], v[190:193], v[104:107]
	v_mfma_f32_16x16x32_bf16 v[92:95], v[222:225], v[198:201], v[92:95]
	v_mfma_f32_16x16x32_bf16 v[88:91], v[230:233], v[198:201], v[88:91]
	v_mfma_f32_16x16x32_bf16 v[76:79], v[222:225], v[206:209], v[76:79]
	v_mfma_f32_16x16x32_bf16 v[72:75], v[230:233], v[206:209], v[72:75]
	v_mfma_f32_16x16x32_bf16 v[68:71], v[222:225], v[214:217], v[68:71]
	v_mfma_f32_16x16x32_bf16 v[64:67], v[230:233], v[214:217], v[64:67]
	s_waitcnt lgkmcnt(0)
	v_mfma_f32_16x16x32_bf16 v[108:111], v[226:229], v[194:197], v[108:111]
	v_mfma_f32_16x16x32_bf16 v[104:107], v[234:237], v[194:197], v[104:107]
	v_mfma_f32_16x16x32_bf16 v[92:95], v[226:229], v[202:205], v[92:95]
	v_mfma_f32_16x16x32_bf16 v[88:91], v[234:237], v[202:205], v[88:91]
	v_mfma_f32_16x16x32_bf16 v[76:79], v[226:229], v[210:213], v[76:79]
	v_mfma_f32_16x16x32_bf16 v[72:75], v[234:237], v[210:213], v[72:75]
	v_mfma_f32_16x16x32_bf16 v[68:71], v[226:229], v[218:221], v[68:71]
	v_mfma_f32_16x16x32_bf16 v[64:67], v[234:237], v[218:221], v[64:67]
	s_setprio 0
	v_readfirstlane_b32 s1, v146
	v_lshl_add_u64 v[238:239], v[162:163], 0, s[88:89]
	s_mov_b32 m0, s1
	v_readfirstlane_b32 s1, v150
	s_barrier
	ds_read_b128 v[190:193], v144 offset:16384
	ds_read_b128 v[198:201], v144 offset:18432
	ds_read_b128 v[206:209], v144 offset:20480
	ds_read_b128 v[214:217], v144 offset:22528
	ds_read_b128 v[194:197], v144 offset:17408
	ds_read_b128 v[202:205], v144 offset:19456
	ds_read_b128 v[210:213], v144 offset:21504
	ds_read_b128 v[218:221], v144 offset:23552
	global_load_lds_dwordx4 v[238:239], off
	v_lshl_add_u64 v[238:239], v[162:163], 0, s[90:91]
	s_mov_b32 m0, s1
	s_nop 0
	global_load_lds_dwordx4 v[238:239], off
	s_barrier
	s_waitcnt lgkmcnt(4)
	s_setprio 1
	s_waitcnt lgkmcnt(4)
	v_mfma_f32_16x16x32_bf16 v[60:63], v[140:143], v[190:193], v[60:63]
	v_mfma_f32_16x16x32_bf16 v[56:59], v[182:185], v[190:193], v[56:59]
	v_mfma_f32_16x16x32_bf16 v[52:55], v[140:143], v[198:201], v[52:55]
	v_mfma_f32_16x16x32_bf16 v[44:47], v[182:185], v[198:201], v[44:47]
	v_mfma_f32_16x16x32_bf16 v[36:39], v[140:143], v[206:209], v[36:39]
	v_mfma_f32_16x16x32_bf16 v[28:31], v[182:185], v[206:209], v[28:31]
	v_mfma_f32_16x16x32_bf16 v[20:23], v[140:143], v[214:217], v[20:23]
	v_mfma_f32_16x16x32_bf16 v[12:15], v[182:185], v[214:217], v[12:15]
	s_waitcnt lgkmcnt(0)
	v_mfma_f32_16x16x32_bf16 v[60:63], v[178:181], v[194:197], v[60:63]
	v_mfma_f32_16x16x32_bf16 v[56:59], v[186:189], v[194:197], v[56:59]
	v_mfma_f32_16x16x32_bf16 v[52:55], v[178:181], v[202:205], v[52:55]
	v_mfma_f32_16x16x32_bf16 v[44:47], v[186:189], v[202:205], v[44:47]
	v_mfma_f32_16x16x32_bf16 v[36:39], v[178:181], v[210:213], v[36:39]
	v_mfma_f32_16x16x32_bf16 v[28:31], v[186:189], v[210:213], v[28:31]
	v_mfma_f32_16x16x32_bf16 v[20:23], v[178:181], v[218:221], v[20:23]
	v_mfma_f32_16x16x32_bf16 v[12:15], v[186:189], v[218:221], v[12:15]
	s_setprio 0
	s_barrier
	s_mov_b64 s[6:7], 0x10c0100
	v_readfirstlane_b32 s1, v151
	v_lshl_add_u64 v[140:141], v[164:165], 0, s[6:7]
	s_mov_b32 m0, s1
	s_mov_b64 s[6:7], 0x10e0100
	v_readfirstlane_b32 s1, v152
	global_load_lds_dwordx4 v[140:141], off
	v_lshl_add_u64 v[140:141], v[164:165], 0, s[6:7]
	s_mov_b32 m0, s1
	s_nop 0
	global_load_lds_dwordx4 v[140:141], off
	s_waitcnt vmcnt(6)
	s_barrier
	s_setprio 1
	v_mfma_f32_16x16x32_bf16 v[48:51], v[222:225], v[190:193], v[48:51]
	v_mfma_f32_16x16x32_bf16 v[40:43], v[230:233], v[190:193], v[40:43]
	v_mfma_f32_16x16x32_bf16 v[32:35], v[222:225], v[198:201], v[32:35]
	v_mfma_f32_16x16x32_bf16 v[24:27], v[230:233], v[198:201], v[24:27]
	v_mfma_f32_16x16x32_bf16 v[16:19], v[222:225], v[206:209], v[16:19]
	v_mfma_f32_16x16x32_bf16 v[8:11], v[230:233], v[206:209], v[8:11]
	v_mfma_f32_16x16x32_bf16 v[4:7], v[222:225], v[214:217], v[4:7]
	v_mfma_f32_16x16x32_bf16 v[0:3], v[230:233], v[214:217], v[0:3]
	v_mfma_f32_16x16x32_bf16 v[48:51], v[226:229], v[194:197], v[48:51]
	v_mfma_f32_16x16x32_bf16 v[40:43], v[234:237], v[194:197], v[40:43]
	v_mfma_f32_16x16x32_bf16 v[32:35], v[226:229], v[202:205], v[32:35]
	v_mfma_f32_16x16x32_bf16 v[24:27], v[234:237], v[202:205], v[24:27]
	v_mfma_f32_16x16x32_bf16 v[16:19], v[226:229], v[210:213], v[16:19]
	v_mfma_f32_16x16x32_bf16 v[8:11], v[234:237], v[210:213], v[8:11]
	v_mfma_f32_16x16x32_bf16 v[4:7], v[226:229], v[218:221], v[4:7]
	v_mfma_f32_16x16x32_bf16 v[0:3], v[234:237], v[218:221], v[0:3]
	s_setprio 0
	s_barrier
	ds_read_b128 v[140:143], v139
	ds_read_b128 v[182:185], v139 offset:2048
	ds_read_b128 v[178:181], v139 offset:1024
	ds_read_b128 v[186:189], v139 offset:3072
	v_readfirstlane_b32 s1, v153
	v_lshl_add_u64 v[222:223], v[162:163], 0, s[94:95]
	s_mov_b32 m0, s1
	v_readfirstlane_b32 s1, v170
	ds_read_b128 v[190:193], v135
	ds_read_b128 v[198:201], v135 offset:2048
	ds_read_b128 v[206:209], v135 offset:4096
	ds_read_b128 v[214:217], v135 offset:6144
	ds_read_b128 v[194:197], v135 offset:1024
	ds_read_b128 v[202:205], v135 offset:3072
	ds_read_b128 v[210:213], v135 offset:5120
	ds_read_b128 v[218:221], v135 offset:7168
	global_load_lds_dwordx4 v[222:223], off
	v_lshl_add_u64 v[222:223], v[162:163], 0, s[78:79]
	s_mov_b32 m0, s1
	s_nop 0
	global_load_lds_dwordx4 v[222:223], off
	s_waitcnt lgkmcnt(8)
	s_barrier
	s_waitcnt lgkmcnt(4)
	s_setprio 1
	s_waitcnt lgkmcnt(4)
	v_mfma_f32_16x16x32_bf16 v[124:127], v[140:143], v[190:193], v[124:127]
	v_mfma_f32_16x16x32_bf16 v[120:123], v[182:185], v[190:193], v[120:123]
	v_mfma_f32_16x16x32_bf16 v[116:119], v[140:143], v[198:201], v[116:119]
	v_mfma_f32_16x16x32_bf16 v[112:115], v[182:185], v[198:201], v[112:115]
	v_mfma_f32_16x16x32_bf16 v[100:103], v[140:143], v[206:209], v[100:103]
	v_mfma_f32_16x16x32_bf16 v[96:99], v[182:185], v[206:209], v[96:99]
	v_mfma_f32_16x16x32_bf16 v[84:87], v[140:143], v[214:217], v[84:87]
	v_mfma_f32_16x16x32_bf16 v[80:83], v[182:185], v[214:217], v[80:83]
	s_waitcnt lgkmcnt(0)
	v_mfma_f32_16x16x32_bf16 v[124:127], v[178:181], v[194:197], v[124:127]
	v_mfma_f32_16x16x32_bf16 v[120:123], v[186:189], v[194:197], v[120:123]
	v_mfma_f32_16x16x32_bf16 v[116:119], v[178:181], v[202:205], v[116:119]
	v_mfma_f32_16x16x32_bf16 v[112:115], v[186:189], v[202:205], v[112:115]
	v_mfma_f32_16x16x32_bf16 v[100:103], v[178:181], v[210:213], v[100:103]
	v_mfma_f32_16x16x32_bf16 v[96:99], v[186:189], v[210:213], v[96:99]
	v_mfma_f32_16x16x32_bf16 v[84:87], v[178:181], v[218:221], v[84:87]
	v_mfma_f32_16x16x32_bf16 v[80:83], v[186:189], v[218:221], v[80:83]
	s_setprio 0
	s_barrier
	s_mov_b64 s[6:7], 0x1080180
	v_readfirstlane_b32 s1, v171
	v_lshl_add_u64 v[238:239], v[164:165], 0, s[6:7]
	s_mov_b32 m0, s1
	s_mov_b64 s[6:7], 0x10a0180
	v_readfirstlane_b32 s1, v172
	ds_read_b128 v[222:225], v139 offset:16384
	ds_read_b128 v[230:233], v139 offset:18432
	ds_read_b128 v[226:229], v139 offset:17408
	ds_read_b128 v[234:237], v139 offset:19456
	global_load_lds_dwordx4 v[238:239], off
	v_lshl_add_u64 v[238:239], v[164:165], 0, s[6:7]
	s_mov_b32 m0, s1
	s_nop 0
	global_load_lds_dwordx4 v[238:239], off
	s_barrier
	s_waitcnt lgkmcnt(2)
	s_setprio 1
	s_waitcnt lgkmcnt(2)
	v_mfma_f32_16x16x32_bf16 v[108:111], v[222:225], v[190:193], v[108:111]
	v_mfma_f32_16x16x32_bf16 v[104:107], v[230:233], v[190:193], v[104:107]
	v_mfma_f32_16x16x32_bf16 v[92:95], v[222:225], v[198:201], v[92:95]
	v_mfma_f32_16x16x32_bf16 v[88:91], v[230:233], v[198:201], v[88:91]
	v_mfma_f32_16x16x32_bf16 v[76:79], v[222:225], v[206:209], v[76:79]
	v_mfma_f32_16x16x32_bf16 v[72:75], v[230:233], v[206:209], v[72:75]
	v_mfma_f32_16x16x32_bf16 v[68:71], v[222:225], v[214:217], v[68:71]
	v_mfma_f32_16x16x32_bf16 v[64:67], v[230:233], v[214:217], v[64:67]
	s_waitcnt lgkmcnt(0)
	v_mfma_f32_16x16x32_bf16 v[108:111], v[226:229], v[194:197], v[108:111]
	v_mfma_f32_16x16x32_bf16 v[104:107], v[234:237], v[194:197], v[104:107]
	v_mfma_f32_16x16x32_bf16 v[92:95], v[226:229], v[202:205], v[92:95]
	v_mfma_f32_16x16x32_bf16 v[88:91], v[234:237], v[202:205], v[88:91]
	v_mfma_f32_16x16x32_bf16 v[76:79], v[226:229], v[210:213], v[76:79]
	v_mfma_f32_16x16x32_bf16 v[72:75], v[234:237], v[210:213], v[72:75]
	v_mfma_f32_16x16x32_bf16 v[68:71], v[226:229], v[218:221], v[68:71]
	v_mfma_f32_16x16x32_bf16 v[64:67], v[234:237], v[218:221], v[64:67]
	s_setprio 0
	v_readfirstlane_b32 s1, v147
	v_lshl_add_u64 v[238:239], v[162:163], 0, s[24:25]
	s_mov_b32 m0, s1
	v_readfirstlane_b32 s1, v173
	s_barrier
	ds_read_b128 v[190:193], v135 offset:16384
	ds_read_b128 v[198:201], v135 offset:18432
	ds_read_b128 v[206:209], v135 offset:20480
	ds_read_b128 v[214:217], v135 offset:22528
	ds_read_b128 v[194:197], v135 offset:17408
	ds_read_b128 v[202:205], v135 offset:19456
	ds_read_b128 v[210:213], v135 offset:21504
	ds_read_b128 v[218:221], v135 offset:23552
	global_load_lds_dwordx4 v[238:239], off
	v_lshl_add_u64 v[162:163], v[162:163], 0, s[28:29]
	s_mov_b32 m0, s1
	s_nop 0
	global_load_lds_dwordx4 v[162:163], off
	s_barrier
	s_waitcnt lgkmcnt(4)
	s_setprio 1
	s_waitcnt lgkmcnt(4)
	v_mfma_f32_16x16x32_bf16 v[60:63], v[140:143], v[190:193], v[60:63]
	v_mfma_f32_16x16x32_bf16 v[56:59], v[182:185], v[190:193], v[56:59]
	v_mfma_f32_16x16x32_bf16 v[52:55], v[140:143], v[198:201], v[52:55]
	v_mfma_f32_16x16x32_bf16 v[44:47], v[182:185], v[198:201], v[44:47]
	v_mfma_f32_16x16x32_bf16 v[36:39], v[140:143], v[206:209], v[36:39]
	v_mfma_f32_16x16x32_bf16 v[28:31], v[182:185], v[206:209], v[28:31]
	v_mfma_f32_16x16x32_bf16 v[20:23], v[140:143], v[214:217], v[20:23]
	v_mfma_f32_16x16x32_bf16 v[12:15], v[182:185], v[214:217], v[12:15]
	s_waitcnt lgkmcnt(0)
	v_mfma_f32_16x16x32_bf16 v[60:63], v[178:181], v[194:197], v[60:63]
	v_mfma_f32_16x16x32_bf16 v[56:59], v[186:189], v[194:197], v[56:59]
	v_mfma_f32_16x16x32_bf16 v[52:55], v[178:181], v[202:205], v[52:55]
	v_mfma_f32_16x16x32_bf16 v[44:47], v[186:189], v[202:205], v[44:47]
	v_mfma_f32_16x16x32_bf16 v[36:39], v[178:181], v[210:213], v[36:39]
	v_mfma_f32_16x16x32_bf16 v[28:31], v[186:189], v[210:213], v[28:31]
	v_mfma_f32_16x16x32_bf16 v[20:23], v[178:181], v[218:221], v[20:23]
	v_mfma_f32_16x16x32_bf16 v[12:15], v[186:189], v[218:221], v[12:15]
	s_setprio 0
	s_barrier
	s_mov_b64 s[6:7], 0x10c0180
	v_readfirstlane_b32 s1, v174
	v_lshl_add_u64 v[140:141], v[164:165], 0, s[6:7]
	s_mov_b32 m0, s1
	s_mov_b64 s[6:7], 0x10e0180
	v_readfirstlane_b32 s1, v175
	global_load_lds_dwordx4 v[140:141], off
	v_lshl_add_u64 v[140:141], v[164:165], 0, s[6:7]
	s_mov_b32 m0, s1
	s_nop 0
	global_load_lds_dwordx4 v[140:141], off
	s_waitcnt vmcnt(6)
	s_barrier
	s_setprio 1
	v_mfma_f32_16x16x32_bf16 v[48:51], v[222:225], v[190:193], v[48:51]
	v_mfma_f32_16x16x32_bf16 v[40:43], v[230:233], v[190:193], v[40:43]
	v_mfma_f32_16x16x32_bf16 v[32:35], v[222:225], v[198:201], v[32:35]
	v_mfma_f32_16x16x32_bf16 v[24:27], v[230:233], v[198:201], v[24:27]
	v_mfma_f32_16x16x32_bf16 v[16:19], v[222:225], v[206:209], v[16:19]
	v_mfma_f32_16x16x32_bf16 v[8:11], v[230:233], v[206:209], v[8:11]
	v_mfma_f32_16x16x32_bf16 v[4:7], v[222:225], v[214:217], v[4:7]
	v_mfma_f32_16x16x32_bf16 v[0:3], v[230:233], v[214:217], v[0:3]
	v_mfma_f32_16x16x32_bf16 v[48:51], v[226:229], v[194:197], v[48:51]
	v_mfma_f32_16x16x32_bf16 v[40:43], v[234:237], v[194:197], v[40:43]
	v_mfma_f32_16x16x32_bf16 v[32:35], v[226:229], v[202:205], v[32:35]
	v_mfma_f32_16x16x32_bf16 v[24:27], v[234:237], v[202:205], v[24:27]
	v_mfma_f32_16x16x32_bf16 v[16:19], v[226:229], v[210:213], v[16:19]
	v_mfma_f32_16x16x32_bf16 v[8:11], v[234:237], v[210:213], v[8:11]
	v_mfma_f32_16x16x32_bf16 v[4:7], v[226:229], v[218:221], v[4:7]
	v_mfma_f32_16x16x32_bf16 v[0:3], v[234:237], v[218:221], v[0:3]
	s_setprio 0
	s_add_i32 s0, s0, 2
	v_lshl_add_u64 v[130:131], v[130:131], 0, s[86:87]
	s_cmp_gt_u32 s0, 11
	v_lshl_add_u64 v[132:133], v[132:133], 0, s[86:87]
	s_barrier
	s_cbranch_scc0 .LBB0_225
	s_mov_b64 s[0:1], 0x40780
	v_lshl_add_u64 v[140:141], v[128:129], 0, s[0:1]
	v_readfirstlane_b32 s0, v176
	s_mov_b32 m0, s0
	s_mov_b64 s[0:1], 0x60780
	v_lshl_add_u64 v[128:129], v[128:129], 0, s[0:1]
	v_readfirstlane_b32 s0, v177
	ds_read_b128 v[130:133], v145
	ds_read_b128 v[146:149], v145 offset:1024
	ds_read_b128 v[150:153], v145 offset:2048
	ds_read_b128 v[170:173], v145 offset:3072
	ds_read_b128 v[178:181], v144
	ds_read_b128 v[182:185], v144 offset:1024
	ds_read_b128 v[186:189], v144 offset:2048
	ds_read_b128 v[190:193], v144 offset:3072
	ds_read_b128 v[194:197], v144 offset:4096
	ds_read_b128 v[198:201], v144 offset:5120
	ds_read_b128 v[202:205], v144 offset:6144
	ds_read_b128 v[206:209], v144 offset:7168
	global_load_lds_dwordx4 v[140:141], off
	s_mov_b32 m0, s0
	s_nop 0
	global_load_lds_dwordx4 v[128:129], off
	s_barrier
	s_waitcnt lgkmcnt(0)
	s_setprio 1
	s_waitcnt lgkmcnt(0)
	v_mfma_f32_16x16x32_bf16 v[124:127], v[130:133], v[178:181], v[124:127]
	v_mfma_f32_16x16x32_bf16 v[116:119], v[130:133], v[186:189], v[116:119]
	v_mfma_f32_16x16x32_bf16 v[100:103], v[130:133], v[194:197], v[100:103]
	v_mfma_f32_16x16x32_bf16 v[84:87], v[130:133], v[202:205], v[84:87]
	v_mfma_f32_16x16x32_bf16 v[80:83], v[150:153], v[202:205], v[80:83]
	v_mfma_f32_16x16x32_bf16 v[124:127], v[146:149], v[182:185], v[124:127]
	v_mfma_f32_16x16x32_bf16 v[120:123], v[150:153], v[178:181], v[120:123]
	v_mfma_f32_16x16x32_bf16 v[116:119], v[146:149], v[190:193], v[116:119]
	v_mfma_f32_16x16x32_bf16 v[112:115], v[150:153], v[186:189], v[112:115]
	v_mfma_f32_16x16x32_bf16 v[100:103], v[146:149], v[198:201], v[100:103]
	v_mfma_f32_16x16x32_bf16 v[96:99], v[150:153], v[194:197], v[96:99]
	v_mfma_f32_16x16x32_bf16 v[84:87], v[146:149], v[206:209], v[84:87]
	v_mfma_f32_16x16x32_bf16 v[80:83], v[170:173], v[206:209], v[80:83]
	v_mfma_f32_16x16x32_bf16 v[174:177], v[170:173], v[182:185], v[120:123]
	v_mfma_f32_16x16x32_bf16 v[210:213], v[170:173], v[190:193], v[112:115]
	v_mfma_f32_16x16x32_bf16 v[214:217], v[170:173], v[198:201], v[96:99]
	s_setprio 0
	s_barrier
	s_nop 0
	ds_read_b128 v[96:99], v145 offset:16384
	ds_read_b128 v[112:115], v145 offset:17408
	ds_read_b128 v[120:123], v145 offset:18432
	ds_read_b128 v[218:221], v145 offset:19456
	s_barrier
	s_waitcnt lgkmcnt(0)
	s_setprio 1
	s_waitcnt lgkmcnt(0)
	v_mfma_f32_16x16x32_bf16 v[108:111], v[96:99], v[178:181], v[108:111]
	v_mfma_f32_16x16x32_bf16 v[104:107], v[120:123], v[178:181], v[104:107]
	v_mfma_f32_16x16x32_bf16 v[76:79], v[96:99], v[194:197], v[76:79]
	v_mfma_f32_16x16x32_bf16 v[72:75], v[120:123], v[194:197], v[72:75]
	v_mfma_f32_16x16x32_bf16 v[68:71], v[96:99], v[202:205], v[68:71]
	v_mfma_f32_16x16x32_bf16 v[64:67], v[120:123], v[202:205], v[64:67]
	v_mfma_f32_16x16x32_bf16 v[108:111], v[112:115], v[182:185], v[108:111]
	v_mfma_f32_16x16x32_bf16 v[104:107], v[218:221], v[182:185], v[104:107]
	v_mfma_f32_16x16x32_bf16 v[92:95], v[96:99], v[186:189], v[92:95]
	v_mfma_f32_16x16x32_bf16 v[88:91], v[120:123], v[186:189], v[88:91]
	v_mfma_f32_16x16x32_bf16 v[76:79], v[112:115], v[198:201], v[76:79]
	v_mfma_f32_16x16x32_bf16 v[72:75], v[218:221], v[198:201], v[72:75]
	v_mfma_f32_16x16x32_bf16 v[68:71], v[112:115], v[206:209], v[68:71]
	v_mfma_f32_16x16x32_bf16 v[64:67], v[218:221], v[206:209], v[64:67]
	v_mfma_f32_16x16x32_bf16 v[178:181], v[112:115], v[190:193], v[92:95]
	v_mfma_f32_16x16x32_bf16 v[182:185], v[218:221], v[190:193], v[88:91]
	s_setprio 0
	s_barrier
	s_nop 0
	ds_read_b128 v[88:91], v144 offset:16384
	ds_read_b128 v[92:95], v144 offset:17408
	ds_read_b128 v[186:189], v144 offset:18432
	ds_read_b128 v[190:193], v144 offset:19456
	ds_read_b128 v[194:197], v144 offset:20480
	ds_read_b128 v[198:201], v144 offset:21504
	ds_read_b128 v[202:205], v144 offset:22528
	ds_read_b128 v[206:209], v144 offset:23552
	s_waitcnt vmcnt(4)
	s_barrier
	s_waitcnt lgkmcnt(0)
	s_setprio 1
	s_waitcnt lgkmcnt(0)
	v_mfma_f32_16x16x32_bf16 v[36:39], v[130:133], v[194:197], v[36:39]
	v_mfma_f32_16x16x32_bf16 v[20:23], v[130:133], v[202:205], v[20:23]
	v_mfma_f32_16x16x32_bf16 v[12:15], v[150:153], v[202:205], v[12:15]
	v_mfma_f32_16x16x32_bf16 v[60:63], v[130:133], v[88:91], v[60:63]
	v_mfma_f32_16x16x32_bf16 v[56:59], v[150:153], v[88:91], v[56:59]
	v_mfma_f32_16x16x32_bf16 v[52:55], v[130:133], v[186:189], v[52:55]
	v_mfma_f32_16x16x32_bf16 v[44:47], v[150:153], v[186:189], v[44:47]
	v_mfma_f32_16x16x32_bf16 v[36:39], v[146:149], v[198:201], v[36:39]
	v_mfma_f32_16x16x32_bf16 v[28:31], v[150:153], v[194:197], v[28:31]
	v_mfma_f32_16x16x32_bf16 v[20:23], v[146:149], v[206:209], v[20:23]
	v_mfma_f32_16x16x32_bf16 v[12:15], v[170:173], v[206:209], v[12:15]
	v_mfma_f32_16x16x32_bf16 v[222:225], v[146:149], v[92:95], v[60:63]
	v_mfma_f32_16x16x32_bf16 v[226:229], v[170:173], v[92:95], v[56:59]
	v_mfma_f32_16x16x32_bf16 v[230:233], v[146:149], v[190:193], v[52:55]
	v_mfma_f32_16x16x32_bf16 v[234:237], v[170:173], v[190:193], v[44:47]
	v_mfma_f32_16x16x32_bf16 v[238:241], v[170:173], v[198:201], v[28:31]
	s_setprio 0
	s_setprio 1
	v_mfma_f32_16x16x32_bf16 v[28:31], v[96:99], v[88:91], v[48:51]
	v_mfma_f32_16x16x32_bf16 v[128:131], v[112:115], v[92:95], v[28:31]
	v_mfma_f32_16x16x32_bf16 v[28:31], v[120:123], v[88:91], v[40:43]
	v_mfma_f32_16x16x32_bf16 v[4:7], v[96:99], v[202:205], v[4:7]
	v_mfma_f32_16x16x32_bf16 v[144:147], v[218:221], v[92:95], v[28:31]
	v_mfma_f32_16x16x32_bf16 v[28:31], v[96:99], v[186:189], v[32:35]
	v_mfma_f32_16x16x32_bf16 v[24:27], v[120:123], v[186:189], v[24:27]
	v_mfma_f32_16x16x32_bf16 v[16:19], v[96:99], v[194:197], v[16:19]
	v_mfma_f32_16x16x32_bf16 v[8:11], v[120:123], v[194:197], v[8:11]
	v_mfma_f32_16x16x32_bf16 v[4:7], v[112:115], v[206:209], v[4:7]
	v_mfma_f32_16x16x32_bf16 v[0:3], v[120:123], v[202:205], v[0:3]
	v_mfma_f32_16x16x32_bf16 v[148:151], v[112:115], v[190:193], v[28:31]
	v_mfma_f32_16x16x32_bf16 v[170:173], v[218:221], v[190:193], v[24:27]
	v_mfma_f32_16x16x32_bf16 v[186:189], v[112:115], v[198:201], v[16:19]
	v_mfma_f32_16x16x32_bf16 v[190:193], v[218:221], v[198:201], v[8:11]
	v_mfma_f32_16x16x32_bf16 v[194:197], v[218:221], v[206:209], v[0:3]
	s_setprio 0
	s_barrier
	s_nop 0
	ds_read_b128 v[0:3], v139
	ds_read_b128 v[8:11], v139 offset:1024
	ds_read_b128 v[16:19], v139 offset:2048
	ds_read_b128 v[32:35], v139 offset:3072
	ds_read_b128 v[24:27], v135
	ds_read_b128 v[28:31], v135 offset:1024
	ds_read_b128 v[40:43], v135 offset:2048
	ds_read_b128 v[44:47], v135 offset:3072
	ds_read_b128 v[198:201], v135 offset:4096
	ds_read_b128 v[202:205], v135 offset:5120
	ds_read_b128 v[206:209], v135 offset:6144
	ds_read_b128 v[218:221], v135 offset:7168
	s_waitcnt vmcnt(2)
	s_barrier
	s_waitcnt lgkmcnt(0)
	s_setprio 1
	s_waitcnt lgkmcnt(0)
	v_mfma_f32_16x16x32_bf16 v[48:51], v[0:3], v[24:27], v[124:127]
	v_mfma_f32_16x16x32_bf16 v[120:123], v[8:11], v[28:31], v[48:51]
	v_mfma_f32_16x16x32_bf16 v[48:51], v[16:19], v[24:27], v[174:177]
	v_mfma_f32_16x16x32_bf16 v[124:127], v[32:35], v[28:31], v[48:51]
	v_mfma_f32_16x16x32_bf16 v[48:51], v[0:3], v[40:43], v[116:119]
	v_mfma_f32_16x16x32_bf16 v[112:115], v[8:11], v[44:47], v[48:51]
	v_mfma_f32_16x16x32_bf16 v[48:51], v[16:19], v[40:43], v[210:213]
	v_mfma_f32_16x16x32_bf16 v[116:119], v[32:35], v[44:47], v[48:51]
	v_mfma_f32_16x16x32_bf16 v[48:51], v[0:3], v[198:201], v[100:103]
	v_mfma_f32_16x16x32_bf16 v[96:99], v[8:11], v[202:205], v[48:51]
	v_mfma_f32_16x16x32_bf16 v[48:51], v[16:19], v[198:201], v[214:217]
	v_mfma_f32_16x16x32_bf16 v[100:103], v[32:35], v[202:205], v[48:51]
	v_mfma_f32_16x16x32_bf16 v[48:51], v[0:3], v[206:209], v[84:87]
	v_mfma_f32_16x16x32_bf16 v[88:91], v[8:11], v[218:221], v[48:51]
	v_mfma_f32_16x16x32_bf16 v[48:51], v[16:19], v[206:209], v[80:83]
	v_mfma_f32_16x16x32_bf16 v[92:95], v[32:35], v[218:221], v[48:51]
	s_setprio 0
	s_barrier
	ds_read_b128 v[174:177], v139 offset:16384
	ds_read_b128 v[210:213], v139 offset:17408
	ds_read_b128 v[214:217], v139 offset:18432
	ds_read_b128 v[242:245], v139 offset:19456
	s_waitcnt vmcnt(0)
	s_barrier
	s_waitcnt lgkmcnt(0)
	s_setprio 1
	s_waitcnt lgkmcnt(0)
	v_mfma_f32_16x16x32_bf16 v[48:51], v[174:177], v[24:27], v[108:111]
	v_mfma_f32_16x16x32_bf16 v[24:27], v[214:217], v[24:27], v[104:107]
	v_mfma_f32_16x16x32_bf16 v[60:63], v[242:245], v[28:31], v[24:27]
	v_mfma_f32_16x16x32_bf16 v[24:27], v[174:177], v[40:43], v[178:181]
	v_mfma_f32_16x16x32_bf16 v[56:59], v[210:213], v[28:31], v[48:51]
	v_mfma_f32_16x16x32_bf16 v[48:51], v[210:213], v[44:47], v[24:27]
	v_mfma_f32_16x16x32_bf16 v[24:27], v[214:217], v[40:43], v[182:185]
	v_mfma_f32_16x16x32_bf16 v[52:55], v[242:245], v[44:47], v[24:27]
	v_mfma_f32_16x16x32_bf16 v[24:27], v[174:177], v[198:201], v[76:79]
	v_mfma_f32_16x16x32_bf16 v[40:43], v[210:213], v[202:205], v[24:27]
	v_mfma_f32_16x16x32_bf16 v[24:27], v[214:217], v[198:201], v[72:75]
	v_mfma_f32_16x16x32_bf16 v[44:47], v[242:245], v[202:205], v[24:27]
	v_mfma_f32_16x16x32_bf16 v[24:27], v[174:177], v[206:209], v[68:71]
	v_mfma_f32_16x16x32_bf16 v[28:31], v[214:217], v[206:209], v[64:67]
	v_mfma_f32_16x16x32_bf16 v[24:27], v[210:213], v[218:221], v[24:27]
	v_mfma_f32_16x16x32_bf16 v[28:31], v[242:245], v[218:221], v[28:31]
	s_setprio 0
	s_barrier
	ds_read_b128 v[178:181], v135 offset:16384
	ds_read_b128 v[182:185], v135 offset:17408
	ds_read_b128 v[198:201], v135 offset:18432
	ds_read_b128 v[202:205], v135 offset:19456
	ds_read_b128 v[206:209], v135 offset:20480
	ds_read_b128 v[218:221], v135 offset:21504
	ds_read_b128 v[246:249], v135 offset:22528
	ds_read_b128 v[140:143], v135 offset:23552
	s_barrier
	s_waitcnt lgkmcnt(0)
	s_setprio 1
	s_waitcnt lgkmcnt(0)
	v_mfma_f32_16x16x32_bf16 v[64:67], v[0:3], v[178:181], v[222:225]
	v_mfma_f32_16x16x32_bf16 v[104:107], v[8:11], v[182:185], v[64:67]
	v_mfma_f32_16x16x32_bf16 v[64:67], v[16:19], v[178:181], v[226:229]
	v_mfma_f32_16x16x32_bf16 v[108:111], v[32:35], v[182:185], v[64:67]
	v_mfma_f32_16x16x32_bf16 v[64:67], v[0:3], v[198:201], v[230:233]
	v_mfma_f32_16x16x32_bf16 v[80:83], v[8:11], v[202:205], v[64:67]
	v_mfma_f32_16x16x32_bf16 v[64:67], v[16:19], v[198:201], v[234:237]
	v_mfma_f32_16x16x32_bf16 v[36:39], v[0:3], v[206:209], v[36:39]
	v_mfma_f32_16x16x32_bf16 v[0:3], v[0:3], v[246:249], v[20:23]
	v_mfma_f32_16x16x32_bf16 v[84:87], v[32:35], v[202:205], v[64:67]
	v_mfma_f32_16x16x32_bf16 v[72:75], v[8:11], v[218:221], v[36:39]
	v_mfma_f32_16x16x32_bf16 v[36:39], v[16:19], v[206:209], v[238:241]
	v_mfma_f32_16x16x32_bf16 v[64:67], v[8:11], v[140:143], v[0:3]
	v_mfma_f32_16x16x32_bf16 v[0:3], v[16:19], v[246:249], v[12:15]
	v_mfma_f32_16x16x32_bf16 v[76:79], v[32:35], v[218:221], v[36:39]
	v_mfma_f32_16x16x32_bf16 v[68:71], v[32:35], v[140:143], v[0:3]
	s_setprio 0
	s_setprio 1
	v_mfma_f32_16x16x32_bf16 v[0:3], v[174:177], v[178:181], v[128:131]
	v_mfma_f32_16x16x32_bf16 v[32:35], v[210:213], v[182:185], v[0:3]
	v_mfma_f32_16x16x32_bf16 v[0:3], v[214:217], v[178:181], v[144:147]
	v_mfma_f32_16x16x32_bf16 v[36:39], v[242:245], v[182:185], v[0:3]
	v_mfma_f32_16x16x32_bf16 v[0:3], v[174:177], v[198:201], v[148:151]
	v_mfma_f32_16x16x32_bf16 v[16:19], v[210:213], v[202:205], v[0:3]
	v_mfma_f32_16x16x32_bf16 v[0:3], v[214:217], v[198:201], v[170:173]
	v_mfma_f32_16x16x32_bf16 v[20:23], v[242:245], v[202:205], v[0:3]
	v_mfma_f32_16x16x32_bf16 v[0:3], v[174:177], v[206:209], v[186:189]
	v_mfma_f32_16x16x32_bf16 v[8:11], v[210:213], v[218:221], v[0:3]
	v_mfma_f32_16x16x32_bf16 v[0:3], v[214:217], v[206:209], v[190:193]
	v_mfma_f32_16x16x32_bf16 v[12:15], v[242:245], v[218:221], v[0:3]
	v_mfma_f32_16x16x32_bf16 v[0:3], v[174:177], v[246:249], v[4:7]
	v_mfma_f32_16x16x32_bf16 v[4:7], v[214:217], v[246:249], v[194:197]
	v_mfma_f32_16x16x32_bf16 v[0:3], v[210:213], v[140:143], v[0:3]
	v_mfma_f32_16x16x32_bf16 v[4:7], v[242:245], v[140:143], v[4:7]
	s_setprio 0
	s_movk_i32 s0, 0x100
	v_cmp_gt_u32_e32 vcc, s0, v134
	s_barrier
	s_and_saveexec_b64 s[0:1], vcc
	s_cbranch_execz .LBB0_228
	s_barrier

.LBB0_552:
	ds_read_b128 v[140:143], v145
	ds_read_b128 v[178:181], v145 offset:2048
	ds_read_b128 v[162:165], v145 offset:1024
	ds_read_b128 v[182:185], v145 offset:3072
	v_lshl_add_u64 v[234:235], v[132:133], 0, v[136:137]
	s_mov_b64 s[4:5], 0x1b540080
	v_add_u32_e32 v176, 0x4000, v147
	v_lshl_add_u64 v[218:219], v[234:235], 0, s[4:5]
	v_readfirstlane_b32 s4, v176
	s_mov_b32 m0, s4
	s_mov_b64 s[4:5], 0x1b560080
	v_add_u32_e32 v177, 0x6000, v147
	ds_read_b128 v[186:189], v144
	ds_read_b128 v[194:197], v144 offset:2048
	ds_read_b128 v[202:205], v144 offset:4096
	ds_read_b128 v[210:213], v144 offset:6144
	ds_read_b128 v[190:193], v144 offset:1024
	ds_read_b128 v[198:201], v144 offset:3072
	ds_read_b128 v[206:209], v144 offset:5120
	ds_read_b128 v[214:217], v144 offset:7168
	global_load_lds_dwordx4 v[218:219], off
	v_lshl_add_u64 v[218:219], v[234:235], 0, s[4:5]
	v_readfirstlane_b32 s4, v177
	s_mov_b32 m0, s4
	s_nop 0
	global_load_lds_dwordx4 v[218:219], off
	s_waitcnt lgkmcnt(8)
	s_barrier
	s_waitcnt lgkmcnt(4)
	s_setprio 1
	s_waitcnt lgkmcnt(4)
	v_mfma_f32_16x16x32_bf16 v[124:127], v[140:143], v[186:189], v[124:127]
	v_mfma_f32_16x16x32_bf16 v[120:123], v[178:181], v[186:189], v[120:123]
	v_mfma_f32_16x16x32_bf16 v[116:119], v[140:143], v[194:197], v[116:119]
	v_mfma_f32_16x16x32_bf16 v[112:115], v[178:181], v[194:197], v[112:115]
	v_mfma_f32_16x16x32_bf16 v[100:103], v[140:143], v[202:205], v[100:103]
	v_mfma_f32_16x16x32_bf16 v[96:99], v[178:181], v[202:205], v[96:99]
	v_mfma_f32_16x16x32_bf16 v[84:87], v[140:143], v[210:213], v[84:87]
	v_mfma_f32_16x16x32_bf16 v[80:83], v[178:181], v[210:213], v[80:83]
	s_waitcnt lgkmcnt(0)
	v_mfma_f32_16x16x32_bf16 v[124:127], v[162:165], v[190:193], v[124:127]
	v_mfma_f32_16x16x32_bf16 v[120:123], v[182:185], v[190:193], v[120:123]
	v_mfma_f32_16x16x32_bf16 v[116:119], v[162:165], v[198:201], v[116:119]
	v_mfma_f32_16x16x32_bf16 v[112:115], v[182:185], v[198:201], v[112:115]
	v_mfma_f32_16x16x32_bf16 v[100:103], v[162:165], v[206:209], v[100:103]
	v_mfma_f32_16x16x32_bf16 v[96:99], v[182:185], v[206:209], v[96:99]
	v_mfma_f32_16x16x32_bf16 v[84:87], v[162:165], v[214:217], v[84:87]
	v_mfma_f32_16x16x32_bf16 v[80:83], v[182:185], v[214:217], v[80:83]
	s_setprio 0
	s_barrier
	v_lshl_add_u64 v[236:237], v[130:131], 0, v[136:137]
	s_mov_b64 s[4:5], 0x2200100
	v_lshl_add_u64 v[238:239], v[236:237], 0, s[4:5]
	v_readfirstlane_b32 s4, v148
	s_mov_b32 m0, s4
	s_mov_b64 s[4:5], 0x2220100
	ds_read_b128 v[218:221], v145 offset:16384
	ds_read_b128 v[226:229], v145 offset:18432
	ds_read_b128 v[222:225], v145 offset:17408
	ds_read_b128 v[230:233], v145 offset:19456
	global_load_lds_dwordx4 v[238:239], off
	v_lshl_add_u64 v[238:239], v[236:237], 0, s[4:5]
	v_readfirstlane_b32 s4, v149
	s_mov_b32 m0, s4
	s_nop 0
	global_load_lds_dwordx4 v[238:239], off
	s_barrier
	s_waitcnt lgkmcnt(2)
	s_setprio 1
	s_waitcnt lgkmcnt(2)
	v_mfma_f32_16x16x32_bf16 v[108:111], v[218:221], v[186:189], v[108:111]
	v_mfma_f32_16x16x32_bf16 v[104:107], v[226:229], v[186:189], v[104:107]
	v_mfma_f32_16x16x32_bf16 v[92:95], v[218:221], v[194:197], v[92:95]
	v_mfma_f32_16x16x32_bf16 v[88:91], v[226:229], v[194:197], v[88:91]
	v_mfma_f32_16x16x32_bf16 v[76:79], v[218:221], v[202:205], v[76:79]
	v_mfma_f32_16x16x32_bf16 v[72:75], v[226:229], v[202:205], v[72:75]
	v_mfma_f32_16x16x32_bf16 v[68:71], v[218:221], v[210:213], v[68:71]
	v_mfma_f32_16x16x32_bf16 v[64:67], v[226:229], v[210:213], v[64:67]
	s_waitcnt lgkmcnt(0)
	v_mfma_f32_16x16x32_bf16 v[108:111], v[222:225], v[190:193], v[108:111]
	v_mfma_f32_16x16x32_bf16 v[104:107], v[230:233], v[190:193], v[104:107]
	v_mfma_f32_16x16x32_bf16 v[92:95], v[222:225], v[198:201], v[92:95]
	v_mfma_f32_16x16x32_bf16 v[88:91], v[230:233], v[198:201], v[88:91]
	v_mfma_f32_16x16x32_bf16 v[76:79], v[222:225], v[206:209], v[76:79]
	v_mfma_f32_16x16x32_bf16 v[72:75], v[230:233], v[206:209], v[72:75]
	v_mfma_f32_16x16x32_bf16 v[68:71], v[222:225], v[214:217], v[68:71]
	v_mfma_f32_16x16x32_bf16 v[64:67], v[230:233], v[214:217], v[64:67]
	s_setprio 0
	s_mov_b64 s[4:5], 0x1b500100
	v_lshl_add_u64 v[238:239], v[234:235], 0, s[4:5]
	v_readfirstlane_b32 s4, v146
	s_mov_b32 m0, s4
	s_mov_b64 s[4:5], 0x1b520100
	s_barrier
	ds_read_b128 v[186:189], v144 offset:16384
	ds_read_b128 v[194:197], v144 offset:18432
	ds_read_b128 v[202:205], v144 offset:20480
	ds_read_b128 v[210:213], v144 offset:22528
	ds_read_b128 v[190:193], v144 offset:17408
	ds_read_b128 v[198:201], v144 offset:19456
	ds_read_b128 v[206:209], v144 offset:21504
	ds_read_b128 v[214:217], v144 offset:23552
	global_load_lds_dwordx4 v[238:239], off
	v_lshl_add_u64 v[238:239], v[234:235], 0, s[4:5]
	v_readfirstlane_b32 s4, v150
	s_mov_b32 m0, s4
	s_nop 0
	global_load_lds_dwordx4 v[238:239], off
	s_barrier
	s_waitcnt lgkmcnt(4)
	s_setprio 1
	s_waitcnt lgkmcnt(4)
	v_mfma_f32_16x16x32_bf16 v[60:63], v[140:143], v[186:189], v[60:63]
	v_mfma_f32_16x16x32_bf16 v[56:59], v[178:181], v[186:189], v[56:59]
	v_mfma_f32_16x16x32_bf16 v[52:55], v[140:143], v[194:197], v[52:55]
	v_mfma_f32_16x16x32_bf16 v[44:47], v[178:181], v[194:197], v[44:47]
	v_mfma_f32_16x16x32_bf16 v[36:39], v[140:143], v[202:205], v[36:39]
	v_mfma_f32_16x16x32_bf16 v[28:31], v[178:181], v[202:205], v[28:31]
	v_mfma_f32_16x16x32_bf16 v[20:23], v[140:143], v[210:213], v[20:23]
	v_mfma_f32_16x16x32_bf16 v[12:15], v[178:181], v[210:213], v[12:15]
	s_waitcnt lgkmcnt(0)
	v_mfma_f32_16x16x32_bf16 v[60:63], v[162:165], v[190:193], v[60:63]
	v_mfma_f32_16x16x32_bf16 v[56:59], v[182:185], v[190:193], v[56:59]
	v_mfma_f32_16x16x32_bf16 v[52:55], v[162:165], v[198:201], v[52:55]
	v_mfma_f32_16x16x32_bf16 v[44:47], v[182:185], v[198:201], v[44:47]
	v_mfma_f32_16x16x32_bf16 v[36:39], v[162:165], v[206:209], v[36:39]
	v_mfma_f32_16x16x32_bf16 v[28:31], v[182:185], v[206:209], v[28:31]
	v_mfma_f32_16x16x32_bf16 v[20:23], v[162:165], v[214:217], v[20:23]
	v_mfma_f32_16x16x32_bf16 v[12:15], v[182:185], v[214:217], v[12:15]
	s_setprio 0
	s_barrier
	s_mov_b64 s[4:5], 0x2240100
	v_lshl_add_u64 v[140:141], v[236:237], 0, s[4:5]
	v_readfirstlane_b32 s4, v151
	s_mov_b32 m0, s4
	s_mov_b64 s[4:5], 0x2260100
	global_load_lds_dwordx4 v[140:141], off
	v_lshl_add_u64 v[140:141], v[236:237], 0, s[4:5]
	v_readfirstlane_b32 s4, v152
	s_mov_b32 m0, s4
	s_nop 0
	global_load_lds_dwordx4 v[140:141], off
	s_waitcnt vmcnt(6)
	s_barrier
	s_setprio 1
	v_mfma_f32_16x16x32_bf16 v[48:51], v[218:221], v[186:189], v[48:51]
	v_mfma_f32_16x16x32_bf16 v[40:43], v[226:229], v[186:189], v[40:43]
	v_mfma_f32_16x16x32_bf16 v[32:35], v[218:221], v[194:197], v[32:35]
	v_mfma_f32_16x16x32_bf16 v[24:27], v[226:229], v[194:197], v[24:27]
	v_mfma_f32_16x16x32_bf16 v[16:19], v[218:221], v[202:205], v[16:19]
	v_mfma_f32_16x16x32_bf16 v[8:11], v[226:229], v[202:205], v[8:11]
	v_mfma_f32_16x16x32_bf16 v[4:7], v[218:221], v[210:213], v[4:7]
	v_mfma_f32_16x16x32_bf16 v[0:3], v[226:229], v[210:213], v[0:3]
	v_mfma_f32_16x16x32_bf16 v[48:51], v[222:225], v[190:193], v[48:51]
	v_mfma_f32_16x16x32_bf16 v[40:43], v[230:233], v[190:193], v[40:43]
	v_mfma_f32_16x16x32_bf16 v[32:35], v[222:225], v[198:201], v[32:35]
	v_mfma_f32_16x16x32_bf16 v[24:27], v[230:233], v[198:201], v[24:27]
	v_mfma_f32_16x16x32_bf16 v[16:19], v[222:225], v[206:209], v[16:19]
	v_mfma_f32_16x16x32_bf16 v[8:11], v[230:233], v[206:209], v[8:11]
	v_mfma_f32_16x16x32_bf16 v[4:7], v[222:225], v[214:217], v[4:7]
	v_mfma_f32_16x16x32_bf16 v[0:3], v[230:233], v[214:217], v[0:3]
	s_setprio 0
	s_barrier
	ds_read_b128 v[140:143], v139
	ds_read_b128 v[178:181], v139 offset:2048
	ds_read_b128 v[162:165], v139 offset:1024
	ds_read_b128 v[182:185], v139 offset:3072
	s_mov_b64 s[4:5], 0x1b540100
	v_lshl_add_u64 v[218:219], v[234:235], 0, s[4:5]
	v_readfirstlane_b32 s4, v153
	s_mov_b32 m0, s4
	s_mov_b64 s[4:5], 0x1b560100
	ds_read_b128 v[186:189], v135
	ds_read_b128 v[194:197], v135 offset:2048
	ds_read_b128 v[202:205], v135 offset:4096
	ds_read_b128 v[210:213], v135 offset:6144
	ds_read_b128 v[190:193], v135 offset:1024
	ds_read_b128 v[198:201], v135 offset:3072
	ds_read_b128 v[206:209], v135 offset:5120
	ds_read_b128 v[214:217], v135 offset:7168
	global_load_lds_dwordx4 v[218:219], off
	v_lshl_add_u64 v[218:219], v[234:235], 0, s[4:5]
	v_readfirstlane_b32 s4, v170
	s_mov_b32 m0, s4
	s_nop 0
	global_load_lds_dwordx4 v[218:219], off
	s_waitcnt lgkmcnt(8)
	s_barrier
	s_waitcnt lgkmcnt(4)
	s_setprio 1
	s_waitcnt lgkmcnt(4)
	v_mfma_f32_16x16x32_bf16 v[124:127], v[140:143], v[186:189], v[124:127]
	v_mfma_f32_16x16x32_bf16 v[120:123], v[178:181], v[186:189], v[120:123]
	v_mfma_f32_16x16x32_bf16 v[116:119], v[140:143], v[194:197], v[116:119]
	v_mfma_f32_16x16x32_bf16 v[112:115], v[178:181], v[194:197], v[112:115]
	v_mfma_f32_16x16x32_bf16 v[100:103], v[140:143], v[202:205], v[100:103]
	v_mfma_f32_16x16x32_bf16 v[96:99], v[178:181], v[202:205], v[96:99]
	v_mfma_f32_16x16x32_bf16 v[84:87], v[140:143], v[210:213], v[84:87]
	v_mfma_f32_16x16x32_bf16 v[80:83], v[178:181], v[210:213], v[80:83]
	s_waitcnt lgkmcnt(0)
	v_mfma_f32_16x16x32_bf16 v[124:127], v[162:165], v[190:193], v[124:127]
	v_mfma_f32_16x16x32_bf16 v[120:123], v[182:185], v[190:193], v[120:123]
	v_mfma_f32_16x16x32_bf16 v[116:119], v[162:165], v[198:201], v[116:119]
	v_mfma_f32_16x16x32_bf16 v[112:115], v[182:185], v[198:201], v[112:115]
	v_mfma_f32_16x16x32_bf16 v[100:103], v[162:165], v[206:209], v[100:103]
	v_mfma_f32_16x16x32_bf16 v[96:99], v[182:185], v[206:209], v[96:99]
	v_mfma_f32_16x16x32_bf16 v[84:87], v[162:165], v[214:217], v[84:87]
	v_mfma_f32_16x16x32_bf16 v[80:83], v[182:185], v[214:217], v[80:83]
	s_setprio 0
	s_barrier
	s_mov_b64 s[4:5], 0x2200180
	v_lshl_add_u64 v[238:239], v[236:237], 0, s[4:5]
	v_readfirstlane_b32 s4, v171
	s_mov_b32 m0, s4
	s_mov_b64 s[4:5], 0x2220180
	ds_read_b128 v[218:221], v139 offset:16384
	ds_read_b128 v[226:229], v139 offset:18432
	ds_read_b128 v[222:225], v139 offset:17408
	ds_read_b128 v[230:233], v139 offset:19456
	global_load_lds_dwordx4 v[238:239], off
	v_lshl_add_u64 v[238:239], v[236:237], 0, s[4:5]
	v_readfirstlane_b32 s4, v172
	s_mov_b32 m0, s4
	s_nop 0
	global_load_lds_dwordx4 v[238:239], off
	s_barrier
	s_waitcnt lgkmcnt(2)
	s_setprio 1
	s_waitcnt lgkmcnt(2)
	v_mfma_f32_16x16x32_bf16 v[108:111], v[218:221], v[186:189], v[108:111]
	v_mfma_f32_16x16x32_bf16 v[104:107], v[226:229], v[186:189], v[104:107]
	v_mfma_f32_16x16x32_bf16 v[92:95], v[218:221], v[194:197], v[92:95]
	v_mfma_f32_16x16x32_bf16 v[88:91], v[226:229], v[194:197], v[88:91]
	v_mfma_f32_16x16x32_bf16 v[76:79], v[218:221], v[202:205], v[76:79]
	v_mfma_f32_16x16x32_bf16 v[72:75], v[226:229], v[202:205], v[72:75]
	v_mfma_f32_16x16x32_bf16 v[68:71], v[218:221], v[210:213], v[68:71]
	v_mfma_f32_16x16x32_bf16 v[64:67], v[226:229], v[210:213], v[64:67]
	s_waitcnt lgkmcnt(0)
	v_mfma_f32_16x16x32_bf16 v[108:111], v[222:225], v[190:193], v[108:111]
	v_mfma_f32_16x16x32_bf16 v[104:107], v[230:233], v[190:193], v[104:107]
	v_mfma_f32_16x16x32_bf16 v[92:95], v[222:225], v[198:201], v[92:95]
	v_mfma_f32_16x16x32_bf16 v[88:91], v[230:233], v[198:201], v[88:91]
	v_mfma_f32_16x16x32_bf16 v[76:79], v[222:225], v[206:209], v[76:79]
	v_mfma_f32_16x16x32_bf16 v[72:75], v[230:233], v[206:209], v[72:75]
	v_mfma_f32_16x16x32_bf16 v[68:71], v[222:225], v[214:217], v[68:71]
	v_mfma_f32_16x16x32_bf16 v[64:67], v[230:233], v[214:217], v[64:67]
	s_setprio 0
	s_mov_b64 s[4:5], 0x1b500180
	v_lshl_add_u64 v[238:239], v[234:235], 0, s[4:5]
	v_readfirstlane_b32 s4, v147
	s_mov_b32 m0, s4
	s_mov_b64 s[4:5], 0x1b520180
	v_lshl_add_u64 v[234:235], v[234:235], 0, s[4:5]
	v_readfirstlane_b32 s4, v173
	s_barrier
	ds_read_b128 v[186:189], v135 offset:16384
	ds_read_b128 v[194:197], v135 offset:18432
	ds_read_b128 v[202:205], v135 offset:20480
	ds_read_b128 v[210:213], v135 offset:22528
	ds_read_b128 v[190:193], v135 offset:17408
	ds_read_b128 v[198:201], v135 offset:19456
	ds_read_b128 v[206:209], v135 offset:21504
	ds_read_b128 v[214:217], v135 offset:23552
	global_load_lds_dwordx4 v[238:239], off
	s_mov_b32 m0, s4
	s_nop 0
	global_load_lds_dwordx4 v[234:235], off
	s_barrier
	s_waitcnt lgkmcnt(4)
	s_setprio 1
	s_waitcnt lgkmcnt(4)
	v_mfma_f32_16x16x32_bf16 v[60:63], v[140:143], v[186:189], v[60:63]
	v_mfma_f32_16x16x32_bf16 v[56:59], v[178:181], v[186:189], v[56:59]
	v_mfma_f32_16x16x32_bf16 v[52:55], v[140:143], v[194:197], v[52:55]
	v_mfma_f32_16x16x32_bf16 v[44:47], v[178:181], v[194:197], v[44:47]
	v_mfma_f32_16x16x32_bf16 v[36:39], v[140:143], v[202:205], v[36:39]
	v_mfma_f32_16x16x32_bf16 v[28:31], v[178:181], v[202:205], v[28:31]
	v_mfma_f32_16x16x32_bf16 v[20:23], v[140:143], v[210:213], v[20:23]
	v_mfma_f32_16x16x32_bf16 v[12:15], v[178:181], v[210:213], v[12:15]
	s_waitcnt lgkmcnt(0)
	v_mfma_f32_16x16x32_bf16 v[60:63], v[162:165], v[190:193], v[60:63]
	v_mfma_f32_16x16x32_bf16 v[56:59], v[182:185], v[190:193], v[56:59]
	v_mfma_f32_16x16x32_bf16 v[52:55], v[162:165], v[198:201], v[52:55]
	v_mfma_f32_16x16x32_bf16 v[44:47], v[182:185], v[198:201], v[44:47]
	v_mfma_f32_16x16x32_bf16 v[36:39], v[162:165], v[206:209], v[36:39]
	v_mfma_f32_16x16x32_bf16 v[28:31], v[182:185], v[206:209], v[28:31]
	v_mfma_f32_16x16x32_bf16 v[20:23], v[162:165], v[214:217], v[20:23]
	v_mfma_f32_16x16x32_bf16 v[12:15], v[182:185], v[214:217], v[12:15]
	s_setprio 0
	s_barrier
	s_mov_b64 s[4:5], 0x2240180
	v_lshl_add_u64 v[140:141], v[236:237], 0, s[4:5]
	v_readfirstlane_b32 s4, v174
	s_mov_b32 m0, s4
	s_mov_b64 s[4:5], 0x2260180
	global_load_lds_dwordx4 v[140:141], off
	v_lshl_add_u64 v[140:141], v[236:237], 0, s[4:5]
	v_readfirstlane_b32 s4, v175
	s_mov_b32 m0, s4
	s_nop 0
	global_load_lds_dwordx4 v[140:141], off
	s_waitcnt vmcnt(6)
	s_barrier
	s_setprio 1
	v_mfma_f32_16x16x32_bf16 v[48:51], v[218:221], v[186:189], v[48:51]
	v_mfma_f32_16x16x32_bf16 v[40:43], v[226:229], v[186:189], v[40:43]
	v_mfma_f32_16x16x32_bf16 v[32:35], v[218:221], v[194:197], v[32:35]
	v_mfma_f32_16x16x32_bf16 v[24:27], v[226:229], v[194:197], v[24:27]
	v_mfma_f32_16x16x32_bf16 v[16:19], v[218:221], v[202:205], v[16:19]
	v_mfma_f32_16x16x32_bf16 v[8:11], v[226:229], v[202:205], v[8:11]
	v_mfma_f32_16x16x32_bf16 v[4:7], v[218:221], v[210:213], v[4:7]
	v_mfma_f32_16x16x32_bf16 v[0:3], v[226:229], v[210:213], v[0:3]
	v_mfma_f32_16x16x32_bf16 v[48:51], v[222:225], v[190:193], v[48:51]
	v_mfma_f32_16x16x32_bf16 v[40:43], v[230:233], v[190:193], v[40:43]
	v_mfma_f32_16x16x32_bf16 v[32:35], v[222:225], v[198:201], v[32:35]
	v_mfma_f32_16x16x32_bf16 v[24:27], v[230:233], v[198:201], v[24:27]
	v_mfma_f32_16x16x32_bf16 v[16:19], v[222:225], v[206:209], v[16:19]
	v_mfma_f32_16x16x32_bf16 v[8:11], v[230:233], v[206:209], v[8:11]
	v_mfma_f32_16x16x32_bf16 v[4:7], v[222:225], v[214:217], v[4:7]
	v_mfma_f32_16x16x32_bf16 v[0:3], v[230:233], v[214:217], v[0:3]
	s_setprio 0
	s_add_i32 s1, s1, 2
	v_lshl_add_u64 v[130:131], v[130:131], 0, s[86:87]
	s_cmp_gt_u32 s1, 11
	v_lshl_add_u64 v[132:133], v[132:133], 0, s[86:87]
	s_barrier
	s_cbranch_scc0 .LBB0_552
	s_mov_b64 s[4:5], 0x40780
	v_readfirstlane_b32 s1, v176
	v_lshl_add_u64 v[174:175], v[128:129], 0, s[4:5]
	s_mov_b32 m0, s1
	s_mov_b64 s[4:5], 0x60780
	v_readfirstlane_b32 s1, v177
	ds_read_b128 v[130:133], v145
	ds_read_b128 v[140:143], v145 offset:1024
	ds_read_b128 v[146:149], v145 offset:2048
	ds_read_b128 v[150:153], v145 offset:3072
	ds_read_b128 v[162:165], v144
	ds_read_b128 v[170:173], v144 offset:1024
	ds_read_b128 v[178:181], v144 offset:2048
	ds_read_b128 v[182:185], v144 offset:3072
	ds_read_b128 v[186:189], v144 offset:4096
	ds_read_b128 v[190:193], v144 offset:5120
	ds_read_b128 v[194:197], v144 offset:6144
	ds_read_b128 v[198:201], v144 offset:7168
	global_load_lds_dwordx4 v[174:175], off
	v_lshl_add_u64 v[128:129], v[128:129], 0, s[4:5]
	s_mov_b32 m0, s1
	s_nop 0
	global_load_lds_dwordx4 v[128:129], off
	s_barrier
	s_waitcnt lgkmcnt(0)
	s_setprio 1
	s_waitcnt lgkmcnt(0)
	v_mfma_f32_16x16x32_bf16 v[124:127], v[130:133], v[162:165], v[124:127]
	v_mfma_f32_16x16x32_bf16 v[120:123], v[146:149], v[162:165], v[120:123]
	v_mfma_f32_16x16x32_bf16 v[116:119], v[130:133], v[178:181], v[116:119]
	v_mfma_f32_16x16x32_bf16 v[112:115], v[146:149], v[178:181], v[112:115]
	v_mfma_f32_16x16x32_bf16 v[100:103], v[130:133], v[186:189], v[100:103]
	v_mfma_f32_16x16x32_bf16 v[96:99], v[146:149], v[186:189], v[96:99]
	v_mfma_f32_16x16x32_bf16 v[84:87], v[130:133], v[194:197], v[84:87]
	v_mfma_f32_16x16x32_bf16 v[80:83], v[146:149], v[194:197], v[80:83]
	v_mfma_f32_16x16x32_bf16 v[124:127], v[140:143], v[170:173], v[124:127]
	v_mfma_f32_16x16x32_bf16 v[120:123], v[150:153], v[170:173], v[120:123]
	v_mfma_f32_16x16x32_bf16 v[116:119], v[140:143], v[182:185], v[116:119]
	v_mfma_f32_16x16x32_bf16 v[112:115], v[150:153], v[182:185], v[112:115]
	v_mfma_f32_16x16x32_bf16 v[100:103], v[140:143], v[190:193], v[100:103]
	v_mfma_f32_16x16x32_bf16 v[96:99], v[150:153], v[190:193], v[96:99]
	v_mfma_f32_16x16x32_bf16 v[84:87], v[140:143], v[198:201], v[84:87]
	v_mfma_f32_16x16x32_bf16 v[80:83], v[150:153], v[198:201], v[80:83]
	s_setprio 0
	s_barrier
	ds_read_b128 v[174:177], v145 offset:16384
	ds_read_b128 v[202:205], v145 offset:17408
	ds_read_b128 v[206:209], v145 offset:18432
	ds_read_b128 v[210:213], v145 offset:19456
	s_barrier
	s_waitcnt lgkmcnt(0)
	s_setprio 1
	s_waitcnt lgkmcnt(0)
	v_mfma_f32_16x16x32_bf16 v[68:71], v[174:177], v[194:197], v[68:71]
	v_mfma_f32_16x16x32_bf16 v[64:67], v[206:209], v[194:197], v[64:67]
	v_mfma_f32_16x16x32_bf16 v[108:111], v[174:177], v[162:165], v[108:111]
	v_mfma_f32_16x16x32_bf16 v[104:107], v[206:209], v[162:165], v[104:107]
	v_mfma_f32_16x16x32_bf16 v[92:95], v[174:177], v[178:181], v[92:95]
	v_mfma_f32_16x16x32_bf16 v[88:91], v[206:209], v[178:181], v[88:91]
	v_mfma_f32_16x16x32_bf16 v[76:79], v[174:177], v[186:189], v[76:79]
	v_mfma_f32_16x16x32_bf16 v[72:75], v[206:209], v[186:189], v[72:75]
	v_mfma_f32_16x16x32_bf16 v[68:71], v[202:205], v[198:201], v[68:71]
	v_mfma_f32_16x16x32_bf16 v[64:67], v[210:213], v[198:201], v[64:67]
	v_mfma_f32_16x16x32_bf16 v[214:217], v[202:205], v[170:173], v[108:111]
	v_mfma_f32_16x16x32_bf16 v[162:165], v[210:213], v[170:173], v[104:107]
	v_mfma_f32_16x16x32_bf16 v[170:173], v[202:205], v[182:185], v[92:95]
	v_mfma_f32_16x16x32_bf16 v[178:181], v[210:213], v[182:185], v[88:91]
	v_mfma_f32_16x16x32_bf16 v[182:185], v[202:205], v[190:193], v[76:79]
	v_mfma_f32_16x16x32_bf16 v[186:189], v[210:213], v[190:193], v[72:75]
	s_setprio 0
	s_barrier
	s_nop 0
	ds_read_b128 v[72:75], v144 offset:16384
	ds_read_b128 v[76:79], v144 offset:17408
	ds_read_b128 v[88:91], v144 offset:18432
	ds_read_b128 v[92:95], v144 offset:19456
	ds_read_b128 v[104:107], v144 offset:20480
	ds_read_b128 v[108:111], v144 offset:21504
	ds_read_b128 v[190:193], v144 offset:22528
	ds_read_b128 v[194:197], v144 offset:23552
	s_waitcnt vmcnt(4)
	s_barrier
	s_waitcnt lgkmcnt(0)
	s_setprio 1
	s_waitcnt lgkmcnt(0)
	v_mfma_f32_16x16x32_bf16 v[60:63], v[130:133], v[72:75], v[60:63]
	v_mfma_f32_16x16x32_bf16 v[56:59], v[146:149], v[72:75], v[56:59]
	v_mfma_f32_16x16x32_bf16 v[52:55], v[130:133], v[88:91], v[52:55]
	v_mfma_f32_16x16x32_bf16 v[36:39], v[130:133], v[104:107], v[36:39]
	v_mfma_f32_16x16x32_bf16 v[20:23], v[130:133], v[190:193], v[20:23]
	v_mfma_f32_16x16x32_bf16 v[60:63], v[140:143], v[76:79], v[60:63]
	v_mfma_f32_16x16x32_bf16 v[56:59], v[150:153], v[76:79], v[56:59]
	v_mfma_f32_16x16x32_bf16 v[52:55], v[140:143], v[92:95], v[52:55]
	v_mfma_f32_16x16x32_bf16 v[44:47], v[146:149], v[88:91], v[44:47]
	v_mfma_f32_16x16x32_bf16 v[36:39], v[140:143], v[108:111], v[36:39]
	v_mfma_f32_16x16x32_bf16 v[28:31], v[146:149], v[104:107], v[28:31]
	v_mfma_f32_16x16x32_bf16 v[20:23], v[140:143], v[194:197], v[20:23]
	v_mfma_f32_16x16x32_bf16 v[12:15], v[146:149], v[190:193], v[12:15]
	v_mfma_f32_16x16x32_bf16 v[198:201], v[150:153], v[92:95], v[44:47]
	v_mfma_f32_16x16x32_bf16 v[218:221], v[150:153], v[108:111], v[28:31]
	v_mfma_f32_16x16x32_bf16 v[128:131], v[150:153], v[194:197], v[12:15]
	s_setprio 0
	s_setprio 1
	v_mfma_f32_16x16x32_bf16 v[12:15], v[174:177], v[72:75], v[48:51]
	v_mfma_f32_16x16x32_bf16 v[48:51], v[202:205], v[76:79], v[12:15]
	v_mfma_f32_16x16x32_bf16 v[12:15], v[206:209], v[72:75], v[40:43]
	v_mfma_f32_16x16x32_bf16 v[140:143], v[210:213], v[76:79], v[12:15]
	v_mfma_f32_16x16x32_bf16 v[12:15], v[174:177], v[88:91], v[32:35]
	v_mfma_f32_16x16x32_bf16 v[32:35], v[202:205], v[92:95], v[12:15]
	v_mfma_f32_16x16x32_bf16 v[12:15], v[206:209], v[88:91], v[24:27]
	v_mfma_f32_16x16x32_bf16 v[144:147], v[210:213], v[92:95], v[12:15]
	v_mfma_f32_16x16x32_bf16 v[12:15], v[174:177], v[104:107], v[16:19]
	v_mfma_f32_16x16x32_bf16 v[4:7], v[174:177], v[190:193], v[4:7]
	v_mfma_f32_16x16x32_bf16 v[0:3], v[206:209], v[190:193], v[0:3]
	v_mfma_f32_16x16x32_bf16 v[16:19], v[202:205], v[108:111], v[12:15]
	v_mfma_f32_16x16x32_bf16 v[8:11], v[206:209], v[104:107], v[8:11]
	v_mfma_f32_16x16x32_bf16 v[4:7], v[202:205], v[194:197], v[4:7]
	v_mfma_f32_16x16x32_bf16 v[0:3], v[210:213], v[194:197], v[0:3]
	v_mfma_f32_16x16x32_bf16 v[148:151], v[210:213], v[108:111], v[8:11]
	s_setprio 0
	s_barrier
	s_nop 2
	ds_read_b128 v[8:11], v139
	ds_read_b128 v[12:15], v139 offset:1024
	ds_read_b128 v[174:177], v139 offset:2048
	ds_read_b128 v[190:193], v139 offset:3072
	ds_read_b128 v[24:27], v135
	ds_read_b128 v[28:31], v135 offset:1024
	ds_read_b128 v[40:43], v135 offset:2048
	ds_read_b128 v[44:47], v135 offset:3072
	ds_read_b128 v[194:197], v135 offset:4096
	ds_read_b128 v[202:205], v135 offset:5120
	ds_read_b128 v[206:209], v135 offset:6144
	ds_read_b128 v[210:213], v135 offset:7168
	s_waitcnt vmcnt(2)
	s_barrier
	s_waitcnt lgkmcnt(0)
	s_setprio 1
	s_waitcnt lgkmcnt(0)
	v_mfma_f32_16x16x32_bf16 v[72:75], v[8:11], v[24:27], v[124:127]
	v_mfma_f32_16x16x32_bf16 v[124:127], v[12:15], v[28:31], v[72:75]
	v_mfma_f32_16x16x32_bf16 v[72:75], v[174:177], v[24:27], v[120:123]
	v_mfma_f32_16x16x32_bf16 v[120:123], v[190:193], v[28:31], v[72:75]
	v_mfma_f32_16x16x32_bf16 v[72:75], v[8:11], v[40:43], v[116:119]
	v_mfma_f32_16x16x32_bf16 v[108:111], v[12:15], v[44:47], v[72:75]
	v_mfma_f32_16x16x32_bf16 v[72:75], v[174:177], v[40:43], v[112:115]
	v_mfma_f32_16x16x32_bf16 v[104:107], v[190:193], v[44:47], v[72:75]
	v_mfma_f32_16x16x32_bf16 v[72:75], v[8:11], v[194:197], v[100:103]
	v_mfma_f32_16x16x32_bf16 v[92:95], v[12:15], v[202:205], v[72:75]
	v_mfma_f32_16x16x32_bf16 v[72:75], v[174:177], v[194:197], v[96:99]
	v_mfma_f32_16x16x32_bf16 v[88:91], v[190:193], v[202:205], v[72:75]
	v_mfma_f32_16x16x32_bf16 v[72:75], v[8:11], v[206:209], v[84:87]
	v_mfma_f32_16x16x32_bf16 v[76:79], v[12:15], v[210:213], v[72:75]
	v_mfma_f32_16x16x32_bf16 v[72:75], v[174:177], v[206:209], v[80:83]
	v_mfma_f32_16x16x32_bf16 v[72:75], v[190:193], v[210:213], v[72:75]
	s_setprio 0
	s_barrier
	ds_read_b128 v[222:225], v139 offset:16384
	ds_read_b128 v[226:229], v139 offset:17408
	ds_read_b128 v[230:233], v139 offset:18432
	ds_read_b128 v[234:237], v139 offset:19456
	s_waitcnt vmcnt(0)
	s_barrier
	s_waitcnt lgkmcnt(0)
	s_setprio 1
	s_waitcnt lgkmcnt(0)
	v_mfma_f32_16x16x32_bf16 v[80:83], v[222:225], v[24:27], v[214:217]
	v_mfma_f32_16x16x32_bf16 v[24:27], v[230:233], v[24:27], v[162:165]
	v_mfma_f32_16x16x32_bf16 v[112:115], v[234:237], v[28:31], v[24:27]
	v_mfma_f32_16x16x32_bf16 v[24:27], v[222:225], v[40:43], v[170:173]
	v_mfma_f32_16x16x32_bf16 v[100:103], v[226:229], v[44:47], v[24:27]
	v_mfma_f32_16x16x32_bf16 v[24:27], v[230:233], v[40:43], v[178:181]
	v_mfma_f32_16x16x32_bf16 v[96:99], v[234:237], v[44:47], v[24:27]
	v_mfma_f32_16x16x32_bf16 v[24:27], v[222:225], v[194:197], v[182:185]
	v_mfma_f32_16x16x32_bf16 v[84:87], v[226:229], v[202:205], v[24:27]
	v_mfma_f32_16x16x32_bf16 v[24:27], v[230:233], v[194:197], v[186:189]
	v_mfma_f32_16x16x32_bf16 v[116:119], v[226:229], v[28:31], v[80:83]
	v_mfma_f32_16x16x32_bf16 v[80:83], v[234:237], v[202:205], v[24:27]
	v_mfma_f32_16x16x32_bf16 v[24:27], v[222:225], v[206:209], v[68:71]
	v_mfma_f32_16x16x32_bf16 v[68:71], v[226:229], v[210:213], v[24:27]
	v_mfma_f32_16x16x32_bf16 v[24:27], v[230:233], v[206:209], v[64:67]
	v_mfma_f32_16x16x32_bf16 v[64:67], v[234:237], v[210:213], v[24:27]
	s_setprio 0
	s_barrier
	ds_read_b128 v[162:165], v135 offset:16384
	ds_read_b128 v[170:173], v135 offset:17408
	ds_read_b128 v[178:181], v135 offset:18432
	ds_read_b128 v[182:185], v135 offset:19456
	ds_read_b128 v[186:189], v135 offset:20480
	ds_read_b128 v[194:197], v135 offset:21504
	ds_read_b128 v[202:205], v135 offset:22528
	ds_read_b128 v[206:209], v135 offset:23552
	s_barrier
	s_waitcnt lgkmcnt(0)
	s_setprio 1
	s_waitcnt lgkmcnt(0)
	v_mfma_f32_16x16x32_bf16 v[24:27], v[8:11], v[162:165], v[60:63]
	v_mfma_f32_16x16x32_bf16 v[60:63], v[12:15], v[170:173], v[24:27]
	v_mfma_f32_16x16x32_bf16 v[24:27], v[174:177], v[162:165], v[56:59]
	v_mfma_f32_16x16x32_bf16 v[56:59], v[190:193], v[170:173], v[24:27]
	v_mfma_f32_16x16x32_bf16 v[24:27], v[8:11], v[178:181], v[52:55]
	v_mfma_f32_16x16x32_bf16 v[44:47], v[12:15], v[182:185], v[24:27]
	v_mfma_f32_16x16x32_bf16 v[24:27], v[174:177], v[178:181], v[198:201]
	v_mfma_f32_16x16x32_bf16 v[40:43], v[190:193], v[182:185], v[24:27]
	v_mfma_f32_16x16x32_bf16 v[24:27], v[8:11], v[186:189], v[36:39]
	v_mfma_f32_16x16x32_bf16 v[8:11], v[8:11], v[202:205], v[20:23]
	v_mfma_f32_16x16x32_bf16 v[28:31], v[12:15], v[194:197], v[24:27]
	v_mfma_f32_16x16x32_bf16 v[24:27], v[174:177], v[186:189], v[218:221]
	v_mfma_f32_16x16x32_bf16 v[12:15], v[12:15], v[206:209], v[8:11]
	v_mfma_f32_16x16x32_bf16 v[8:11], v[174:177], v[202:205], v[128:131]
	v_mfma_f32_16x16x32_bf16 v[24:27], v[190:193], v[194:197], v[24:27]
	v_mfma_f32_16x16x32_bf16 v[8:11], v[190:193], v[206:209], v[8:11]
	s_setprio 0
	s_setprio 1
	v_mfma_f32_16x16x32_bf16 v[20:23], v[222:225], v[162:165], v[48:51]
	v_mfma_f32_16x16x32_bf16 v[52:55], v[226:229], v[170:173], v[20:23]
	v_mfma_f32_16x16x32_bf16 v[20:23], v[230:233], v[162:165], v[140:143]
	v_mfma_f32_16x16x32_bf16 v[48:51], v[234:237], v[170:173], v[20:23]
	v_mfma_f32_16x16x32_bf16 v[20:23], v[222:225], v[178:181], v[32:35]
	v_mfma_f32_16x16x32_bf16 v[36:39], v[226:229], v[182:185], v[20:23]
	v_mfma_f32_16x16x32_bf16 v[20:23], v[230:233], v[178:181], v[144:147]
	v_mfma_f32_16x16x32_bf16 v[16:19], v[222:225], v[186:189], v[16:19]
	v_mfma_f32_16x16x32_bf16 v[32:35], v[234:237], v[182:185], v[20:23]
	v_mfma_f32_16x16x32_bf16 v[20:23], v[226:229], v[194:197], v[16:19]
	v_mfma_f32_16x16x32_bf16 v[16:19], v[230:233], v[186:189], v[148:151]
	v_mfma_f32_16x16x32_bf16 v[4:7], v[222:225], v[202:205], v[4:7]
	v_mfma_f32_16x16x32_bf16 v[0:3], v[230:233], v[202:205], v[0:3]
	v_mfma_f32_16x16x32_bf16 v[16:19], v[234:237], v[194:197], v[16:19]
	v_mfma_f32_16x16x32_bf16 v[4:7], v[226:229], v[206:209], v[4:7]
	v_mfma_f32_16x16x32_bf16 v[0:3], v[234:237], v[206:209], v[0:3]
	s_setprio 0
	s_movk_i32 s1, 0x100
	v_cmp_gt_u32_e32 vcc, s1, v134
	s_barrier
	s_and_saveexec_b64 s[4:5], vcc
	s_cbranch_execz .LBB0_548
	s_barrier
	s_branch .LBB0_548

.LBB0_591:
	ds_read_b128 v[140:143], v135
	ds_read_b128 v[178:181], v135 offset:2048
	ds_read_b128 v[162:165], v135 offset:1024
	ds_read_b128 v[182:185], v135 offset:3072
	v_lshl_add_u64 v[234:235], v[132:133], 0, v[136:137]
	s_mov_b64 s[4:5], 0x1d540080
	v_add_u32_e32 v176, 0x4000, v147
	v_lshl_add_u64 v[218:219], v[234:235], 0, s[4:5]
	v_readfirstlane_b32 s4, v176
	s_mov_b32 m0, s4
	s_mov_b64 s[4:5], 0x1d560080
	v_add_u32_e32 v177, 0x6000, v147
	ds_read_b128 v[186:189], v134
	ds_read_b128 v[194:197], v134 offset:2048
	ds_read_b128 v[202:205], v134 offset:4096
	ds_read_b128 v[210:213], v134 offset:6144
	ds_read_b128 v[190:193], v134 offset:1024
	ds_read_b128 v[198:201], v134 offset:3072
	ds_read_b128 v[206:209], v134 offset:5120
	ds_read_b128 v[214:217], v134 offset:7168
	global_load_lds_dwordx4 v[218:219], off
	v_lshl_add_u64 v[218:219], v[234:235], 0, s[4:5]
	v_readfirstlane_b32 s4, v177
	s_mov_b32 m0, s4
	s_nop 0
	global_load_lds_dwordx4 v[218:219], off
	s_waitcnt lgkmcnt(8)
	s_barrier
	s_waitcnt lgkmcnt(4)
	s_setprio 1
	s_waitcnt lgkmcnt(4)
	v_mfma_f32_16x16x32_bf16 v[124:127], v[140:143], v[186:189], v[124:127]
	v_mfma_f32_16x16x32_bf16 v[120:123], v[178:181], v[186:189], v[120:123]
	v_mfma_f32_16x16x32_bf16 v[116:119], v[140:143], v[194:197], v[116:119]
	v_mfma_f32_16x16x32_bf16 v[112:115], v[178:181], v[194:197], v[112:115]
	v_mfma_f32_16x16x32_bf16 v[100:103], v[140:143], v[202:205], v[100:103]
	v_mfma_f32_16x16x32_bf16 v[96:99], v[178:181], v[202:205], v[96:99]
	v_mfma_f32_16x16x32_bf16 v[84:87], v[140:143], v[210:213], v[84:87]
	v_mfma_f32_16x16x32_bf16 v[80:83], v[178:181], v[210:213], v[80:83]
	s_waitcnt lgkmcnt(0)
	v_mfma_f32_16x16x32_bf16 v[124:127], v[162:165], v[190:193], v[124:127]
	v_mfma_f32_16x16x32_bf16 v[120:123], v[182:185], v[190:193], v[120:123]
	v_mfma_f32_16x16x32_bf16 v[116:119], v[162:165], v[198:201], v[116:119]
	v_mfma_f32_16x16x32_bf16 v[112:115], v[182:185], v[198:201], v[112:115]
	v_mfma_f32_16x16x32_bf16 v[100:103], v[162:165], v[206:209], v[100:103]
	v_mfma_f32_16x16x32_bf16 v[96:99], v[182:185], v[206:209], v[96:99]
	v_mfma_f32_16x16x32_bf16 v[84:87], v[162:165], v[214:217], v[84:87]
	v_mfma_f32_16x16x32_bf16 v[80:83], v[182:185], v[214:217], v[80:83]
	s_setprio 0
	s_barrier
	v_lshl_add_u64 v[236:237], v[130:131], 0, v[136:137]
	s_mov_b64 s[4:5], 0x2400100
	v_lshl_add_u64 v[238:239], v[236:237], 0, s[4:5]
	v_readfirstlane_b32 s4, v148
	s_mov_b32 m0, s4
	s_mov_b64 s[4:5], 0x2420100
	ds_read_b128 v[218:221], v135 offset:16384
	ds_read_b128 v[226:229], v135 offset:18432
	ds_read_b128 v[222:225], v135 offset:17408
	ds_read_b128 v[230:233], v135 offset:19456
	global_load_lds_dwordx4 v[238:239], off
	v_lshl_add_u64 v[238:239], v[236:237], 0, s[4:5]
	v_readfirstlane_b32 s4, v149
	s_mov_b32 m0, s4
	s_nop 0
	global_load_lds_dwordx4 v[238:239], off
	s_barrier
	s_waitcnt lgkmcnt(2)
	s_setprio 1
	s_waitcnt lgkmcnt(2)
	v_mfma_f32_16x16x32_bf16 v[108:111], v[218:221], v[186:189], v[108:111]
	v_mfma_f32_16x16x32_bf16 v[104:107], v[226:229], v[186:189], v[104:107]
	v_mfma_f32_16x16x32_bf16 v[92:95], v[218:221], v[194:197], v[92:95]
	v_mfma_f32_16x16x32_bf16 v[88:91], v[226:229], v[194:197], v[88:91]
	v_mfma_f32_16x16x32_bf16 v[76:79], v[218:221], v[202:205], v[76:79]
	v_mfma_f32_16x16x32_bf16 v[72:75], v[226:229], v[202:205], v[72:75]
	v_mfma_f32_16x16x32_bf16 v[68:71], v[218:221], v[210:213], v[68:71]
	v_mfma_f32_16x16x32_bf16 v[64:67], v[226:229], v[210:213], v[64:67]
	s_waitcnt lgkmcnt(0)
	v_mfma_f32_16x16x32_bf16 v[108:111], v[222:225], v[190:193], v[108:111]
	v_mfma_f32_16x16x32_bf16 v[104:107], v[230:233], v[190:193], v[104:107]
	v_mfma_f32_16x16x32_bf16 v[92:95], v[222:225], v[198:201], v[92:95]
	v_mfma_f32_16x16x32_bf16 v[88:91], v[230:233], v[198:201], v[88:91]
	v_mfma_f32_16x16x32_bf16 v[76:79], v[222:225], v[206:209], v[76:79]
	v_mfma_f32_16x16x32_bf16 v[72:75], v[230:233], v[206:209], v[72:75]
	v_mfma_f32_16x16x32_bf16 v[68:71], v[222:225], v[214:217], v[68:71]
	v_mfma_f32_16x16x32_bf16 v[64:67], v[230:233], v[214:217], v[64:67]
	s_setprio 0
	s_mov_b64 s[4:5], 0x1d500100
	v_lshl_add_u64 v[238:239], v[234:235], 0, s[4:5]
	v_readfirstlane_b32 s4, v146
	s_mov_b32 m0, s4
	s_mov_b64 s[4:5], 0x1d520100
	s_barrier
	ds_read_b128 v[186:189], v134 offset:16384
	ds_read_b128 v[194:197], v134 offset:18432
	ds_read_b128 v[202:205], v134 offset:20480
	ds_read_b128 v[210:213], v134 offset:22528
	ds_read_b128 v[190:193], v134 offset:17408
	ds_read_b128 v[198:201], v134 offset:19456
	ds_read_b128 v[206:209], v134 offset:21504
	ds_read_b128 v[214:217], v134 offset:23552
	global_load_lds_dwordx4 v[238:239], off
	v_lshl_add_u64 v[238:239], v[234:235], 0, s[4:5]
	v_readfirstlane_b32 s4, v150
	s_mov_b32 m0, s4
	s_nop 0
	global_load_lds_dwordx4 v[238:239], off
	s_barrier
	s_waitcnt lgkmcnt(4)
	s_setprio 1
	s_waitcnt lgkmcnt(4)
	v_mfma_f32_16x16x32_bf16 v[60:63], v[140:143], v[186:189], v[60:63]
	v_mfma_f32_16x16x32_bf16 v[56:59], v[178:181], v[186:189], v[56:59]
	v_mfma_f32_16x16x32_bf16 v[52:55], v[140:143], v[194:197], v[52:55]
	v_mfma_f32_16x16x32_bf16 v[44:47], v[178:181], v[194:197], v[44:47]
	v_mfma_f32_16x16x32_bf16 v[36:39], v[140:143], v[202:205], v[36:39]
	v_mfma_f32_16x16x32_bf16 v[28:31], v[178:181], v[202:205], v[28:31]
	v_mfma_f32_16x16x32_bf16 v[20:23], v[140:143], v[210:213], v[20:23]
	v_mfma_f32_16x16x32_bf16 v[12:15], v[178:181], v[210:213], v[12:15]
	s_waitcnt lgkmcnt(0)
	v_mfma_f32_16x16x32_bf16 v[60:63], v[162:165], v[190:193], v[60:63]
	v_mfma_f32_16x16x32_bf16 v[56:59], v[182:185], v[190:193], v[56:59]
	v_mfma_f32_16x16x32_bf16 v[52:55], v[162:165], v[198:201], v[52:55]
	v_mfma_f32_16x16x32_bf16 v[44:47], v[182:185], v[198:201], v[44:47]
	v_mfma_f32_16x16x32_bf16 v[36:39], v[162:165], v[206:209], v[36:39]
	v_mfma_f32_16x16x32_bf16 v[28:31], v[182:185], v[206:209], v[28:31]
	v_mfma_f32_16x16x32_bf16 v[20:23], v[162:165], v[214:217], v[20:23]
	v_mfma_f32_16x16x32_bf16 v[12:15], v[182:185], v[214:217], v[12:15]
	s_setprio 0
	s_barrier
	s_mov_b64 s[4:5], 0x2440100
	v_lshl_add_u64 v[140:141], v[236:237], 0, s[4:5]
	v_readfirstlane_b32 s4, v151
	s_mov_b32 m0, s4
	s_mov_b64 s[4:5], 0x2460100
	global_load_lds_dwordx4 v[140:141], off
	v_lshl_add_u64 v[140:141], v[236:237], 0, s[4:5]
	v_readfirstlane_b32 s4, v152
	s_mov_b32 m0, s4
	s_nop 0
	global_load_lds_dwordx4 v[140:141], off
	s_waitcnt vmcnt(6)
	s_barrier
	s_setprio 1
	v_mfma_f32_16x16x32_bf16 v[48:51], v[218:221], v[186:189], v[48:51]
	v_mfma_f32_16x16x32_bf16 v[40:43], v[226:229], v[186:189], v[40:43]
	v_mfma_f32_16x16x32_bf16 v[32:35], v[218:221], v[194:197], v[32:35]
	v_mfma_f32_16x16x32_bf16 v[24:27], v[226:229], v[194:197], v[24:27]
	v_mfma_f32_16x16x32_bf16 v[16:19], v[218:221], v[202:205], v[16:19]
	v_mfma_f32_16x16x32_bf16 v[8:11], v[226:229], v[202:205], v[8:11]
	v_mfma_f32_16x16x32_bf16 v[4:7], v[218:221], v[210:213], v[4:7]
	v_mfma_f32_16x16x32_bf16 v[0:3], v[226:229], v[210:213], v[0:3]
	v_mfma_f32_16x16x32_bf16 v[48:51], v[222:225], v[190:193], v[48:51]
	v_mfma_f32_16x16x32_bf16 v[40:43], v[230:233], v[190:193], v[40:43]
	v_mfma_f32_16x16x32_bf16 v[32:35], v[222:225], v[198:201], v[32:35]
	v_mfma_f32_16x16x32_bf16 v[24:27], v[230:233], v[198:201], v[24:27]
	v_mfma_f32_16x16x32_bf16 v[16:19], v[222:225], v[206:209], v[16:19]
	v_mfma_f32_16x16x32_bf16 v[8:11], v[230:233], v[206:209], v[8:11]
	v_mfma_f32_16x16x32_bf16 v[4:7], v[222:225], v[214:217], v[4:7]
	v_mfma_f32_16x16x32_bf16 v[0:3], v[230:233], v[214:217], v[0:3]
	s_setprio 0
	s_barrier
	ds_read_b128 v[140:143], v145
	ds_read_b128 v[178:181], v145 offset:2048
	ds_read_b128 v[162:165], v145 offset:1024
	ds_read_b128 v[182:185], v145 offset:3072
	s_mov_b64 s[4:5], 0x1d540100
	v_lshl_add_u64 v[218:219], v[234:235], 0, s[4:5]
	v_readfirstlane_b32 s4, v153
	s_mov_b32 m0, s4
	s_mov_b64 s[4:5], 0x1d560100
	ds_read_b128 v[186:189], v144
	ds_read_b128 v[194:197], v144 offset:2048
	ds_read_b128 v[202:205], v144 offset:4096
	ds_read_b128 v[210:213], v144 offset:6144
	ds_read_b128 v[190:193], v144 offset:1024
	ds_read_b128 v[198:201], v144 offset:3072
	ds_read_b128 v[206:209], v144 offset:5120
	ds_read_b128 v[214:217], v144 offset:7168
	global_load_lds_dwordx4 v[218:219], off
	v_lshl_add_u64 v[218:219], v[234:235], 0, s[4:5]
	v_readfirstlane_b32 s4, v170
	s_mov_b32 m0, s4
	s_nop 0
	global_load_lds_dwordx4 v[218:219], off
	s_waitcnt lgkmcnt(8)
	s_barrier
	s_waitcnt lgkmcnt(4)
	s_setprio 1
	s_waitcnt lgkmcnt(4)
	v_mfma_f32_16x16x32_bf16 v[124:127], v[140:143], v[186:189], v[124:127]
	v_mfma_f32_16x16x32_bf16 v[120:123], v[178:181], v[186:189], v[120:123]
	v_mfma_f32_16x16x32_bf16 v[116:119], v[140:143], v[194:197], v[116:119]
	v_mfma_f32_16x16x32_bf16 v[112:115], v[178:181], v[194:197], v[112:115]
	v_mfma_f32_16x16x32_bf16 v[100:103], v[140:143], v[202:205], v[100:103]
	v_mfma_f32_16x16x32_bf16 v[96:99], v[178:181], v[202:205], v[96:99]
	v_mfma_f32_16x16x32_bf16 v[84:87], v[140:143], v[210:213], v[84:87]
	v_mfma_f32_16x16x32_bf16 v[80:83], v[178:181], v[210:213], v[80:83]
	s_waitcnt lgkmcnt(0)
	v_mfma_f32_16x16x32_bf16 v[124:127], v[162:165], v[190:193], v[124:127]
	v_mfma_f32_16x16x32_bf16 v[120:123], v[182:185], v[190:193], v[120:123]
	v_mfma_f32_16x16x32_bf16 v[116:119], v[162:165], v[198:201], v[116:119]
	v_mfma_f32_16x16x32_bf16 v[112:115], v[182:185], v[198:201], v[112:115]
	v_mfma_f32_16x16x32_bf16 v[100:103], v[162:165], v[206:209], v[100:103]
	v_mfma_f32_16x16x32_bf16 v[96:99], v[182:185], v[206:209], v[96:99]
	v_mfma_f32_16x16x32_bf16 v[84:87], v[162:165], v[214:217], v[84:87]
	v_mfma_f32_16x16x32_bf16 v[80:83], v[182:185], v[214:217], v[80:83]
	s_setprio 0
	s_barrier
	s_mov_b64 s[4:5], 0x2400180
	v_lshl_add_u64 v[238:239], v[236:237], 0, s[4:5]
	v_readfirstlane_b32 s4, v171
	s_mov_b32 m0, s4
	s_mov_b64 s[4:5], 0x2420180
	ds_read_b128 v[218:221], v145 offset:16384
	ds_read_b128 v[226:229], v145 offset:18432
	ds_read_b128 v[222:225], v145 offset:17408
	ds_read_b128 v[230:233], v145 offset:19456
	global_load_lds_dwordx4 v[238:239], off
	v_lshl_add_u64 v[238:239], v[236:237], 0, s[4:5]
	v_readfirstlane_b32 s4, v172
	s_mov_b32 m0, s4
	s_nop 0
	global_load_lds_dwordx4 v[238:239], off
	s_barrier
	s_waitcnt lgkmcnt(2)
	s_setprio 1
	s_waitcnt lgkmcnt(2)
	v_mfma_f32_16x16x32_bf16 v[108:111], v[218:221], v[186:189], v[108:111]
	v_mfma_f32_16x16x32_bf16 v[104:107], v[226:229], v[186:189], v[104:107]
	v_mfma_f32_16x16x32_bf16 v[92:95], v[218:221], v[194:197], v[92:95]
	v_mfma_f32_16x16x32_bf16 v[88:91], v[226:229], v[194:197], v[88:91]
	v_mfma_f32_16x16x32_bf16 v[76:79], v[218:221], v[202:205], v[76:79]
	v_mfma_f32_16x16x32_bf16 v[72:75], v[226:229], v[202:205], v[72:75]
	v_mfma_f32_16x16x32_bf16 v[68:71], v[218:221], v[210:213], v[68:71]
	v_mfma_f32_16x16x32_bf16 v[64:67], v[226:229], v[210:213], v[64:67]
	s_waitcnt lgkmcnt(0)
	v_mfma_f32_16x16x32_bf16 v[108:111], v[222:225], v[190:193], v[108:111]
	v_mfma_f32_16x16x32_bf16 v[104:107], v[230:233], v[190:193], v[104:107]
	v_mfma_f32_16x16x32_bf16 v[92:95], v[222:225], v[198:201], v[92:95]
	v_mfma_f32_16x16x32_bf16 v[88:91], v[230:233], v[198:201], v[88:91]
	v_mfma_f32_16x16x32_bf16 v[76:79], v[222:225], v[206:209], v[76:79]
	v_mfma_f32_16x16x32_bf16 v[72:75], v[230:233], v[206:209], v[72:75]
	v_mfma_f32_16x16x32_bf16 v[68:71], v[222:225], v[214:217], v[68:71]
	v_mfma_f32_16x16x32_bf16 v[64:67], v[230:233], v[214:217], v[64:67]
	s_setprio 0
	s_mov_b64 s[4:5], 0x1d500180
	v_lshl_add_u64 v[238:239], v[234:235], 0, s[4:5]
	v_readfirstlane_b32 s4, v147
	s_mov_b32 m0, s4
	s_mov_b64 s[4:5], 0x1d520180
	v_lshl_add_u64 v[234:235], v[234:235], 0, s[4:5]
	v_readfirstlane_b32 s4, v173
	s_barrier
	ds_read_b128 v[186:189], v144 offset:16384
	ds_read_b128 v[194:197], v144 offset:18432
	ds_read_b128 v[202:205], v144 offset:20480
	ds_read_b128 v[210:213], v144 offset:22528
	ds_read_b128 v[190:193], v144 offset:17408
	ds_read_b128 v[198:201], v144 offset:19456
	ds_read_b128 v[206:209], v144 offset:21504
	ds_read_b128 v[214:217], v144 offset:23552
	global_load_lds_dwordx4 v[238:239], off
	s_mov_b32 m0, s4
	s_nop 0
	global_load_lds_dwordx4 v[234:235], off
	s_barrier
	s_waitcnt lgkmcnt(4)
	s_setprio 1
	s_waitcnt lgkmcnt(4)
	v_mfma_f32_16x16x32_bf16 v[60:63], v[140:143], v[186:189], v[60:63]
	v_mfma_f32_16x16x32_bf16 v[56:59], v[178:181], v[186:189], v[56:59]
	v_mfma_f32_16x16x32_bf16 v[52:55], v[140:143], v[194:197], v[52:55]
	v_mfma_f32_16x16x32_bf16 v[44:47], v[178:181], v[194:197], v[44:47]
	v_mfma_f32_16x16x32_bf16 v[36:39], v[140:143], v[202:205], v[36:39]
	v_mfma_f32_16x16x32_bf16 v[28:31], v[178:181], v[202:205], v[28:31]
	v_mfma_f32_16x16x32_bf16 v[20:23], v[140:143], v[210:213], v[20:23]
	v_mfma_f32_16x16x32_bf16 v[12:15], v[178:181], v[210:213], v[12:15]
	s_waitcnt lgkmcnt(0)
	v_mfma_f32_16x16x32_bf16 v[60:63], v[162:165], v[190:193], v[60:63]
	v_mfma_f32_16x16x32_bf16 v[56:59], v[182:185], v[190:193], v[56:59]
	v_mfma_f32_16x16x32_bf16 v[52:55], v[162:165], v[198:201], v[52:55]
	v_mfma_f32_16x16x32_bf16 v[44:47], v[182:185], v[198:201], v[44:47]
	v_mfma_f32_16x16x32_bf16 v[36:39], v[162:165], v[206:209], v[36:39]
	v_mfma_f32_16x16x32_bf16 v[28:31], v[182:185], v[206:209], v[28:31]
	v_mfma_f32_16x16x32_bf16 v[20:23], v[162:165], v[214:217], v[20:23]
	v_mfma_f32_16x16x32_bf16 v[12:15], v[182:185], v[214:217], v[12:15]
	s_setprio 0
	s_barrier
	s_mov_b64 s[4:5], 0x2440180
	v_lshl_add_u64 v[140:141], v[236:237], 0, s[4:5]
	v_readfirstlane_b32 s4, v174
	s_mov_b32 m0, s4
	s_mov_b64 s[4:5], 0x2460180
	global_load_lds_dwordx4 v[140:141], off
	v_lshl_add_u64 v[140:141], v[236:237], 0, s[4:5]
	v_readfirstlane_b32 s4, v175
	s_mov_b32 m0, s4
	s_nop 0
	global_load_lds_dwordx4 v[140:141], off
	s_waitcnt vmcnt(6)
	s_barrier
	s_setprio 1
	v_mfma_f32_16x16x32_bf16 v[48:51], v[218:221], v[186:189], v[48:51]
	v_mfma_f32_16x16x32_bf16 v[40:43], v[226:229], v[186:189], v[40:43]
	v_mfma_f32_16x16x32_bf16 v[32:35], v[218:221], v[194:197], v[32:35]
	v_mfma_f32_16x16x32_bf16 v[24:27], v[226:229], v[194:197], v[24:27]
	v_mfma_f32_16x16x32_bf16 v[16:19], v[218:221], v[202:205], v[16:19]
	v_mfma_f32_16x16x32_bf16 v[8:11], v[226:229], v[202:205], v[8:11]
	v_mfma_f32_16x16x32_bf16 v[4:7], v[218:221], v[210:213], v[4:7]
	v_mfma_f32_16x16x32_bf16 v[0:3], v[226:229], v[210:213], v[0:3]
	v_mfma_f32_16x16x32_bf16 v[48:51], v[222:225], v[190:193], v[48:51]
	v_mfma_f32_16x16x32_bf16 v[40:43], v[230:233], v[190:193], v[40:43]
	v_mfma_f32_16x16x32_bf16 v[32:35], v[222:225], v[198:201], v[32:35]
	v_mfma_f32_16x16x32_bf16 v[24:27], v[230:233], v[198:201], v[24:27]
	v_mfma_f32_16x16x32_bf16 v[16:19], v[222:225], v[206:209], v[16:19]
	v_mfma_f32_16x16x32_bf16 v[8:11], v[230:233], v[206:209], v[8:11]
	v_mfma_f32_16x16x32_bf16 v[4:7], v[222:225], v[214:217], v[4:7]
	v_mfma_f32_16x16x32_bf16 v[0:3], v[230:233], v[214:217], v[0:3]
	s_setprio 0
	s_add_i32 s1, s1, 2
	v_lshl_add_u64 v[130:131], v[130:131], 0, s[86:87]
	s_cmp_gt_u32 s1, 11
	v_lshl_add_u64 v[132:133], v[132:133], 0, s[86:87]
	s_barrier
	s_cbranch_scc0 .LBB0_591
	s_mov_b64 s[4:5], 0x40780
	v_readfirstlane_b32 s1, v176
	v_lshl_add_u64 v[174:175], v[128:129], 0, s[4:5]
	s_mov_b32 m0, s1
	s_mov_b64 s[4:5], 0x60780
	v_readfirstlane_b32 s1, v177
	ds_read_b128 v[130:133], v135
	ds_read_b128 v[140:143], v135 offset:1024
	ds_read_b128 v[146:149], v135 offset:2048
	ds_read_b128 v[150:153], v135 offset:3072
	ds_read_b128 v[162:165], v134
	ds_read_b128 v[170:173], v134 offset:1024
	ds_read_b128 v[178:181], v134 offset:2048
	ds_read_b128 v[182:185], v134 offset:3072
	ds_read_b128 v[186:189], v134 offset:4096
	ds_read_b128 v[190:193], v134 offset:5120
	ds_read_b128 v[194:197], v134 offset:6144
	ds_read_b128 v[198:201], v134 offset:7168
	global_load_lds_dwordx4 v[174:175], off
	v_lshl_add_u64 v[128:129], v[128:129], 0, s[4:5]
	s_mov_b32 m0, s1
	s_nop 0
	global_load_lds_dwordx4 v[128:129], off
	s_barrier
	s_waitcnt lgkmcnt(0)
	s_setprio 1
	s_waitcnt lgkmcnt(0)
	v_mfma_f32_16x16x32_bf16 v[124:127], v[130:133], v[162:165], v[124:127]
	v_mfma_f32_16x16x32_bf16 v[120:123], v[146:149], v[162:165], v[120:123]
	v_mfma_f32_16x16x32_bf16 v[116:119], v[130:133], v[178:181], v[116:119]
	v_mfma_f32_16x16x32_bf16 v[112:115], v[146:149], v[178:181], v[112:115]
	v_mfma_f32_16x16x32_bf16 v[100:103], v[130:133], v[186:189], v[100:103]
	v_mfma_f32_16x16x32_bf16 v[96:99], v[146:149], v[186:189], v[96:99]
	v_mfma_f32_16x16x32_bf16 v[84:87], v[130:133], v[194:197], v[84:87]
	v_mfma_f32_16x16x32_bf16 v[124:127], v[140:143], v[170:173], v[124:127]
	v_mfma_f32_16x16x32_bf16 v[120:123], v[150:153], v[170:173], v[120:123]
	v_mfma_f32_16x16x32_bf16 v[116:119], v[140:143], v[182:185], v[116:119]
	v_mfma_f32_16x16x32_bf16 v[112:115], v[150:153], v[182:185], v[112:115]
	v_mfma_f32_16x16x32_bf16 v[100:103], v[140:143], v[190:193], v[100:103]
	v_mfma_f32_16x16x32_bf16 v[96:99], v[150:153], v[190:193], v[96:99]
	v_mfma_f32_16x16x32_bf16 v[84:87], v[140:143], v[198:201], v[84:87]
	v_mfma_f32_16x16x32_bf16 v[80:83], v[146:149], v[194:197], v[80:83]
	v_mfma_f32_16x16x32_bf16 v[80:83], v[150:153], v[198:201], v[80:83]
	s_setprio 0
	s_barrier
	ds_read_b128 v[174:177], v135 offset:16384
	ds_read_b128 v[202:205], v135 offset:17408
	ds_read_b128 v[206:209], v135 offset:18432
	ds_read_b128 v[210:213], v135 offset:19456
	s_barrier
	s_waitcnt lgkmcnt(0)
	s_setprio 1
	s_waitcnt lgkmcnt(0)
	v_mfma_f32_16x16x32_bf16 v[108:111], v[174:177], v[162:165], v[108:111]
	v_mfma_f32_16x16x32_bf16 v[104:107], v[206:209], v[162:165], v[104:107]
	v_mfma_f32_16x16x32_bf16 v[92:95], v[174:177], v[178:181], v[92:95]
	v_mfma_f32_16x16x32_bf16 v[76:79], v[174:177], v[186:189], v[76:79]
	v_mfma_f32_16x16x32_bf16 v[72:75], v[206:209], v[186:189], v[72:75]
	v_mfma_f32_16x16x32_bf16 v[68:71], v[174:177], v[194:197], v[68:71]
	v_mfma_f32_16x16x32_bf16 v[64:67], v[206:209], v[194:197], v[64:67]
	v_mfma_f32_16x16x32_bf16 v[108:111], v[202:205], v[170:173], v[108:111]
	v_mfma_f32_16x16x32_bf16 v[104:107], v[210:213], v[170:173], v[104:107]
	v_mfma_f32_16x16x32_bf16 v[92:95], v[202:205], v[182:185], v[92:95]
	v_mfma_f32_16x16x32_bf16 v[88:91], v[206:209], v[178:181], v[88:91]
	v_mfma_f32_16x16x32_bf16 v[76:79], v[202:205], v[190:193], v[76:79]
	v_mfma_f32_16x16x32_bf16 v[72:75], v[210:213], v[190:193], v[72:75]
	v_mfma_f32_16x16x32_bf16 v[68:71], v[202:205], v[198:201], v[68:71]
	v_mfma_f32_16x16x32_bf16 v[64:67], v[210:213], v[198:201], v[64:67]
	v_mfma_f32_16x16x32_bf16 v[88:91], v[210:213], v[182:185], v[88:91]
	s_setprio 0
	s_barrier
	ds_read_b128 v[162:165], v134 offset:16384
	ds_read_b128 v[170:173], v134 offset:17408
	ds_read_b128 v[178:181], v134 offset:18432
	ds_read_b128 v[182:185], v134 offset:19456
	ds_read_b128 v[186:189], v134 offset:20480
	ds_read_b128 v[190:193], v134 offset:21504
	ds_read_b128 v[194:197], v134 offset:22528
	ds_read_b128 v[198:201], v134 offset:23552
	s_waitcnt vmcnt(4)
	s_barrier
	s_waitcnt lgkmcnt(0)
	s_setprio 1
	s_waitcnt lgkmcnt(0)
	v_mfma_f32_16x16x32_bf16 v[36:39], v[130:133], v[186:189], v[36:39]
	v_mfma_f32_16x16x32_bf16 v[28:31], v[146:149], v[186:189], v[28:31]
	v_mfma_f32_16x16x32_bf16 v[20:23], v[130:133], v[194:197], v[20:23]
	v_mfma_f32_16x16x32_bf16 v[12:15], v[146:149], v[194:197], v[12:15]
	v_mfma_f32_16x16x32_bf16 v[60:63], v[130:133], v[162:165], v[60:63]
	v_mfma_f32_16x16x32_bf16 v[56:59], v[146:149], v[162:165], v[56:59]
	v_mfma_f32_16x16x32_bf16 v[52:55], v[130:133], v[178:181], v[52:55]
	v_mfma_f32_16x16x32_bf16 v[44:47], v[146:149], v[178:181], v[44:47]
	v_mfma_f32_16x16x32_bf16 v[36:39], v[140:143], v[190:193], v[36:39]
	v_mfma_f32_16x16x32_bf16 v[28:31], v[150:153], v[190:193], v[28:31]
	v_mfma_f32_16x16x32_bf16 v[20:23], v[140:143], v[198:201], v[20:23]
	v_mfma_f32_16x16x32_bf16 v[12:15], v[150:153], v[198:201], v[12:15]
	v_mfma_f32_16x16x32_bf16 v[214:217], v[140:143], v[170:173], v[60:63]
	v_mfma_f32_16x16x32_bf16 v[218:221], v[150:153], v[170:173], v[56:59]
	v_mfma_f32_16x16x32_bf16 v[222:225], v[140:143], v[182:185], v[52:55]
	v_mfma_f32_16x16x32_bf16 v[226:229], v[150:153], v[182:185], v[44:47]
	s_setprio 0
	s_setprio 1
	v_mfma_f32_16x16x32_bf16 v[8:11], v[206:209], v[186:189], v[8:11]
	v_mfma_f32_16x16x32_bf16 v[4:7], v[174:177], v[194:197], v[4:7]
	v_mfma_f32_16x16x32_bf16 v[0:3], v[206:209], v[194:197], v[0:3]
	v_mfma_f32_16x16x32_bf16 v[44:47], v[174:177], v[162:165], v[48:51]
	v_mfma_f32_16x16x32_bf16 v[40:43], v[206:209], v[162:165], v[40:43]
	v_mfma_f32_16x16x32_bf16 v[32:35], v[174:177], v[178:181], v[32:35]
	v_mfma_f32_16x16x32_bf16 v[24:27], v[206:209], v[178:181], v[24:27]
	v_mfma_f32_16x16x32_bf16 v[16:19], v[174:177], v[186:189], v[16:19]
	v_mfma_f32_16x16x32_bf16 v[8:11], v[210:213], v[190:193], v[8:11]
	v_mfma_f32_16x16x32_bf16 v[4:7], v[202:205], v[198:201], v[4:7]
	v_mfma_f32_16x16x32_bf16 v[0:3], v[210:213], v[198:201], v[0:3]
	v_mfma_f32_16x16x32_bf16 v[140:143], v[202:205], v[170:173], v[44:47]
	v_mfma_f32_16x16x32_bf16 v[146:149], v[210:213], v[170:173], v[40:43]
	v_mfma_f32_16x16x32_bf16 v[150:153], v[202:205], v[182:185], v[32:35]
	v_mfma_f32_16x16x32_bf16 v[162:165], v[210:213], v[182:185], v[24:27]
	v_mfma_f32_16x16x32_bf16 v[170:173], v[202:205], v[190:193], v[16:19]
	s_setprio 0
	s_barrier
	s_nop 0
	ds_read_b128 v[16:19], v145
	ds_read_b128 v[174:177], v145 offset:1024
	ds_read_b128 v[178:181], v145 offset:2048
	ds_read_b128 v[182:185], v145 offset:3072
	ds_read_b128 v[24:27], v144
	ds_read_b128 v[32:35], v144 offset:1024
	ds_read_b128 v[40:43], v144 offset:2048
	ds_read_b128 v[44:47], v144 offset:3072
	ds_read_b128 v[186:189], v144 offset:4096
	ds_read_b128 v[190:193], v144 offset:5120
	ds_read_b128 v[194:197], v144 offset:6144
	ds_read_b128 v[198:201], v144 offset:7168
	s_waitcnt vmcnt(2)
	s_barrier
	s_waitcnt lgkmcnt(0)
	s_setprio 1
	s_waitcnt lgkmcnt(0)
	v_mfma_f32_16x16x32_bf16 v[48:51], v[16:19], v[24:27], v[124:127]
	v_mfma_f32_16x16x32_bf16 v[128:131], v[174:177], v[32:35], v[48:51]
	v_mfma_f32_16x16x32_bf16 v[48:51], v[178:181], v[24:27], v[120:123]
	v_mfma_f32_16x16x32_bf16 v[132:135], v[182:185], v[32:35], v[48:51]
	v_mfma_f32_16x16x32_bf16 v[48:51], v[16:19], v[40:43], v[116:119]
	v_mfma_f32_16x16x32_bf16 v[124:127], v[174:177], v[44:47], v[48:51]
	v_mfma_f32_16x16x32_bf16 v[48:51], v[178:181], v[40:43], v[112:115]
	v_mfma_f32_16x16x32_bf16 v[120:123], v[182:185], v[44:47], v[48:51]
	v_mfma_f32_16x16x32_bf16 v[48:51], v[16:19], v[186:189], v[100:103]
	v_mfma_f32_16x16x32_bf16 v[112:115], v[174:177], v[190:193], v[48:51]
	v_mfma_f32_16x16x32_bf16 v[48:51], v[178:181], v[186:189], v[96:99]
	v_mfma_f32_16x16x32_bf16 v[116:119], v[182:185], v[190:193], v[48:51]
	v_mfma_f32_16x16x32_bf16 v[48:51], v[16:19], v[194:197], v[84:87]
	v_mfma_f32_16x16x32_bf16 v[100:103], v[174:177], v[198:201], v[48:51]
	v_mfma_f32_16x16x32_bf16 v[48:51], v[178:181], v[194:197], v[80:83]
	v_mfma_f32_16x16x32_bf16 v[96:99], v[182:185], v[198:201], v[48:51]
	s_setprio 0
	s_barrier
	ds_read_b128 v[80:83], v145 offset:16384
	ds_read_b128 v[202:205], v145 offset:17408
	ds_read_b128 v[206:209], v145 offset:18432
	ds_read_b128 v[210:213], v145 offset:19456
	s_waitcnt vmcnt(0)
	s_barrier
	s_waitcnt lgkmcnt(0)
	s_setprio 1
	s_waitcnt lgkmcnt(0)
	v_mfma_f32_16x16x32_bf16 v[48:51], v[80:83], v[24:27], v[108:111]
	v_mfma_f32_16x16x32_bf16 v[24:27], v[206:209], v[24:27], v[104:107]
	v_mfma_f32_16x16x32_bf16 v[60:63], v[210:213], v[32:35], v[24:27]
	v_mfma_f32_16x16x32_bf16 v[24:27], v[80:83], v[40:43], v[92:95]
	v_mfma_f32_16x16x32_bf16 v[52:55], v[202:205], v[44:47], v[24:27]
	v_mfma_f32_16x16x32_bf16 v[24:27], v[206:209], v[40:43], v[88:91]
	v_mfma_f32_16x16x32_bf16 v[56:59], v[202:205], v[32:35], v[48:51]
	v_mfma_f32_16x16x32_bf16 v[48:51], v[210:213], v[44:47], v[24:27]
	v_mfma_f32_16x16x32_bf16 v[24:27], v[80:83], v[186:189], v[76:79]
	v_mfma_f32_16x16x32_bf16 v[40:43], v[202:205], v[190:193], v[24:27]
	v_mfma_f32_16x16x32_bf16 v[24:27], v[206:209], v[186:189], v[72:75]
	v_mfma_f32_16x16x32_bf16 v[44:47], v[210:213], v[190:193], v[24:27]
	v_mfma_f32_16x16x32_bf16 v[24:27], v[80:83], v[194:197], v[68:71]
	v_mfma_f32_16x16x32_bf16 v[32:35], v[202:205], v[198:201], v[24:27]
	v_mfma_f32_16x16x32_bf16 v[24:27], v[206:209], v[194:197], v[64:67]
	v_mfma_f32_16x16x32_bf16 v[24:27], v[210:213], v[198:201], v[24:27]
	s_setprio 0
	s_barrier
	ds_read_b128 v[88:91], v144 offset:16384
	ds_read_b128 v[186:189], v144 offset:17408
	ds_read_b128 v[190:193], v144 offset:18432
	ds_read_b128 v[194:197], v144 offset:19456
	ds_read_b128 v[198:201], v144 offset:20480
	ds_read_b128 v[230:233], v144 offset:21504
	ds_read_b128 v[234:237], v144 offset:22528
	ds_read_b128 v[238:241], v144 offset:23552
	s_barrier
	s_waitcnt lgkmcnt(0)
	s_setprio 1
	s_waitcnt lgkmcnt(0)
	v_mfma_f32_16x16x32_bf16 v[64:67], v[16:19], v[88:91], v[214:217]
	v_mfma_f32_16x16x32_bf16 v[104:107], v[174:177], v[186:189], v[64:67]
	v_mfma_f32_16x16x32_bf16 v[64:67], v[178:181], v[88:91], v[218:221]
	v_mfma_f32_16x16x32_bf16 v[108:111], v[182:185], v[186:189], v[64:67]
	v_mfma_f32_16x16x32_bf16 v[64:67], v[16:19], v[190:193], v[222:225]
	v_mfma_f32_16x16x32_bf16 v[92:95], v[174:177], v[194:197], v[64:67]
	v_mfma_f32_16x16x32_bf16 v[64:67], v[178:181], v[190:193], v[226:229]
	v_mfma_f32_16x16x32_bf16 v[36:39], v[16:19], v[198:201], v[36:39]
	v_mfma_f32_16x16x32_bf16 v[28:31], v[178:181], v[198:201], v[28:31]
	v_mfma_f32_16x16x32_bf16 v[16:19], v[16:19], v[234:237], v[20:23]
	v_mfma_f32_16x16x32_bf16 v[12:15], v[178:181], v[234:237], v[12:15]
	v_mfma_f32_16x16x32_bf16 v[84:87], v[182:185], v[194:197], v[64:67]
	v_mfma_f32_16x16x32_bf16 v[72:75], v[174:177], v[230:233], v[36:39]
	v_mfma_f32_16x16x32_bf16 v[76:79], v[182:185], v[230:233], v[28:31]
	v_mfma_f32_16x16x32_bf16 v[68:71], v[174:177], v[238:241], v[16:19]
	v_mfma_f32_16x16x32_bf16 v[64:67], v[182:185], v[238:241], v[12:15]
	s_setprio 0
	s_setprio 1
	v_mfma_f32_16x16x32_bf16 v[12:15], v[80:83], v[88:91], v[140:143]
	v_mfma_f32_16x16x32_bf16 v[36:39], v[202:205], v[186:189], v[12:15]
	v_mfma_f32_16x16x32_bf16 v[12:15], v[206:209], v[88:91], v[146:149]
	v_mfma_f32_16x16x32_bf16 v[28:31], v[210:213], v[186:189], v[12:15]
	v_mfma_f32_16x16x32_bf16 v[12:15], v[80:83], v[190:193], v[150:153]
	v_mfma_f32_16x16x32_bf16 v[20:23], v[202:205], v[194:197], v[12:15]
	v_mfma_f32_16x16x32_bf16 v[12:15], v[206:209], v[190:193], v[162:165]
	v_mfma_f32_16x16x32_bf16 v[16:19], v[210:213], v[194:197], v[12:15]
	v_mfma_f32_16x16x32_bf16 v[12:15], v[80:83], v[198:201], v[170:173]
	v_mfma_f32_16x16x32_bf16 v[8:11], v[206:209], v[198:201], v[8:11]
	v_mfma_f32_16x16x32_bf16 v[4:7], v[80:83], v[234:237], v[4:7]
	v_mfma_f32_16x16x32_bf16 v[0:3], v[206:209], v[234:237], v[0:3]
	v_mfma_f32_16x16x32_bf16 v[12:15], v[202:205], v[230:233], v[12:15]
	v_mfma_f32_16x16x32_bf16 v[8:11], v[210:213], v[230:233], v[8:11]
	v_mfma_f32_16x16x32_bf16 v[4:7], v[202:205], v[238:241], v[4:7]
	v_mfma_f32_16x16x32_bf16 v[0:3], v[210:213], v[238:241], v[0:3]
	s_setprio 0
	s_movk_i32 s1, 0x100
	v_cmp_gt_u32_e32 vcc, s1, v139
	s_barrier
	s_and_saveexec_b64 s[4:5], vcc
	s_cbranch_execz .LBB0_587
	s_barrier
	s_branch .LBB0_587

.LBB0_663:
	ds_read_b128 v[140:143], v145
	ds_read_b128 v[178:181], v145 offset:2048
	ds_read_b128 v[162:165], v145 offset:1024
	ds_read_b128 v[182:185], v145 offset:3072
	v_add_u32_e32 v176, 0x4000, v147
	v_lshl_add_u64 v[234:235], v[132:133], 0, v[136:137]
	v_readfirstlane_b32 s4, v176
	v_add_u32_e32 v177, 0x6000, v147
	v_lshl_add_u64 v[218:219], v[234:235], 0, s[76:77]
	s_mov_b32 m0, s4
	v_readfirstlane_b32 s4, v177
	ds_read_b128 v[186:189], v144
	ds_read_b128 v[194:197], v144 offset:2048
	ds_read_b128 v[202:205], v144 offset:4096
	ds_read_b128 v[210:213], v144 offset:6144
	ds_read_b128 v[190:193], v144 offset:1024
	ds_read_b128 v[198:201], v144 offset:3072
	ds_read_b128 v[206:209], v144 offset:5120
	ds_read_b128 v[214:217], v144 offset:7168
	global_load_lds_dwordx4 v[218:219], off
	v_lshl_add_u64 v[218:219], v[234:235], 0, s[16:17]
	s_mov_b32 m0, s4
	s_nop 0
	global_load_lds_dwordx4 v[218:219], off
	s_waitcnt lgkmcnt(8)
	s_barrier
	s_waitcnt lgkmcnt(4)
	s_setprio 1
	s_waitcnt lgkmcnt(4)
	v_mfma_f32_16x16x32_bf16 v[124:127], v[140:143], v[186:189], v[124:127]
	v_mfma_f32_16x16x32_bf16 v[120:123], v[178:181], v[186:189], v[120:123]
	v_mfma_f32_16x16x32_bf16 v[116:119], v[140:143], v[194:197], v[116:119]
	v_mfma_f32_16x16x32_bf16 v[112:115], v[178:181], v[194:197], v[112:115]
	v_mfma_f32_16x16x32_bf16 v[100:103], v[140:143], v[202:205], v[100:103]
	v_mfma_f32_16x16x32_bf16 v[96:99], v[178:181], v[202:205], v[96:99]
	v_mfma_f32_16x16x32_bf16 v[84:87], v[140:143], v[210:213], v[84:87]
	v_mfma_f32_16x16x32_bf16 v[80:83], v[178:181], v[210:213], v[80:83]
	s_waitcnt lgkmcnt(0)
	v_mfma_f32_16x16x32_bf16 v[124:127], v[162:165], v[190:193], v[124:127]
	v_mfma_f32_16x16x32_bf16 v[120:123], v[182:185], v[190:193], v[120:123]
	v_mfma_f32_16x16x32_bf16 v[116:119], v[162:165], v[198:201], v[116:119]
	v_mfma_f32_16x16x32_bf16 v[112:115], v[182:185], v[198:201], v[112:115]
	v_mfma_f32_16x16x32_bf16 v[100:103], v[162:165], v[206:209], v[100:103]
	v_mfma_f32_16x16x32_bf16 v[96:99], v[182:185], v[206:209], v[96:99]
	v_mfma_f32_16x16x32_bf16 v[84:87], v[162:165], v[214:217], v[84:87]
	v_mfma_f32_16x16x32_bf16 v[80:83], v[182:185], v[214:217], v[80:83]
	s_setprio 0
	s_barrier
	v_lshl_add_u64 v[236:237], v[130:131], 0, v[136:137]
	s_mov_b64 s[4:5], 0x2600100
	v_lshl_add_u64 v[238:239], v[236:237], 0, s[4:5]
	v_readfirstlane_b32 s4, v148
	s_mov_b32 m0, s4
	s_mov_b64 s[4:5], 0x2620100
	ds_read_b128 v[218:221], v145 offset:16384
	ds_read_b128 v[226:229], v145 offset:18432
	ds_read_b128 v[222:225], v145 offset:17408
	ds_read_b128 v[230:233], v145 offset:19456
	global_load_lds_dwordx4 v[238:239], off
	v_lshl_add_u64 v[238:239], v[236:237], 0, s[4:5]
	v_readfirstlane_b32 s4, v149
	s_mov_b32 m0, s4
	s_nop 0
	global_load_lds_dwordx4 v[238:239], off
	s_barrier
	s_waitcnt lgkmcnt(2)
	s_setprio 1
	s_waitcnt lgkmcnt(2)
	v_mfma_f32_16x16x32_bf16 v[108:111], v[218:221], v[186:189], v[108:111]
	v_mfma_f32_16x16x32_bf16 v[104:107], v[226:229], v[186:189], v[104:107]
	v_mfma_f32_16x16x32_bf16 v[92:95], v[218:221], v[194:197], v[92:95]
	v_mfma_f32_16x16x32_bf16 v[88:91], v[226:229], v[194:197], v[88:91]
	v_mfma_f32_16x16x32_bf16 v[76:79], v[218:221], v[202:205], v[76:79]
	v_mfma_f32_16x16x32_bf16 v[72:75], v[226:229], v[202:205], v[72:75]
	v_mfma_f32_16x16x32_bf16 v[68:71], v[218:221], v[210:213], v[68:71]
	v_mfma_f32_16x16x32_bf16 v[64:67], v[226:229], v[210:213], v[64:67]
	s_waitcnt lgkmcnt(0)
	v_mfma_f32_16x16x32_bf16 v[108:111], v[222:225], v[190:193], v[108:111]
	v_mfma_f32_16x16x32_bf16 v[104:107], v[230:233], v[190:193], v[104:107]
	v_mfma_f32_16x16x32_bf16 v[92:95], v[222:225], v[198:201], v[92:95]
	v_mfma_f32_16x16x32_bf16 v[88:91], v[230:233], v[198:201], v[88:91]
	v_mfma_f32_16x16x32_bf16 v[76:79], v[222:225], v[206:209], v[76:79]
	v_mfma_f32_16x16x32_bf16 v[72:75], v[230:233], v[206:209], v[72:75]
	v_mfma_f32_16x16x32_bf16 v[68:71], v[222:225], v[214:217], v[68:71]
	v_mfma_f32_16x16x32_bf16 v[64:67], v[230:233], v[214:217], v[64:67]
	s_setprio 0
	v_readfirstlane_b32 s4, v146
	v_lshl_add_u64 v[238:239], v[234:235], 0, s[88:89]
	s_mov_b32 m0, s4
	v_readfirstlane_b32 s4, v150
	s_barrier
	ds_read_b128 v[186:189], v144 offset:16384
	ds_read_b128 v[194:197], v144 offset:18432
	ds_read_b128 v[202:205], v144 offset:20480
	ds_read_b128 v[210:213], v144 offset:22528
	ds_read_b128 v[190:193], v144 offset:17408
	ds_read_b128 v[198:201], v144 offset:19456
	ds_read_b128 v[206:209], v144 offset:21504
	ds_read_b128 v[214:217], v144 offset:23552
	global_load_lds_dwordx4 v[238:239], off
	v_lshl_add_u64 v[238:239], v[234:235], 0, s[90:91]
	s_mov_b32 m0, s4
	s_nop 0
	global_load_lds_dwordx4 v[238:239], off
	s_barrier
	s_waitcnt lgkmcnt(4)
	s_setprio 1
	s_waitcnt lgkmcnt(4)
	v_mfma_f32_16x16x32_bf16 v[60:63], v[140:143], v[186:189], v[60:63]
	v_mfma_f32_16x16x32_bf16 v[56:59], v[178:181], v[186:189], v[56:59]
	v_mfma_f32_16x16x32_bf16 v[52:55], v[140:143], v[194:197], v[52:55]
	v_mfma_f32_16x16x32_bf16 v[44:47], v[178:181], v[194:197], v[44:47]
	v_mfma_f32_16x16x32_bf16 v[36:39], v[140:143], v[202:205], v[36:39]
	v_mfma_f32_16x16x32_bf16 v[28:31], v[178:181], v[202:205], v[28:31]
	v_mfma_f32_16x16x32_bf16 v[20:23], v[140:143], v[210:213], v[20:23]
	v_mfma_f32_16x16x32_bf16 v[12:15], v[178:181], v[210:213], v[12:15]
	s_waitcnt lgkmcnt(0)
	v_mfma_f32_16x16x32_bf16 v[60:63], v[162:165], v[190:193], v[60:63]
	v_mfma_f32_16x16x32_bf16 v[56:59], v[182:185], v[190:193], v[56:59]
	v_mfma_f32_16x16x32_bf16 v[52:55], v[162:165], v[198:201], v[52:55]
	v_mfma_f32_16x16x32_bf16 v[44:47], v[182:185], v[198:201], v[44:47]
	v_mfma_f32_16x16x32_bf16 v[36:39], v[162:165], v[206:209], v[36:39]
	v_mfma_f32_16x16x32_bf16 v[28:31], v[182:185], v[206:209], v[28:31]
	v_mfma_f32_16x16x32_bf16 v[20:23], v[162:165], v[214:217], v[20:23]
	v_mfma_f32_16x16x32_bf16 v[12:15], v[182:185], v[214:217], v[12:15]
	s_setprio 0
	s_barrier
	s_mov_b64 s[4:5], 0x2640100
	v_lshl_add_u64 v[140:141], v[236:237], 0, s[4:5]
	v_readfirstlane_b32 s4, v151
	s_mov_b32 m0, s4
	s_mov_b64 s[4:5], 0x2660100
	global_load_lds_dwordx4 v[140:141], off
	v_lshl_add_u64 v[140:141], v[236:237], 0, s[4:5]
	v_readfirstlane_b32 s4, v152
	s_mov_b32 m0, s4
	s_nop 0
	global_load_lds_dwordx4 v[140:141], off
	s_waitcnt vmcnt(6)
	s_barrier
	s_setprio 1
	v_mfma_f32_16x16x32_bf16 v[48:51], v[218:221], v[186:189], v[48:51]
	v_mfma_f32_16x16x32_bf16 v[40:43], v[226:229], v[186:189], v[40:43]
	v_mfma_f32_16x16x32_bf16 v[32:35], v[218:221], v[194:197], v[32:35]
	v_mfma_f32_16x16x32_bf16 v[24:27], v[226:229], v[194:197], v[24:27]
	v_mfma_f32_16x16x32_bf16 v[16:19], v[218:221], v[202:205], v[16:19]
	v_mfma_f32_16x16x32_bf16 v[8:11], v[226:229], v[202:205], v[8:11]
	v_mfma_f32_16x16x32_bf16 v[4:7], v[218:221], v[210:213], v[4:7]
	v_mfma_f32_16x16x32_bf16 v[0:3], v[226:229], v[210:213], v[0:3]
	v_mfma_f32_16x16x32_bf16 v[48:51], v[222:225], v[190:193], v[48:51]
	v_mfma_f32_16x16x32_bf16 v[40:43], v[230:233], v[190:193], v[40:43]
	v_mfma_f32_16x16x32_bf16 v[32:35], v[222:225], v[198:201], v[32:35]
	v_mfma_f32_16x16x32_bf16 v[24:27], v[230:233], v[198:201], v[24:27]
	v_mfma_f32_16x16x32_bf16 v[16:19], v[222:225], v[206:209], v[16:19]
	v_mfma_f32_16x16x32_bf16 v[8:11], v[230:233], v[206:209], v[8:11]
	v_mfma_f32_16x16x32_bf16 v[4:7], v[222:225], v[214:217], v[4:7]
	v_mfma_f32_16x16x32_bf16 v[0:3], v[230:233], v[214:217], v[0:3]
	s_setprio 0
	s_barrier
	ds_read_b128 v[140:143], v139
	ds_read_b128 v[178:181], v139 offset:2048
	ds_read_b128 v[162:165], v139 offset:1024
	ds_read_b128 v[182:185], v139 offset:3072
	v_readfirstlane_b32 s4, v153
	v_lshl_add_u64 v[218:219], v[234:235], 0, s[94:95]
	s_mov_b32 m0, s4
	v_readfirstlane_b32 s4, v170
	ds_read_b128 v[186:189], v135
	ds_read_b128 v[194:197], v135 offset:2048
	ds_read_b128 v[202:205], v135 offset:4096
	ds_read_b128 v[210:213], v135 offset:6144
	ds_read_b128 v[190:193], v135 offset:1024
	ds_read_b128 v[198:201], v135 offset:3072
	ds_read_b128 v[206:209], v135 offset:5120
	ds_read_b128 v[214:217], v135 offset:7168
	global_load_lds_dwordx4 v[218:219], off
	v_lshl_add_u64 v[218:219], v[234:235], 0, s[78:79]
	s_mov_b32 m0, s4
	s_nop 0
	global_load_lds_dwordx4 v[218:219], off
	s_waitcnt lgkmcnt(8)
	s_barrier
	s_waitcnt lgkmcnt(4)
	s_setprio 1
	s_waitcnt lgkmcnt(4)
	v_mfma_f32_16x16x32_bf16 v[124:127], v[140:143], v[186:189], v[124:127]
	v_mfma_f32_16x16x32_bf16 v[120:123], v[178:181], v[186:189], v[120:123]
	v_mfma_f32_16x16x32_bf16 v[116:119], v[140:143], v[194:197], v[116:119]
	v_mfma_f32_16x16x32_bf16 v[112:115], v[178:181], v[194:197], v[112:115]
	v_mfma_f32_16x16x32_bf16 v[100:103], v[140:143], v[202:205], v[100:103]
	v_mfma_f32_16x16x32_bf16 v[96:99], v[178:181], v[202:205], v[96:99]
	v_mfma_f32_16x16x32_bf16 v[84:87], v[140:143], v[210:213], v[84:87]
	v_mfma_f32_16x16x32_bf16 v[80:83], v[178:181], v[210:213], v[80:83]
	s_waitcnt lgkmcnt(0)
	v_mfma_f32_16x16x32_bf16 v[124:127], v[162:165], v[190:193], v[124:127]
	v_mfma_f32_16x16x32_bf16 v[120:123], v[182:185], v[190:193], v[120:123]
	v_mfma_f32_16x16x32_bf16 v[116:119], v[162:165], v[198:201], v[116:119]
	v_mfma_f32_16x16x32_bf16 v[112:115], v[182:185], v[198:201], v[112:115]
	v_mfma_f32_16x16x32_bf16 v[100:103], v[162:165], v[206:209], v[100:103]
	v_mfma_f32_16x16x32_bf16 v[96:99], v[182:185], v[206:209], v[96:99]
	v_mfma_f32_16x16x32_bf16 v[84:87], v[162:165], v[214:217], v[84:87]
	v_mfma_f32_16x16x32_bf16 v[80:83], v[182:185], v[214:217], v[80:83]
	s_setprio 0
	s_barrier
	s_mov_b64 s[4:5], 0x2600180
	v_lshl_add_u64 v[238:239], v[236:237], 0, s[4:5]
	v_readfirstlane_b32 s4, v171
	s_mov_b32 m0, s4
	s_mov_b64 s[4:5], 0x2620180
	ds_read_b128 v[218:221], v139 offset:16384
	ds_read_b128 v[226:229], v139 offset:18432
	ds_read_b128 v[222:225], v139 offset:17408
	ds_read_b128 v[230:233], v139 offset:19456
	global_load_lds_dwordx4 v[238:239], off
	v_lshl_add_u64 v[238:239], v[236:237], 0, s[4:5]
	v_readfirstlane_b32 s4, v172
	s_mov_b32 m0, s4
	s_nop 0
	global_load_lds_dwordx4 v[238:239], off
	s_barrier
	s_waitcnt lgkmcnt(2)
	s_setprio 1
	s_waitcnt lgkmcnt(2)
	v_mfma_f32_16x16x32_bf16 v[108:111], v[218:221], v[186:189], v[108:111]
	v_mfma_f32_16x16x32_bf16 v[104:107], v[226:229], v[186:189], v[104:107]
	v_mfma_f32_16x16x32_bf16 v[92:95], v[218:221], v[194:197], v[92:95]
	v_mfma_f32_16x16x32_bf16 v[88:91], v[226:229], v[194:197], v[88:91]
	v_mfma_f32_16x16x32_bf16 v[76:79], v[218:221], v[202:205], v[76:79]
	v_mfma_f32_16x16x32_bf16 v[72:75], v[226:229], v[202:205], v[72:75]
	v_mfma_f32_16x16x32_bf16 v[68:71], v[218:221], v[210:213], v[68:71]
	v_mfma_f32_16x16x32_bf16 v[64:67], v[226:229], v[210:213], v[64:67]
	s_waitcnt lgkmcnt(0)
	v_mfma_f32_16x16x32_bf16 v[108:111], v[222:225], v[190:193], v[108:111]
	v_mfma_f32_16x16x32_bf16 v[104:107], v[230:233], v[190:193], v[104:107]
	v_mfma_f32_16x16x32_bf16 v[92:95], v[222:225], v[198:201], v[92:95]
	v_mfma_f32_16x16x32_bf16 v[88:91], v[230:233], v[198:201], v[88:91]
	v_mfma_f32_16x16x32_bf16 v[76:79], v[222:225], v[206:209], v[76:79]
	v_mfma_f32_16x16x32_bf16 v[72:75], v[230:233], v[206:209], v[72:75]
	v_mfma_f32_16x16x32_bf16 v[68:71], v[222:225], v[214:217], v[68:71]
	v_mfma_f32_16x16x32_bf16 v[64:67], v[230:233], v[214:217], v[64:67]
	s_setprio 0
	v_readfirstlane_b32 s4, v147
	v_lshl_add_u64 v[238:239], v[234:235], 0, s[24:25]
	s_mov_b32 m0, s4
	v_readfirstlane_b32 s4, v173
	s_barrier
	ds_read_b128 v[186:189], v135 offset:16384
	ds_read_b128 v[194:197], v135 offset:18432
	ds_read_b128 v[202:205], v135 offset:20480
	ds_read_b128 v[210:213], v135 offset:22528
	ds_read_b128 v[190:193], v135 offset:17408
	ds_read_b128 v[198:201], v135 offset:19456
	ds_read_b128 v[206:209], v135 offset:21504
	ds_read_b128 v[214:217], v135 offset:23552
	global_load_lds_dwordx4 v[238:239], off
	v_lshl_add_u64 v[234:235], v[234:235], 0, s[28:29]
	s_mov_b32 m0, s4
	s_nop 0
	global_load_lds_dwordx4 v[234:235], off
	s_barrier
	s_waitcnt lgkmcnt(4)
	s_setprio 1
	s_waitcnt lgkmcnt(4)
	v_mfma_f32_16x16x32_bf16 v[60:63], v[140:143], v[186:189], v[60:63]
	v_mfma_f32_16x16x32_bf16 v[56:59], v[178:181], v[186:189], v[56:59]
	v_mfma_f32_16x16x32_bf16 v[52:55], v[140:143], v[194:197], v[52:55]
	v_mfma_f32_16x16x32_bf16 v[44:47], v[178:181], v[194:197], v[44:47]
	v_mfma_f32_16x16x32_bf16 v[36:39], v[140:143], v[202:205], v[36:39]
	v_mfma_f32_16x16x32_bf16 v[28:31], v[178:181], v[202:205], v[28:31]
	v_mfma_f32_16x16x32_bf16 v[20:23], v[140:143], v[210:213], v[20:23]
	v_mfma_f32_16x16x32_bf16 v[12:15], v[178:181], v[210:213], v[12:15]
	s_waitcnt lgkmcnt(0)
	v_mfma_f32_16x16x32_bf16 v[60:63], v[162:165], v[190:193], v[60:63]
	v_mfma_f32_16x16x32_bf16 v[56:59], v[182:185], v[190:193], v[56:59]
	v_mfma_f32_16x16x32_bf16 v[52:55], v[162:165], v[198:201], v[52:55]
	v_mfma_f32_16x16x32_bf16 v[44:47], v[182:185], v[198:201], v[44:47]
	v_mfma_f32_16x16x32_bf16 v[36:39], v[162:165], v[206:209], v[36:39]
	v_mfma_f32_16x16x32_bf16 v[28:31], v[182:185], v[206:209], v[28:31]
	v_mfma_f32_16x16x32_bf16 v[20:23], v[162:165], v[214:217], v[20:23]
	v_mfma_f32_16x16x32_bf16 v[12:15], v[182:185], v[214:217], v[12:15]
	s_setprio 0
	s_barrier
	s_mov_b64 s[4:5], 0x2640180
	v_lshl_add_u64 v[140:141], v[236:237], 0, s[4:5]
	v_readfirstlane_b32 s4, v174
	s_mov_b32 m0, s4
	s_mov_b64 s[4:5], 0x2660180
	global_load_lds_dwordx4 v[140:141], off
	v_lshl_add_u64 v[140:141], v[236:237], 0, s[4:5]
	v_readfirstlane_b32 s4, v175
	s_mov_b32 m0, s4
	s_nop 0
	global_load_lds_dwordx4 v[140:141], off
	s_waitcnt vmcnt(6)
	s_barrier
	s_setprio 1
	v_mfma_f32_16x16x32_bf16 v[48:51], v[218:221], v[186:189], v[48:51]
	v_mfma_f32_16x16x32_bf16 v[40:43], v[226:229], v[186:189], v[40:43]
	v_mfma_f32_16x16x32_bf16 v[32:35], v[218:221], v[194:197], v[32:35]
	v_mfma_f32_16x16x32_bf16 v[24:27], v[226:229], v[194:197], v[24:27]
	v_mfma_f32_16x16x32_bf16 v[16:19], v[218:221], v[202:205], v[16:19]
	v_mfma_f32_16x16x32_bf16 v[8:11], v[226:229], v[202:205], v[8:11]
	v_mfma_f32_16x16x32_bf16 v[4:7], v[218:221], v[210:213], v[4:7]
	v_mfma_f32_16x16x32_bf16 v[0:3], v[226:229], v[210:213], v[0:3]
	v_mfma_f32_16x16x32_bf16 v[48:51], v[222:225], v[190:193], v[48:51]
	v_mfma_f32_16x16x32_bf16 v[40:43], v[230:233], v[190:193], v[40:43]
	v_mfma_f32_16x16x32_bf16 v[32:35], v[222:225], v[198:201], v[32:35]
	v_mfma_f32_16x16x32_bf16 v[24:27], v[230:233], v[198:201], v[24:27]
	v_mfma_f32_16x16x32_bf16 v[16:19], v[222:225], v[206:209], v[16:19]
	v_mfma_f32_16x16x32_bf16 v[8:11], v[230:233], v[206:209], v[8:11]
	v_mfma_f32_16x16x32_bf16 v[4:7], v[222:225], v[214:217], v[4:7]
	v_mfma_f32_16x16x32_bf16 v[0:3], v[230:233], v[214:217], v[0:3]
	s_setprio 0
	s_add_i32 s1, s1, 2
	v_lshl_add_u64 v[130:131], v[130:131], 0, s[86:87]
	s_cmp_gt_u32 s1, 11
	v_lshl_add_u64 v[132:133], v[132:133], 0, s[86:87]
	s_barrier
	s_cbranch_scc0 .LBB0_663
	s_mov_b64 s[4:5], 0x40780
	v_readfirstlane_b32 s1, v176
	v_lshl_add_u64 v[174:175], v[128:129], 0, s[4:5]
	s_mov_b32 m0, s1
	s_mov_b64 s[4:5], 0x60780
	v_readfirstlane_b32 s1, v177
	ds_read_b128 v[130:133], v145
	ds_read_b128 v[140:143], v145 offset:1024
	ds_read_b128 v[146:149], v145 offset:2048
	ds_read_b128 v[150:153], v145 offset:3072
	ds_read_b128 v[162:165], v144
	ds_read_b128 v[170:173], v144 offset:1024
	ds_read_b128 v[178:181], v144 offset:2048
	ds_read_b128 v[182:185], v144 offset:3072
	ds_read_b128 v[186:189], v144 offset:4096
	ds_read_b128 v[190:193], v144 offset:5120
	ds_read_b128 v[194:197], v144 offset:6144
	ds_read_b128 v[198:201], v144 offset:7168
	global_load_lds_dwordx4 v[174:175], off
	v_lshl_add_u64 v[128:129], v[128:129], 0, s[4:5]
	s_mov_b32 m0, s1
	s_nop 0
	global_load_lds_dwordx4 v[128:129], off
	s_barrier
	s_waitcnt lgkmcnt(0)
	s_setprio 1
	s_waitcnt lgkmcnt(0)
	v_mfma_f32_16x16x32_bf16 v[124:127], v[130:133], v[162:165], v[124:127]
	v_mfma_f32_16x16x32_bf16 v[116:119], v[130:133], v[178:181], v[116:119]
	v_mfma_f32_16x16x32_bf16 v[100:103], v[130:133], v[186:189], v[100:103]
	v_mfma_f32_16x16x32_bf16 v[84:87], v[130:133], v[194:197], v[84:87]
	v_mfma_f32_16x16x32_bf16 v[124:127], v[140:143], v[170:173], v[124:127]
	v_mfma_f32_16x16x32_bf16 v[120:123], v[146:149], v[162:165], v[120:123]
	v_mfma_f32_16x16x32_bf16 v[116:119], v[140:143], v[182:185], v[116:119]
	v_mfma_f32_16x16x32_bf16 v[112:115], v[146:149], v[178:181], v[112:115]
	v_mfma_f32_16x16x32_bf16 v[100:103], v[140:143], v[190:193], v[100:103]
	v_mfma_f32_16x16x32_bf16 v[96:99], v[146:149], v[186:189], v[96:99]
	v_mfma_f32_16x16x32_bf16 v[84:87], v[140:143], v[198:201], v[84:87]
	v_mfma_f32_16x16x32_bf16 v[80:83], v[146:149], v[194:197], v[80:83]
	v_mfma_f32_16x16x32_bf16 v[174:177], v[150:153], v[170:173], v[120:123]
	v_mfma_f32_16x16x32_bf16 v[202:205], v[150:153], v[182:185], v[112:115]
	v_mfma_f32_16x16x32_bf16 v[206:209], v[150:153], v[190:193], v[96:99]
	v_mfma_f32_16x16x32_bf16 v[210:213], v[150:153], v[198:201], v[80:83]
	s_setprio 0
	s_barrier
	s_nop 1
	ds_read_b128 v[80:83], v145 offset:16384
	ds_read_b128 v[96:99], v145 offset:17408
	ds_read_b128 v[112:115], v145 offset:18432
	ds_read_b128 v[120:123], v145 offset:19456
	s_barrier
	s_waitcnt lgkmcnt(0)
	s_setprio 1
	s_waitcnt lgkmcnt(0)
	v_mfma_f32_16x16x32_bf16 v[108:111], v[80:83], v[162:165], v[108:111]
	v_mfma_f32_16x16x32_bf16 v[92:95], v[80:83], v[178:181], v[92:95]
	v_mfma_f32_16x16x32_bf16 v[76:79], v[80:83], v[186:189], v[76:79]
	v_mfma_f32_16x16x32_bf16 v[68:71], v[80:83], v[194:197], v[68:71]
	v_mfma_f32_16x16x32_bf16 v[108:111], v[96:99], v[170:173], v[108:111]
	v_mfma_f32_16x16x32_bf16 v[104:107], v[112:115], v[162:165], v[104:107]
	v_mfma_f32_16x16x32_bf16 v[92:95], v[96:99], v[182:185], v[92:95]
	v_mfma_f32_16x16x32_bf16 v[88:91], v[112:115], v[178:181], v[88:91]
	v_mfma_f32_16x16x32_bf16 v[76:79], v[96:99], v[190:193], v[76:79]
	v_mfma_f32_16x16x32_bf16 v[72:75], v[112:115], v[186:189], v[72:75]
	v_mfma_f32_16x16x32_bf16 v[68:71], v[96:99], v[198:201], v[68:71]
	v_mfma_f32_16x16x32_bf16 v[64:67], v[112:115], v[194:197], v[64:67]
	v_mfma_f32_16x16x32_bf16 v[162:165], v[120:123], v[170:173], v[104:107]
	v_mfma_f32_16x16x32_bf16 v[170:173], v[120:123], v[182:185], v[88:91]
	v_mfma_f32_16x16x32_bf16 v[178:181], v[120:123], v[190:193], v[72:75]
	v_mfma_f32_16x16x32_bf16 v[182:185], v[120:123], v[198:201], v[64:67]
	s_setprio 0
	s_barrier
	s_nop 1
	ds_read_b128 v[64:67], v144 offset:16384
	ds_read_b128 v[72:75], v144 offset:17408
	ds_read_b128 v[88:91], v144 offset:18432
	ds_read_b128 v[104:107], v144 offset:19456
	ds_read_b128 v[186:189], v144 offset:20480
	ds_read_b128 v[190:193], v144 offset:21504
	ds_read_b128 v[194:197], v144 offset:22528
	ds_read_b128 v[198:201], v144 offset:23552
	s_waitcnt vmcnt(4)
	s_barrier
	s_waitcnt lgkmcnt(0)
	s_setprio 1
	s_waitcnt lgkmcnt(0)
	v_mfma_f32_16x16x32_bf16 v[60:63], v[130:133], v[64:67], v[60:63]
	v_mfma_f32_16x16x32_bf16 v[56:59], v[146:149], v[64:67], v[56:59]
	v_mfma_f32_16x16x32_bf16 v[52:55], v[130:133], v[88:91], v[52:55]
	v_mfma_f32_16x16x32_bf16 v[36:39], v[130:133], v[186:189], v[36:39]
	v_mfma_f32_16x16x32_bf16 v[20:23], v[130:133], v[194:197], v[20:23]
	v_mfma_f32_16x16x32_bf16 v[60:63], v[140:143], v[72:75], v[60:63]
	v_mfma_f32_16x16x32_bf16 v[56:59], v[150:153], v[72:75], v[56:59]
	v_mfma_f32_16x16x32_bf16 v[52:55], v[140:143], v[104:107], v[52:55]
	v_mfma_f32_16x16x32_bf16 v[44:47], v[146:149], v[88:91], v[44:47]
	v_mfma_f32_16x16x32_bf16 v[36:39], v[140:143], v[190:193], v[36:39]
	v_mfma_f32_16x16x32_bf16 v[28:31], v[146:149], v[186:189], v[28:31]
	v_mfma_f32_16x16x32_bf16 v[20:23], v[140:143], v[198:201], v[20:23]
	v_mfma_f32_16x16x32_bf16 v[12:15], v[146:149], v[194:197], v[12:15]
	v_mfma_f32_16x16x32_bf16 v[214:217], v[150:153], v[104:107], v[44:47]
	v_mfma_f32_16x16x32_bf16 v[218:221], v[150:153], v[190:193], v[28:31]
	v_mfma_f32_16x16x32_bf16 v[128:131], v[150:153], v[198:201], v[12:15]
	s_setprio 0
	s_setprio 1
	v_mfma_f32_16x16x32_bf16 v[12:15], v[80:83], v[64:67], v[48:51]
	v_mfma_f32_16x16x32_bf16 v[140:143], v[96:99], v[72:75], v[12:15]
	v_mfma_f32_16x16x32_bf16 v[12:15], v[112:115], v[64:67], v[40:43]
	v_mfma_f32_16x16x32_bf16 v[40:43], v[120:123], v[72:75], v[12:15]
	v_mfma_f32_16x16x32_bf16 v[12:15], v[80:83], v[88:91], v[32:35]
	v_mfma_f32_16x16x32_bf16 v[144:147], v[96:99], v[104:107], v[12:15]
	v_mfma_f32_16x16x32_bf16 v[12:15], v[112:115], v[88:91], v[24:27]
	v_mfma_f32_16x16x32_bf16 v[8:11], v[112:115], v[186:189], v[8:11]
	v_mfma_f32_16x16x32_bf16 v[4:7], v[80:83], v[194:197], v[4:7]
	v_mfma_f32_16x16x32_bf16 v[24:27], v[120:123], v[104:107], v[12:15]
	v_mfma_f32_16x16x32_bf16 v[12:15], v[80:83], v[186:189], v[16:19]
	v_mfma_f32_16x16x32_bf16 v[8:11], v[120:123], v[190:193], v[8:11]
	v_mfma_f32_16x16x32_bf16 v[4:7], v[96:99], v[198:201], v[4:7]
	v_mfma_f32_16x16x32_bf16 v[0:3], v[112:115], v[194:197], v[0:3]
	v_mfma_f32_16x16x32_bf16 v[148:151], v[96:99], v[190:193], v[12:15]
	v_mfma_f32_16x16x32_bf16 v[186:189], v[120:123], v[198:201], v[0:3]
	s_setprio 0
	s_barrier
	s_nop 3
	ds_read_b128 v[0:3], v139
	ds_read_b128 v[12:15], v139 offset:1024
	ds_read_b128 v[190:193], v139 offset:2048
	ds_read_b128 v[194:197], v139 offset:3072
	ds_read_b128 v[16:19], v135
	ds_read_b128 v[28:31], v135 offset:1024
	ds_read_b128 v[32:35], v135 offset:2048
	ds_read_b128 v[44:47], v135 offset:3072
	ds_read_b128 v[48:51], v135 offset:4096
	ds_read_b128 v[198:201], v135 offset:5120
	ds_read_b128 v[222:225], v135 offset:6144
	ds_read_b128 v[226:229], v135 offset:7168
	s_waitcnt vmcnt(2)
	s_barrier
	s_waitcnt lgkmcnt(0)
	s_setprio 1
	s_waitcnt lgkmcnt(0)
	v_mfma_f32_16x16x32_bf16 v[64:67], v[0:3], v[16:19], v[124:127]
	v_mfma_f32_16x16x32_bf16 v[120:123], v[12:15], v[28:31], v[64:67]
	v_mfma_f32_16x16x32_bf16 v[64:67], v[190:193], v[16:19], v[174:177]
	v_mfma_f32_16x16x32_bf16 v[112:115], v[194:197], v[28:31], v[64:67]
	v_mfma_f32_16x16x32_bf16 v[64:67], v[0:3], v[32:35], v[116:119]
	v_mfma_f32_16x16x32_bf16 v[104:107], v[12:15], v[44:47], v[64:67]
	v_mfma_f32_16x16x32_bf16 v[64:67], v[190:193], v[32:35], v[202:205]
	v_mfma_f32_16x16x32_bf16 v[96:99], v[194:197], v[44:47], v[64:67]
	v_mfma_f32_16x16x32_bf16 v[64:67], v[0:3], v[48:51], v[100:103]
	v_mfma_f32_16x16x32_bf16 v[88:91], v[12:15], v[198:201], v[64:67]
	v_mfma_f32_16x16x32_bf16 v[64:67], v[190:193], v[48:51], v[206:209]
	v_mfma_f32_16x16x32_bf16 v[80:83], v[194:197], v[198:201], v[64:67]
	v_mfma_f32_16x16x32_bf16 v[64:67], v[0:3], v[222:225], v[84:87]
	v_mfma_f32_16x16x32_bf16 v[72:75], v[12:15], v[226:229], v[64:67]
	v_mfma_f32_16x16x32_bf16 v[64:67], v[190:193], v[222:225], v[210:213]
	v_mfma_f32_16x16x32_bf16 v[64:67], v[194:197], v[226:229], v[64:67]
	s_setprio 0
	s_barrier
	ds_read_b128 v[174:177], v139 offset:16384
	ds_read_b128 v[202:205], v139 offset:17408
	ds_read_b128 v[206:209], v139 offset:18432
	ds_read_b128 v[210:213], v139 offset:19456
	s_waitcnt vmcnt(0)
	s_barrier
	s_waitcnt lgkmcnt(0)
	s_setprio 1
	s_waitcnt lgkmcnt(0)
	v_mfma_f32_16x16x32_bf16 v[84:87], v[174:177], v[16:19], v[108:111]
	v_mfma_f32_16x16x32_bf16 v[16:19], v[206:209], v[16:19], v[162:165]
	v_mfma_f32_16x16x32_bf16 v[116:119], v[210:213], v[28:31], v[16:19]
	v_mfma_f32_16x16x32_bf16 v[16:19], v[174:177], v[32:35], v[92:95]
	v_mfma_f32_16x16x32_bf16 v[108:111], v[202:205], v[44:47], v[16:19]
	v_mfma_f32_16x16x32_bf16 v[16:19], v[206:209], v[32:35], v[170:173]
	v_mfma_f32_16x16x32_bf16 v[100:103], v[210:213], v[44:47], v[16:19]
	v_mfma_f32_16x16x32_bf16 v[16:19], v[174:177], v[48:51], v[76:79]
	v_mfma_f32_16x16x32_bf16 v[92:95], v[202:205], v[198:201], v[16:19]
	v_mfma_f32_16x16x32_bf16 v[16:19], v[206:209], v[48:51], v[178:181]
	v_mfma_f32_16x16x32_bf16 v[124:127], v[202:205], v[28:31], v[84:87]
	v_mfma_f32_16x16x32_bf16 v[84:87], v[210:213], v[198:201], v[16:19]
	v_mfma_f32_16x16x32_bf16 v[16:19], v[174:177], v[222:225], v[68:71]
	v_mfma_f32_16x16x32_bf16 v[76:79], v[202:205], v[226:229], v[16:19]
	v_mfma_f32_16x16x32_bf16 v[16:19], v[206:209], v[222:225], v[182:185]
	v_mfma_f32_16x16x32_bf16 v[68:71], v[210:213], v[226:229], v[16:19]
	s_setprio 0
	s_barrier
	ds_read_b128 v[162:165], v135 offset:16384
	ds_read_b128 v[170:173], v135 offset:17408
	ds_read_b128 v[178:181], v135 offset:18432
	ds_read_b128 v[182:185], v135 offset:19456
	ds_read_b128 v[198:201], v135 offset:20480
	ds_read_b128 v[222:225], v135 offset:21504
	ds_read_b128 v[226:229], v135 offset:22528
	ds_read_b128 v[230:233], v135 offset:23552
	s_barrier
	s_waitcnt lgkmcnt(0)
	s_setprio 1
	s_waitcnt lgkmcnt(0)
	v_mfma_f32_16x16x32_bf16 v[16:19], v[0:3], v[162:165], v[60:63]
	v_mfma_f32_16x16x32_bf16 v[60:63], v[12:15], v[170:173], v[16:19]
	v_mfma_f32_16x16x32_bf16 v[16:19], v[190:193], v[162:165], v[56:59]
	v_mfma_f32_16x16x32_bf16 v[48:51], v[194:197], v[170:173], v[16:19]
	v_mfma_f32_16x16x32_bf16 v[16:19], v[0:3], v[178:181], v[52:55]
	v_mfma_f32_16x16x32_bf16 v[44:47], v[12:15], v[182:185], v[16:19]
	v_mfma_f32_16x16x32_bf16 v[16:19], v[190:193], v[178:181], v[214:217]
	v_mfma_f32_16x16x32_bf16 v[32:35], v[194:197], v[182:185], v[16:19]
	v_mfma_f32_16x16x32_bf16 v[16:19], v[0:3], v[198:201], v[36:39]
	v_mfma_f32_16x16x32_bf16 v[0:3], v[0:3], v[226:229], v[20:23]
	v_mfma_f32_16x16x32_bf16 v[28:31], v[12:15], v[222:225], v[16:19]
	v_mfma_f32_16x16x32_bf16 v[16:19], v[190:193], v[198:201], v[218:221]
	v_mfma_f32_16x16x32_bf16 v[12:15], v[12:15], v[230:233], v[0:3]
	v_mfma_f32_16x16x32_bf16 v[0:3], v[190:193], v[226:229], v[128:131]
	v_mfma_f32_16x16x32_bf16 v[16:19], v[194:197], v[222:225], v[16:19]
	v_mfma_f32_16x16x32_bf16 v[0:3], v[194:197], v[230:233], v[0:3]
	s_setprio 0
	s_setprio 1
	v_mfma_f32_16x16x32_bf16 v[20:23], v[174:177], v[162:165], v[140:143]
	v_mfma_f32_16x16x32_bf16 v[56:59], v[202:205], v[170:173], v[20:23]
	v_mfma_f32_16x16x32_bf16 v[20:23], v[206:209], v[162:165], v[40:43]
	v_mfma_f32_16x16x32_bf16 v[52:55], v[210:213], v[170:173], v[20:23]
	v_mfma_f32_16x16x32_bf16 v[20:23], v[174:177], v[178:181], v[144:147]
	v_mfma_f32_16x16x32_bf16 v[40:43], v[202:205], v[182:185], v[20:23]
	v_mfma_f32_16x16x32_bf16 v[20:23], v[206:209], v[178:181], v[24:27]
	v_mfma_f32_16x16x32_bf16 v[36:39], v[210:213], v[182:185], v[20:23]
	v_mfma_f32_16x16x32_bf16 v[20:23], v[174:177], v[198:201], v[148:151]
	v_mfma_f32_16x16x32_bf16 v[8:11], v[206:209], v[198:201], v[8:11]
	v_mfma_f32_16x16x32_bf16 v[4:7], v[174:177], v[226:229], v[4:7]
	v_mfma_f32_16x16x32_bf16 v[24:27], v[202:205], v[222:225], v[20:23]
	v_mfma_f32_16x16x32_bf16 v[20:23], v[210:213], v[222:225], v[8:11]
	v_mfma_f32_16x16x32_bf16 v[8:11], v[202:205], v[230:233], v[4:7]
	v_mfma_f32_16x16x32_bf16 v[4:7], v[206:209], v[226:229], v[186:189]
	v_mfma_f32_16x16x32_bf16 v[4:7], v[210:213], v[230:233], v[4:7]
	s_setprio 0
	s_movk_i32 s1, 0x100
	v_cmp_gt_u32_e32 vcc, s1, v134
	s_barrier
	s_and_saveexec_b64 s[4:5], vcc
	s_cbranch_execz .LBB0_659
	s_barrier
	s_branch .LBB0_659

.LBB0_702:
	ds_read_b128 v[140:143], v135
	ds_read_b128 v[178:181], v135 offset:2048
	ds_read_b128 v[162:165], v135 offset:1024
	ds_read_b128 v[182:185], v135 offset:3072
	v_add_u32_e32 v176, 0x4000, v147
	v_lshl_add_u64 v[234:235], v[132:133], 0, v[136:137]
	v_readfirstlane_b32 s1, v176
	v_add_u32_e32 v177, 0x6000, v147
	v_lshl_add_u64 v[218:219], v[234:235], 0, s[26:27]
	s_mov_b32 m0, s1
	v_readfirstlane_b32 s1, v177
	ds_read_b128 v[186:189], v134
	ds_read_b128 v[194:197], v134 offset:2048
	ds_read_b128 v[202:205], v134 offset:4096
	ds_read_b128 v[210:213], v134 offset:6144
	ds_read_b128 v[190:193], v134 offset:1024
	ds_read_b128 v[198:201], v134 offset:3072
	ds_read_b128 v[206:209], v134 offset:5120
	ds_read_b128 v[214:217], v134 offset:7168
	global_load_lds_dwordx4 v[218:219], off
	v_lshl_add_u64 v[218:219], v[234:235], 0, s[96:97]
	s_mov_b32 m0, s1
	s_nop 0
	global_load_lds_dwordx4 v[218:219], off
	s_waitcnt lgkmcnt(8)
	s_barrier
	s_waitcnt lgkmcnt(4)
	s_setprio 1
	s_waitcnt lgkmcnt(4)
	v_mfma_f32_16x16x32_bf16 v[124:127], v[140:143], v[186:189], v[124:127]
	v_mfma_f32_16x16x32_bf16 v[120:123], v[178:181], v[186:189], v[120:123]
	v_mfma_f32_16x16x32_bf16 v[116:119], v[140:143], v[194:197], v[116:119]
	v_mfma_f32_16x16x32_bf16 v[112:115], v[178:181], v[194:197], v[112:115]
	v_mfma_f32_16x16x32_bf16 v[100:103], v[140:143], v[202:205], v[100:103]
	v_mfma_f32_16x16x32_bf16 v[96:99], v[178:181], v[202:205], v[96:99]
	v_mfma_f32_16x16x32_bf16 v[84:87], v[140:143], v[210:213], v[84:87]
	v_mfma_f32_16x16x32_bf16 v[80:83], v[178:181], v[210:213], v[80:83]
	s_waitcnt lgkmcnt(0)
	v_mfma_f32_16x16x32_bf16 v[124:127], v[162:165], v[190:193], v[124:127]
	v_mfma_f32_16x16x32_bf16 v[120:123], v[182:185], v[190:193], v[120:123]
	v_mfma_f32_16x16x32_bf16 v[116:119], v[162:165], v[198:201], v[116:119]
	v_mfma_f32_16x16x32_bf16 v[112:115], v[182:185], v[198:201], v[112:115]
	v_mfma_f32_16x16x32_bf16 v[100:103], v[162:165], v[206:209], v[100:103]
	v_mfma_f32_16x16x32_bf16 v[96:99], v[182:185], v[206:209], v[96:99]
	v_mfma_f32_16x16x32_bf16 v[84:87], v[162:165], v[214:217], v[84:87]
	v_mfma_f32_16x16x32_bf16 v[80:83], v[182:185], v[214:217], v[80:83]
	s_setprio 0
	s_barrier
	v_lshl_add_u64 v[236:237], v[130:131], 0, v[136:137]
	s_mov_b64 s[14:15], 0x3100100
	v_readfirstlane_b32 s1, v148
	v_lshl_add_u64 v[238:239], v[236:237], 0, s[14:15]
	s_mov_b32 m0, s1
	s_mov_b64 s[14:15], 0x3158100
	v_readfirstlane_b32 s1, v149
	ds_read_b128 v[218:221], v135 offset:16384
	ds_read_b128 v[226:229], v135 offset:18432
	ds_read_b128 v[222:225], v135 offset:17408
	ds_read_b128 v[230:233], v135 offset:19456
	global_load_lds_dwordx4 v[238:239], off
	v_lshl_add_u64 v[238:239], v[236:237], 0, s[14:15]
	s_mov_b32 m0, s1
	s_nop 0
	global_load_lds_dwordx4 v[238:239], off
	s_barrier
	s_waitcnt lgkmcnt(2)
	s_setprio 1
	s_waitcnt lgkmcnt(2)
	v_mfma_f32_16x16x32_bf16 v[108:111], v[218:221], v[186:189], v[108:111]
	v_mfma_f32_16x16x32_bf16 v[104:107], v[226:229], v[186:189], v[104:107]
	v_mfma_f32_16x16x32_bf16 v[92:95], v[218:221], v[194:197], v[92:95]
	v_mfma_f32_16x16x32_bf16 v[88:91], v[226:229], v[194:197], v[88:91]
	v_mfma_f32_16x16x32_bf16 v[76:79], v[218:221], v[202:205], v[76:79]
	v_mfma_f32_16x16x32_bf16 v[72:75], v[226:229], v[202:205], v[72:75]
	v_mfma_f32_16x16x32_bf16 v[68:71], v[218:221], v[210:213], v[68:71]
	v_mfma_f32_16x16x32_bf16 v[64:67], v[226:229], v[210:213], v[64:67]
	s_waitcnt lgkmcnt(0)
	v_mfma_f32_16x16x32_bf16 v[108:111], v[222:225], v[190:193], v[108:111]
	v_mfma_f32_16x16x32_bf16 v[104:107], v[230:233], v[190:193], v[104:107]
	v_mfma_f32_16x16x32_bf16 v[92:95], v[222:225], v[198:201], v[92:95]
	v_mfma_f32_16x16x32_bf16 v[88:91], v[230:233], v[198:201], v[88:91]
	v_mfma_f32_16x16x32_bf16 v[76:79], v[222:225], v[206:209], v[76:79]
	v_mfma_f32_16x16x32_bf16 v[72:75], v[230:233], v[206:209], v[72:75]
	v_mfma_f32_16x16x32_bf16 v[68:71], v[222:225], v[214:217], v[68:71]
	v_mfma_f32_16x16x32_bf16 v[64:67], v[230:233], v[214:217], v[64:67]
	s_setprio 0
	v_readfirstlane_b32 s1, v146
	v_lshl_add_u64 v[238:239], v[234:235], 0, s[34:35]
	s_mov_b32 m0, s1
	v_readfirstlane_b32 s1, v150
	s_barrier
	ds_read_b128 v[186:189], v134 offset:16384
	ds_read_b128 v[194:197], v134 offset:18432
	ds_read_b128 v[202:205], v134 offset:20480
	ds_read_b128 v[210:213], v134 offset:22528
	ds_read_b128 v[190:193], v134 offset:17408
	ds_read_b128 v[198:201], v134 offset:19456
	ds_read_b128 v[206:209], v134 offset:21504
	ds_read_b128 v[214:217], v134 offset:23552
	global_load_lds_dwordx4 v[238:239], off
	v_lshl_add_u64 v[238:239], v[234:235], 0, s[80:81]
	s_mov_b32 m0, s1
	s_nop 0
	global_load_lds_dwordx4 v[238:239], off
	s_barrier
	s_waitcnt lgkmcnt(4)
	s_setprio 1
	s_waitcnt lgkmcnt(4)
	v_mfma_f32_16x16x32_bf16 v[60:63], v[140:143], v[186:189], v[60:63]
	v_mfma_f32_16x16x32_bf16 v[56:59], v[178:181], v[186:189], v[56:59]
	v_mfma_f32_16x16x32_bf16 v[52:55], v[140:143], v[194:197], v[52:55]
	v_mfma_f32_16x16x32_bf16 v[44:47], v[178:181], v[194:197], v[44:47]
	v_mfma_f32_16x16x32_bf16 v[36:39], v[140:143], v[202:205], v[36:39]
	v_mfma_f32_16x16x32_bf16 v[28:31], v[178:181], v[202:205], v[28:31]
	v_mfma_f32_16x16x32_bf16 v[20:23], v[140:143], v[210:213], v[20:23]
	v_mfma_f32_16x16x32_bf16 v[12:15], v[178:181], v[210:213], v[12:15]
	s_waitcnt lgkmcnt(0)
	v_mfma_f32_16x16x32_bf16 v[60:63], v[162:165], v[190:193], v[60:63]
	v_mfma_f32_16x16x32_bf16 v[56:59], v[182:185], v[190:193], v[56:59]
	v_mfma_f32_16x16x32_bf16 v[52:55], v[162:165], v[198:201], v[52:55]
	v_mfma_f32_16x16x32_bf16 v[44:47], v[182:185], v[198:201], v[44:47]
	v_mfma_f32_16x16x32_bf16 v[36:39], v[162:165], v[206:209], v[36:39]
	v_mfma_f32_16x16x32_bf16 v[28:31], v[182:185], v[206:209], v[28:31]
	v_mfma_f32_16x16x32_bf16 v[20:23], v[162:165], v[214:217], v[20:23]
	v_mfma_f32_16x16x32_bf16 v[12:15], v[182:185], v[214:217], v[12:15]
	s_setprio 0
	s_barrier
	s_mov_b64 s[14:15], 0x31b0100
	v_readfirstlane_b32 s1, v151
	v_lshl_add_u64 v[140:141], v[236:237], 0, s[14:15]
	s_mov_b32 m0, s1
	s_mov_b64 s[14:15], 0x3208100
	v_readfirstlane_b32 s1, v152
	global_load_lds_dwordx4 v[140:141], off
	v_lshl_add_u64 v[140:141], v[236:237], 0, s[14:15]
	s_mov_b32 m0, s1
	s_nop 0
	global_load_lds_dwordx4 v[140:141], off
	s_waitcnt vmcnt(6)
	s_barrier
	s_setprio 1
	v_mfma_f32_16x16x32_bf16 v[48:51], v[218:221], v[186:189], v[48:51]
	v_mfma_f32_16x16x32_bf16 v[40:43], v[226:229], v[186:189], v[40:43]
	v_mfma_f32_16x16x32_bf16 v[32:35], v[218:221], v[194:197], v[32:35]
	v_mfma_f32_16x16x32_bf16 v[24:27], v[226:229], v[194:197], v[24:27]
	v_mfma_f32_16x16x32_bf16 v[16:19], v[218:221], v[202:205], v[16:19]
	v_mfma_f32_16x16x32_bf16 v[8:11], v[226:229], v[202:205], v[8:11]
	v_mfma_f32_16x16x32_bf16 v[4:7], v[218:221], v[210:213], v[4:7]
	v_mfma_f32_16x16x32_bf16 v[0:3], v[226:229], v[210:213], v[0:3]
	v_mfma_f32_16x16x32_bf16 v[48:51], v[222:225], v[190:193], v[48:51]
	v_mfma_f32_16x16x32_bf16 v[40:43], v[230:233], v[190:193], v[40:43]
	v_mfma_f32_16x16x32_bf16 v[32:35], v[222:225], v[198:201], v[32:35]
	v_mfma_f32_16x16x32_bf16 v[24:27], v[230:233], v[198:201], v[24:27]
	v_mfma_f32_16x16x32_bf16 v[16:19], v[222:225], v[206:209], v[16:19]
	v_mfma_f32_16x16x32_bf16 v[8:11], v[230:233], v[206:209], v[8:11]
	v_mfma_f32_16x16x32_bf16 v[4:7], v[222:225], v[214:217], v[4:7]
	v_mfma_f32_16x16x32_bf16 v[0:3], v[230:233], v[214:217], v[0:3]
	s_setprio 0
	s_barrier
	ds_read_b128 v[140:143], v145
	ds_read_b128 v[178:181], v145 offset:2048
	ds_read_b128 v[162:165], v145 offset:1024
	ds_read_b128 v[182:185], v145 offset:3072
	v_readfirstlane_b32 s1, v153
	v_lshl_add_u64 v[218:219], v[234:235], 0, s[18:19]
	s_mov_b32 m0, s1
	v_readfirstlane_b32 s1, v170
	ds_read_b128 v[186:189], v144
	ds_read_b128 v[194:197], v144 offset:2048
	ds_read_b128 v[202:205], v144 offset:4096
	ds_read_b128 v[210:213], v144 offset:6144
	ds_read_b128 v[190:193], v144 offset:1024
	ds_read_b128 v[198:201], v144 offset:3072
	ds_read_b128 v[206:209], v144 offset:5120
	ds_read_b128 v[214:217], v144 offset:7168
	global_load_lds_dwordx4 v[218:219], off
	v_lshl_add_u64 v[218:219], v[234:235], 0, s[84:85]
	s_mov_b32 m0, s1
	s_nop 0
	global_load_lds_dwordx4 v[218:219], off
	s_waitcnt lgkmcnt(8)
	s_barrier
	s_waitcnt lgkmcnt(4)
	s_setprio 1
	s_waitcnt lgkmcnt(4)
	v_mfma_f32_16x16x32_bf16 v[124:127], v[140:143], v[186:189], v[124:127]
	v_mfma_f32_16x16x32_bf16 v[120:123], v[178:181], v[186:189], v[120:123]
	v_mfma_f32_16x16x32_bf16 v[116:119], v[140:143], v[194:197], v[116:119]
	v_mfma_f32_16x16x32_bf16 v[112:115], v[178:181], v[194:197], v[112:115]
	v_mfma_f32_16x16x32_bf16 v[100:103], v[140:143], v[202:205], v[100:103]
	v_mfma_f32_16x16x32_bf16 v[96:99], v[178:181], v[202:205], v[96:99]
	v_mfma_f32_16x16x32_bf16 v[84:87], v[140:143], v[210:213], v[84:87]
	v_mfma_f32_16x16x32_bf16 v[80:83], v[178:181], v[210:213], v[80:83]
	s_waitcnt lgkmcnt(0)
	v_mfma_f32_16x16x32_bf16 v[124:127], v[162:165], v[190:193], v[124:127]
	v_mfma_f32_16x16x32_bf16 v[120:123], v[182:185], v[190:193], v[120:123]
	v_mfma_f32_16x16x32_bf16 v[116:119], v[162:165], v[198:201], v[116:119]
	v_mfma_f32_16x16x32_bf16 v[112:115], v[182:185], v[198:201], v[112:115]
	v_mfma_f32_16x16x32_bf16 v[100:103], v[162:165], v[206:209], v[100:103]
	v_mfma_f32_16x16x32_bf16 v[96:99], v[182:185], v[206:209], v[96:99]
	v_mfma_f32_16x16x32_bf16 v[84:87], v[162:165], v[214:217], v[84:87]
	v_mfma_f32_16x16x32_bf16 v[80:83], v[182:185], v[214:217], v[80:83]
	s_setprio 0
	s_barrier
	s_mov_b64 s[14:15], 0x3100180
	v_readfirstlane_b32 s1, v171
	v_lshl_add_u64 v[238:239], v[236:237], 0, s[14:15]
	s_mov_b32 m0, s1
	s_mov_b64 s[14:15], 0x3158180
	v_readfirstlane_b32 s1, v172
	ds_read_b128 v[218:221], v145 offset:16384
	ds_read_b128 v[226:229], v145 offset:18432
	ds_read_b128 v[222:225], v145 offset:17408
	ds_read_b128 v[230:233], v145 offset:19456
	global_load_lds_dwordx4 v[238:239], off
	v_lshl_add_u64 v[238:239], v[236:237], 0, s[14:15]
	s_mov_b32 m0, s1
	s_nop 0
	global_load_lds_dwordx4 v[238:239], off
	s_barrier
	s_waitcnt lgkmcnt(2)
	s_setprio 1
	s_waitcnt lgkmcnt(2)
	v_mfma_f32_16x16x32_bf16 v[108:111], v[218:221], v[186:189], v[108:111]
	v_mfma_f32_16x16x32_bf16 v[104:107], v[226:229], v[186:189], v[104:107]
	v_mfma_f32_16x16x32_bf16 v[92:95], v[218:221], v[194:197], v[92:95]
	v_mfma_f32_16x16x32_bf16 v[88:91], v[226:229], v[194:197], v[88:91]
	v_mfma_f32_16x16x32_bf16 v[76:79], v[218:221], v[202:205], v[76:79]
	v_mfma_f32_16x16x32_bf16 v[72:75], v[226:229], v[202:205], v[72:75]
	v_mfma_f32_16x16x32_bf16 v[68:71], v[218:221], v[210:213], v[68:71]
	v_mfma_f32_16x16x32_bf16 v[64:67], v[226:229], v[210:213], v[64:67]
	s_waitcnt lgkmcnt(0)
	v_mfma_f32_16x16x32_bf16 v[108:111], v[222:225], v[190:193], v[108:111]
	v_mfma_f32_16x16x32_bf16 v[104:107], v[230:233], v[190:193], v[104:107]
	v_mfma_f32_16x16x32_bf16 v[92:95], v[222:225], v[198:201], v[92:95]
	v_mfma_f32_16x16x32_bf16 v[88:91], v[230:233], v[198:201], v[88:91]
	v_mfma_f32_16x16x32_bf16 v[76:79], v[222:225], v[206:209], v[76:79]
	v_mfma_f32_16x16x32_bf16 v[72:75], v[230:233], v[206:209], v[72:75]
	v_mfma_f32_16x16x32_bf16 v[68:71], v[222:225], v[214:217], v[68:71]
	v_mfma_f32_16x16x32_bf16 v[64:67], v[230:233], v[214:217], v[64:67]
	s_setprio 0
	v_readfirstlane_b32 s1, v147
	v_lshl_add_u64 v[238:239], v[234:235], 0, s[30:31]
	s_mov_b32 m0, s1
	v_readfirstlane_b32 s1, v173
	s_barrier
	ds_read_b128 v[186:189], v144 offset:16384
	ds_read_b128 v[194:197], v144 offset:18432
	ds_read_b128 v[202:205], v144 offset:20480
	ds_read_b128 v[210:213], v144 offset:22528
	ds_read_b128 v[190:193], v144 offset:17408
	ds_read_b128 v[198:201], v144 offset:19456
	ds_read_b128 v[206:209], v144 offset:21504
	ds_read_b128 v[214:217], v144 offset:23552
	global_load_lds_dwordx4 v[238:239], off
	v_lshl_add_u64 v[234:235], v[234:235], 0, s[36:37]
	s_mov_b32 m0, s1
	s_nop 0
	global_load_lds_dwordx4 v[234:235], off
	s_barrier
	s_waitcnt lgkmcnt(4)
	s_setprio 1
	s_waitcnt lgkmcnt(4)
	v_mfma_f32_16x16x32_bf16 v[60:63], v[140:143], v[186:189], v[60:63]
	v_mfma_f32_16x16x32_bf16 v[56:59], v[178:181], v[186:189], v[56:59]
	v_mfma_f32_16x16x32_bf16 v[52:55], v[140:143], v[194:197], v[52:55]
	v_mfma_f32_16x16x32_bf16 v[44:47], v[178:181], v[194:197], v[44:47]
	v_mfma_f32_16x16x32_bf16 v[36:39], v[140:143], v[202:205], v[36:39]
	v_mfma_f32_16x16x32_bf16 v[28:31], v[178:181], v[202:205], v[28:31]
	v_mfma_f32_16x16x32_bf16 v[20:23], v[140:143], v[210:213], v[20:23]
	v_mfma_f32_16x16x32_bf16 v[12:15], v[178:181], v[210:213], v[12:15]
	s_waitcnt lgkmcnt(0)
	v_mfma_f32_16x16x32_bf16 v[60:63], v[162:165], v[190:193], v[60:63]
	v_mfma_f32_16x16x32_bf16 v[56:59], v[182:185], v[190:193], v[56:59]
	v_mfma_f32_16x16x32_bf16 v[52:55], v[162:165], v[198:201], v[52:55]
	v_mfma_f32_16x16x32_bf16 v[44:47], v[182:185], v[198:201], v[44:47]
	v_mfma_f32_16x16x32_bf16 v[36:39], v[162:165], v[206:209], v[36:39]
	v_mfma_f32_16x16x32_bf16 v[28:31], v[182:185], v[206:209], v[28:31]
	v_mfma_f32_16x16x32_bf16 v[20:23], v[162:165], v[214:217], v[20:23]
	v_mfma_f32_16x16x32_bf16 v[12:15], v[182:185], v[214:217], v[12:15]
	s_setprio 0
	s_barrier
	s_mov_b64 s[14:15], 0x31b0180
	v_readfirstlane_b32 s1, v174
	v_lshl_add_u64 v[140:141], v[236:237], 0, s[14:15]
	s_mov_b32 m0, s1
	s_mov_b64 s[14:15], 0x3208180
	v_readfirstlane_b32 s1, v175
	global_load_lds_dwordx4 v[140:141], off
	v_lshl_add_u64 v[140:141], v[236:237], 0, s[14:15]
	s_mov_b32 m0, s1
	s_nop 0
	global_load_lds_dwordx4 v[140:141], off
	s_waitcnt vmcnt(6)
	s_barrier
	s_setprio 1
	v_mfma_f32_16x16x32_bf16 v[48:51], v[218:221], v[186:189], v[48:51]
	v_mfma_f32_16x16x32_bf16 v[40:43], v[226:229], v[186:189], v[40:43]
	v_mfma_f32_16x16x32_bf16 v[32:35], v[218:221], v[194:197], v[32:35]
	v_mfma_f32_16x16x32_bf16 v[24:27], v[226:229], v[194:197], v[24:27]
	v_mfma_f32_16x16x32_bf16 v[16:19], v[218:221], v[202:205], v[16:19]
	v_mfma_f32_16x16x32_bf16 v[8:11], v[226:229], v[202:205], v[8:11]
	v_mfma_f32_16x16x32_bf16 v[4:7], v[218:221], v[210:213], v[4:7]
	v_mfma_f32_16x16x32_bf16 v[0:3], v[226:229], v[210:213], v[0:3]
	v_mfma_f32_16x16x32_bf16 v[48:51], v[222:225], v[190:193], v[48:51]
	v_mfma_f32_16x16x32_bf16 v[40:43], v[230:233], v[190:193], v[40:43]
	v_mfma_f32_16x16x32_bf16 v[32:35], v[222:225], v[198:201], v[32:35]
	v_mfma_f32_16x16x32_bf16 v[24:27], v[230:233], v[198:201], v[24:27]
	v_mfma_f32_16x16x32_bf16 v[16:19], v[222:225], v[206:209], v[16:19]
	v_mfma_f32_16x16x32_bf16 v[8:11], v[230:233], v[206:209], v[8:11]
	v_mfma_f32_16x16x32_bf16 v[4:7], v[222:225], v[214:217], v[4:7]
	v_mfma_f32_16x16x32_bf16 v[0:3], v[230:233], v[214:217], v[0:3]
	s_setprio 0
	s_add_i32 s0, s0, 2
	v_lshl_add_u64 v[130:131], v[130:131], 0, s[86:87]
	s_cmp_gt_u32 s0, 39
	v_lshl_add_u64 v[132:133], v[132:133], 0, s[86:87]
	s_barrier
	s_cbranch_scc0 .LBB0_702
	s_mov_b64 s[0:1], 0xb1580
	v_lshl_add_u64 v[174:175], v[128:129], 0, s[0:1]
	v_readfirstlane_b32 s0, v176
	s_mov_b32 m0, s0
	s_mov_b64 s[0:1], 0x109580
	v_lshl_add_u64 v[128:129], v[128:129], 0, s[0:1]
	v_readfirstlane_b32 s0, v177
	ds_read_b128 v[130:133], v135
	ds_read_b128 v[140:143], v135 offset:1024
	ds_read_b128 v[146:149], v135 offset:2048
	ds_read_b128 v[150:153], v135 offset:3072
	ds_read_b128 v[162:165], v134
	ds_read_b128 v[170:173], v134 offset:1024
	ds_read_b128 v[178:181], v134 offset:2048
	ds_read_b128 v[182:185], v134 offset:3072
	ds_read_b128 v[186:189], v134 offset:4096
	ds_read_b128 v[190:193], v134 offset:5120
	ds_read_b128 v[194:197], v134 offset:6144
	ds_read_b128 v[198:201], v134 offset:7168
	global_load_lds_dwordx4 v[174:175], off
	s_mov_b32 m0, s0
	s_nop 0
	global_load_lds_dwordx4 v[128:129], off
	s_barrier
	s_waitcnt lgkmcnt(0)
	s_setprio 1
	s_waitcnt lgkmcnt(0)
	v_mfma_f32_16x16x32_bf16 v[124:127], v[130:133], v[162:165], v[124:127]
	v_mfma_f32_16x16x32_bf16 v[120:123], v[146:149], v[162:165], v[120:123]
	v_mfma_f32_16x16x32_bf16 v[116:119], v[130:133], v[178:181], v[116:119]
	v_mfma_f32_16x16x32_bf16 v[112:115], v[146:149], v[178:181], v[112:115]
	v_mfma_f32_16x16x32_bf16 v[100:103], v[130:133], v[186:189], v[100:103]
	v_mfma_f32_16x16x32_bf16 v[96:99], v[146:149], v[186:189], v[96:99]
	v_mfma_f32_16x16x32_bf16 v[124:127], v[140:143], v[170:173], v[124:127]
	v_mfma_f32_16x16x32_bf16 v[120:123], v[150:153], v[170:173], v[120:123]
	v_mfma_f32_16x16x32_bf16 v[116:119], v[140:143], v[182:185], v[116:119]
	v_mfma_f32_16x16x32_bf16 v[112:115], v[150:153], v[182:185], v[112:115]
	v_mfma_f32_16x16x32_bf16 v[100:103], v[140:143], v[190:193], v[100:103]
	v_mfma_f32_16x16x32_bf16 v[96:99], v[150:153], v[190:193], v[96:99]
	v_mfma_f32_16x16x32_bf16 v[84:87], v[130:133], v[194:197], v[84:87]
	v_mfma_f32_16x16x32_bf16 v[80:83], v[146:149], v[194:197], v[80:83]
	v_mfma_f32_16x16x32_bf16 v[84:87], v[140:143], v[198:201], v[84:87]
	v_mfma_f32_16x16x32_bf16 v[80:83], v[150:153], v[198:201], v[80:83]
	s_setprio 0
	s_barrier
	ds_read_b128 v[174:177], v135 offset:16384
	ds_read_b128 v[202:205], v135 offset:17408
	ds_read_b128 v[206:209], v135 offset:18432
	ds_read_b128 v[210:213], v135 offset:19456
	s_barrier
	s_waitcnt lgkmcnt(0)
	s_setprio 1
	s_waitcnt lgkmcnt(0)
	v_mfma_f32_16x16x32_bf16 v[92:95], v[174:177], v[178:181], v[92:95]
	v_mfma_f32_16x16x32_bf16 v[88:91], v[206:209], v[178:181], v[88:91]
	v_mfma_f32_16x16x32_bf16 v[76:79], v[174:177], v[186:189], v[76:79]
	v_mfma_f32_16x16x32_bf16 v[72:75], v[206:209], v[186:189], v[72:75]
	v_mfma_f32_16x16x32_bf16 v[68:71], v[174:177], v[194:197], v[68:71]
	v_mfma_f32_16x16x32_bf16 v[64:67], v[206:209], v[194:197], v[64:67]
	v_mfma_f32_16x16x32_bf16 v[108:111], v[174:177], v[162:165], v[108:111]
	v_mfma_f32_16x16x32_bf16 v[104:107], v[206:209], v[162:165], v[104:107]
	v_mfma_f32_16x16x32_bf16 v[92:95], v[202:205], v[182:185], v[92:95]
	v_mfma_f32_16x16x32_bf16 v[88:91], v[210:213], v[182:185], v[88:91]
	v_mfma_f32_16x16x32_bf16 v[76:79], v[202:205], v[190:193], v[76:79]
	v_mfma_f32_16x16x32_bf16 v[72:75], v[210:213], v[190:193], v[72:75]
	v_mfma_f32_16x16x32_bf16 v[68:71], v[202:205], v[198:201], v[68:71]
	v_mfma_f32_16x16x32_bf16 v[64:67], v[210:213], v[198:201], v[64:67]
	v_mfma_f32_16x16x32_bf16 v[214:217], v[202:205], v[170:173], v[108:111]
	v_mfma_f32_16x16x32_bf16 v[162:165], v[210:213], v[170:173], v[104:107]
	s_setprio 0
	s_barrier
	s_nop 0
	ds_read_b128 v[104:107], v134 offset:16384
	ds_read_b128 v[108:111], v134 offset:17408
	ds_read_b128 v[170:173], v134 offset:18432
	ds_read_b128 v[178:181], v134 offset:19456
	ds_read_b128 v[182:185], v134 offset:20480
	ds_read_b128 v[186:189], v134 offset:21504
	ds_read_b128 v[190:193], v134 offset:22528
	ds_read_b128 v[194:197], v134 offset:23552
	s_waitcnt vmcnt(4)
	s_barrier
	s_waitcnt lgkmcnt(0)
	s_setprio 1
	s_waitcnt lgkmcnt(0)
	v_mfma_f32_16x16x32_bf16 v[28:31], v[146:149], v[182:185], v[28:31]
	v_mfma_f32_16x16x32_bf16 v[20:23], v[130:133], v[190:193], v[20:23]
	v_mfma_f32_16x16x32_bf16 v[12:15], v[146:149], v[190:193], v[12:15]
	v_mfma_f32_16x16x32_bf16 v[60:63], v[130:133], v[104:107], v[60:63]
	v_mfma_f32_16x16x32_bf16 v[56:59], v[146:149], v[104:107], v[56:59]
	v_mfma_f32_16x16x32_bf16 v[52:55], v[130:133], v[170:173], v[52:55]
	v_mfma_f32_16x16x32_bf16 v[44:47], v[146:149], v[170:173], v[44:47]
	v_mfma_f32_16x16x32_bf16 v[36:39], v[130:133], v[182:185], v[36:39]
	v_mfma_f32_16x16x32_bf16 v[28:31], v[150:153], v[186:189], v[28:31]
	v_mfma_f32_16x16x32_bf16 v[20:23], v[140:143], v[194:197], v[20:23]
	v_mfma_f32_16x16x32_bf16 v[12:15], v[150:153], v[194:197], v[12:15]
	v_mfma_f32_16x16x32_bf16 v[198:201], v[140:143], v[108:111], v[60:63]
	v_mfma_f32_16x16x32_bf16 v[218:221], v[150:153], v[108:111], v[56:59]
	v_mfma_f32_16x16x32_bf16 v[222:225], v[140:143], v[178:181], v[52:55]
	v_mfma_f32_16x16x32_bf16 v[226:229], v[150:153], v[178:181], v[44:47]
	v_mfma_f32_16x16x32_bf16 v[230:233], v[140:143], v[186:189], v[36:39]
	s_setprio 0
	s_setprio 1
	v_mfma_f32_16x16x32_bf16 v[36:39], v[174:177], v[104:107], v[48:51]
	v_mfma_f32_16x16x32_bf16 v[8:11], v[206:209], v[182:185], v[8:11]
	v_mfma_f32_16x16x32_bf16 v[4:7], v[174:177], v[190:193], v[4:7]
	v_mfma_f32_16x16x32_bf16 v[0:3], v[206:209], v[190:193], v[0:3]
	v_mfma_f32_16x16x32_bf16 v[140:143], v[202:205], v[108:111], v[36:39]
	v_mfma_f32_16x16x32_bf16 v[36:39], v[206:209], v[104:107], v[40:43]
	v_mfma_f32_16x16x32_bf16 v[32:35], v[174:177], v[170:173], v[32:35]
	v_mfma_f32_16x16x32_bf16 v[24:27], v[206:209], v[170:173], v[24:27]
	v_mfma_f32_16x16x32_bf16 v[16:19], v[174:177], v[182:185], v[16:19]
	v_mfma_f32_16x16x32_bf16 v[8:11], v[210:213], v[186:189], v[8:11]
	v_mfma_f32_16x16x32_bf16 v[4:7], v[202:205], v[194:197], v[4:7]
	v_mfma_f32_16x16x32_bf16 v[0:3], v[210:213], v[194:197], v[0:3]
	v_mfma_f32_16x16x32_bf16 v[146:149], v[210:213], v[108:111], v[36:39]
	v_mfma_f32_16x16x32_bf16 v[150:153], v[202:205], v[178:181], v[32:35]
	v_mfma_f32_16x16x32_bf16 v[170:173], v[210:213], v[178:181], v[24:27]
	v_mfma_f32_16x16x32_bf16 v[178:181], v[202:205], v[186:189], v[16:19]
	s_setprio 0
	s_barrier
	s_nop 0
	ds_read_b128 v[16:19], v145
	ds_read_b128 v[24:27], v145 offset:1024
	ds_read_b128 v[174:177], v145 offset:2048
	ds_read_b128 v[182:185], v145 offset:3072
	ds_read_b128 v[32:35], v144
	ds_read_b128 v[36:39], v144 offset:1024
	ds_read_b128 v[40:43], v144 offset:2048
	ds_read_b128 v[44:47], v144 offset:3072
	ds_read_b128 v[186:189], v144 offset:4096
	ds_read_b128 v[190:193], v144 offset:5120
	ds_read_b128 v[194:197], v144 offset:6144
	ds_read_b128 v[202:205], v144 offset:7168
	s_waitcnt vmcnt(2)
	s_barrier
	s_waitcnt lgkmcnt(0)
	s_setprio 1
	s_waitcnt lgkmcnt(0)
	v_mfma_f32_16x16x32_bf16 v[48:51], v[16:19], v[32:35], v[124:127]
	v_mfma_f32_16x16x32_bf16 v[132:135], v[24:27], v[36:39], v[48:51]
	v_mfma_f32_16x16x32_bf16 v[48:51], v[174:177], v[32:35], v[120:123]
	v_mfma_f32_16x16x32_bf16 v[128:131], v[182:185], v[36:39], v[48:51]
	v_mfma_f32_16x16x32_bf16 v[48:51], v[16:19], v[40:43], v[116:119]
	v_mfma_f32_16x16x32_bf16 v[124:127], v[24:27], v[44:47], v[48:51]
	v_mfma_f32_16x16x32_bf16 v[48:51], v[174:177], v[40:43], v[112:115]
	v_mfma_f32_16x16x32_bf16 v[120:123], v[182:185], v[44:47], v[48:51]
	v_mfma_f32_16x16x32_bf16 v[48:51], v[16:19], v[186:189], v[100:103]
	v_mfma_f32_16x16x32_bf16 v[116:119], v[24:27], v[190:193], v[48:51]
	v_mfma_f32_16x16x32_bf16 v[48:51], v[174:177], v[186:189], v[96:99]
	v_mfma_f32_16x16x32_bf16 v[112:115], v[182:185], v[190:193], v[48:51]
	v_mfma_f32_16x16x32_bf16 v[48:51], v[16:19], v[194:197], v[84:87]
	v_mfma_f32_16x16x32_bf16 v[108:111], v[24:27], v[202:205], v[48:51]
	v_mfma_f32_16x16x32_bf16 v[48:51], v[174:177], v[194:197], v[80:83]
	v_mfma_f32_16x16x32_bf16 v[104:107], v[182:185], v[202:205], v[48:51]
	s_setprio 0
	s_barrier
	ds_read_b128 v[80:83], v145 offset:16384
	ds_read_b128 v[84:87], v145 offset:17408
	ds_read_b128 v[206:209], v145 offset:18432
	ds_read_b128 v[210:213], v145 offset:19456
	s_waitcnt vmcnt(0)
	s_barrier
	s_waitcnt lgkmcnt(0)
	s_setprio 1
	s_waitcnt lgkmcnt(0)
	v_mfma_f32_16x16x32_bf16 v[48:51], v[80:83], v[32:35], v[214:217]
	v_mfma_f32_16x16x32_bf16 v[32:35], v[206:209], v[32:35], v[162:165]
	v_mfma_f32_16x16x32_bf16 v[56:59], v[210:213], v[36:39], v[32:35]
	v_mfma_f32_16x16x32_bf16 v[32:35], v[80:83], v[40:43], v[92:95]
	v_mfma_f32_16x16x32_bf16 v[52:55], v[84:87], v[44:47], v[32:35]
	v_mfma_f32_16x16x32_bf16 v[32:35], v[206:209], v[40:43], v[88:91]
	v_mfma_f32_16x16x32_bf16 v[60:63], v[84:87], v[36:39], v[48:51]
	v_mfma_f32_16x16x32_bf16 v[48:51], v[210:213], v[44:47], v[32:35]
	v_mfma_f32_16x16x32_bf16 v[32:35], v[80:83], v[186:189], v[76:79]
	v_mfma_f32_16x16x32_bf16 v[44:47], v[84:87], v[190:193], v[32:35]
	v_mfma_f32_16x16x32_bf16 v[32:35], v[206:209], v[186:189], v[72:75]
	v_mfma_f32_16x16x32_bf16 v[40:43], v[210:213], v[190:193], v[32:35]
	v_mfma_f32_16x16x32_bf16 v[32:35], v[80:83], v[194:197], v[68:71]
	v_mfma_f32_16x16x32_bf16 v[36:39], v[84:87], v[202:205], v[32:35]
	v_mfma_f32_16x16x32_bf16 v[32:35], v[206:209], v[194:197], v[64:67]
	v_mfma_f32_16x16x32_bf16 v[32:35], v[210:213], v[202:205], v[32:35]
	s_setprio 0
	s_barrier
	ds_read_b128 v[162:165], v144 offset:16384
	ds_read_b128 v[186:189], v144 offset:17408
	ds_read_b128 v[190:193], v144 offset:18432
	ds_read_b128 v[194:197], v144 offset:19456
	ds_read_b128 v[202:205], v144 offset:20480
	ds_read_b128 v[214:217], v144 offset:21504
	ds_read_b128 v[234:237], v144 offset:22528
	ds_read_b128 v[238:241], v144 offset:23552
	s_barrier
	s_waitcnt lgkmcnt(0)
	s_setprio 1
	s_waitcnt lgkmcnt(0)
	v_mfma_f32_16x16x32_bf16 v[64:67], v[16:19], v[162:165], v[198:201]
	v_mfma_f32_16x16x32_bf16 v[100:103], v[24:27], v[186:189], v[64:67]
	v_mfma_f32_16x16x32_bf16 v[64:67], v[174:177], v[162:165], v[218:221]
	v_mfma_f32_16x16x32_bf16 v[96:99], v[182:185], v[186:189], v[64:67]
	v_mfma_f32_16x16x32_bf16 v[64:67], v[16:19], v[190:193], v[222:225]
	v_mfma_f32_16x16x32_bf16 v[92:95], v[24:27], v[194:197], v[64:67]
	v_mfma_f32_16x16x32_bf16 v[64:67], v[174:177], v[190:193], v[226:229]
	v_mfma_f32_16x16x32_bf16 v[88:91], v[182:185], v[194:197], v[64:67]
	v_mfma_f32_16x16x32_bf16 v[64:67], v[16:19], v[202:205], v[230:233]
	v_mfma_f32_16x16x32_bf16 v[28:31], v[174:177], v[202:205], v[28:31]
	v_mfma_f32_16x16x32_bf16 v[16:19], v[16:19], v[234:237], v[20:23]
	v_mfma_f32_16x16x32_bf16 v[12:15], v[174:177], v[234:237], v[12:15]
	v_mfma_f32_16x16x32_bf16 v[76:79], v[24:27], v[214:217], v[64:67]
	v_mfma_f32_16x16x32_bf16 v[72:75], v[182:185], v[214:217], v[28:31]
	v_mfma_f32_16x16x32_bf16 v[68:71], v[24:27], v[238:241], v[16:19]
	v_mfma_f32_16x16x32_bf16 v[64:67], v[182:185], v[238:241], v[12:15]
	s_setprio 0
	s_setprio 1
	v_mfma_f32_16x16x32_bf16 v[12:15], v[80:83], v[162:165], v[140:143]
	v_mfma_f32_16x16x32_bf16 v[28:31], v[84:87], v[186:189], v[12:15]
	v_mfma_f32_16x16x32_bf16 v[12:15], v[206:209], v[162:165], v[146:149]
	v_mfma_f32_16x16x32_bf16 v[24:27], v[210:213], v[186:189], v[12:15]
	v_mfma_f32_16x16x32_bf16 v[12:15], v[80:83], v[190:193], v[150:153]
	v_mfma_f32_16x16x32_bf16 v[20:23], v[84:87], v[194:197], v[12:15]
	v_mfma_f32_16x16x32_bf16 v[12:15], v[206:209], v[190:193], v[170:173]
	v_mfma_f32_16x16x32_bf16 v[16:19], v[210:213], v[194:197], v[12:15]
	v_mfma_f32_16x16x32_bf16 v[12:15], v[80:83], v[202:205], v[178:181]
	v_mfma_f32_16x16x32_bf16 v[8:11], v[206:209], v[202:205], v[8:11]
	v_mfma_f32_16x16x32_bf16 v[4:7], v[80:83], v[234:237], v[4:7]
	v_mfma_f32_16x16x32_bf16 v[0:3], v[206:209], v[234:237], v[0:3]
	v_mfma_f32_16x16x32_bf16 v[12:15], v[84:87], v[214:217], v[12:15]
	v_mfma_f32_16x16x32_bf16 v[8:11], v[210:213], v[214:217], v[8:11]
	v_mfma_f32_16x16x32_bf16 v[4:7], v[84:87], v[238:241], v[4:7]
	v_mfma_f32_16x16x32_bf16 v[0:3], v[210:213], v[238:241], v[0:3]
	s_setprio 0
	s_movk_i32 s0, 0x100
	v_cmp_gt_u32_e32 vcc, s0, v139
	s_barrier
	s_and_saveexec_b64 s[0:1], vcc
	s_cbranch_execz .LBB0_698
	s_barrier
	s_branch .LBB0_698
